# combo30 + FFT forward pass 2: one LDS base register with immediate offsets 256+264*(j-1) instead of one address register per element; 242 dead address instructions removed
# speedup vs baseline: 1.0038x; 1.0038x over previous
.Lmy_fft_kj:
	v_mov_b32 v66, 0
	v_mov_b32_e32 v68, v1
	v_add_u32_e32 v0, v66, v0
	v_cvt_f32_i32_e32 v70, v0
	v_ashrrev_i32_e32 v66, 5, v0
	v_lshlrev_b32_e32 v69, 3, v0
	v_lshlrev_b32_e32 v66, 3, v66
	v_add3_u32 v127, 0, v66, v69
	v_add_u32_e32 v220, 0x10800, v127
	v_mul_f32_e32 v0, 0x38800000, v70
	v_sin_f32_e32 v107, v0
	v_cos_f32_e32 v106, v0
	v_xor_b32_e32 v124, 0x80000000, v107
	v_mov_b32_e32 v125, v107
	v_pk_mul_f32 v[128:129], v[124:125], v[106:107] op_sel:[0,1] op_sel_hi:[1,0]
	v_pk_fma_f32 v[128:129], v[106:107], v[106:107], v[128:129] op_sel_hi:[1,0,1]
	v_pk_mul_f32 v[132:133], v[124:125], v[128:129] op_sel:[0,1] op_sel_hi:[1,0]
	s_waitcnt vmcnt(21)
	v_sub_f32_e32 v70, v112, v120
	v_pk_fma_f32 v[132:133], v[128:129], v[106:107], v[132:133] op_sel_hi:[1,0,1]
	s_waitcnt vmcnt(20)
	v_sub_f32_e32 v76, v113, v121
	v_pk_mul_f32 v[136:137], v[124:125], v[132:133] op_sel:[0,1] op_sel_hi:[1,0]
	v_pk_fma_f32 v[136:137], v[132:133], v[106:107], v[136:137] op_sel_hi:[1,0,1]
	v_pk_mul_f32 v[140:141], v[124:125], v[136:137] op_sel:[0,1] op_sel_hi:[1,0]
	v_pk_fma_f32 v[140:141], v[136:137], v[106:107], v[140:141] op_sel_hi:[1,0,1]
	v_sub_f32_e32 v66, v109, v119
	v_pk_mul_f32 v[144:145], v[124:125], v[140:141] op_sel:[0,1] op_sel_hi:[1,0]
	v_mul_f32_e32 v73, 0xbf3504f3, v70
	v_pk_fma_f32 v[144:145], v[140:141], v[106:107], v[144:145] op_sel_hi:[1,0,1]
	v_mul_f32_e32 v85, 0xbf6c835e, v76
	v_pk_mul_f32 v[148:149], v[124:125], v[144:145] op_sel:[0,1] op_sel_hi:[1,0]
	v_pk_fma_f32 v[148:149], v[144:145], v[106:107], v[148:149] op_sel_hi:[1,0,1]
	v_pk_mul_f32 v[152:153], v[124:125], v[148:149] op_sel:[0,1] op_sel_hi:[1,0]
	v_pk_fma_f32 v[152:153], v[148:149], v[106:107], v[152:153] op_sel_hi:[1,0,1]
	v_pk_mul_f32 v[156:157], v[124:125], v[152:153] op_sel:[0,1] op_sel_hi:[1,0]
	v_pk_fma_f32 v[156:157], v[152:153], v[106:107], v[156:157] op_sel_hi:[1,0,1]
	v_sub_f32_e32 v0, v108, v118
	v_pk_mul_f32 v[160:161], v[124:125], v[156:157] op_sel:[0,1] op_sel_hi:[1,0]
	v_pk_add_f32 v[108:109], v[108:109], v[118:119]
	v_pk_fma_f32 v[160:161], v[156:157], v[106:107], v[160:161] op_sel_hi:[1,0,1]
	v_mul_f32_e32 v69, 0xbec3ef15, v66
	v_pk_mul_f32 v[164:165], v[124:125], v[160:161] op_sel:[0,1] op_sel_hi:[1,0]
	v_pk_fma_f32 v[70:71], v[70:71], s[10:11], v[72:73] op_sel_hi:[1,0,1]
	v_pk_fma_f32 v[72:73], v[76:77], s[14:15], v[84:85] op_sel_hi:[1,0,1]
	s_waitcnt vmcnt(18)
	v_sub_f32_e32 v82, v115, v123
	v_pk_add_f32 v[76:77], v[114:115], v[122:123]
	v_mov_b32_e32 v83, v1
	v_mov_b32_e32 v90, v1
	s_movk_i32 s5, 0x200
	v_pk_fma_f32 v[164:165], v[160:161], v[106:107], v[164:165] op_sel_hi:[1,0,1]
	v_pk_fma_f32 v[66:67], v[66:67], s[6:7], v[68:69] op_sel_hi:[1,0,1]
	v_pk_add_f32 v[68:69], v[112:113], v[120:121]
	v_mul_f32_e32 v91, 0xbf6c835e, v82
	s_waitcnt vmcnt(17)
	v_sub_f32_e32 v80, v116, v110
	v_pk_add_f32 v[112:113], v[108:109], v[76:77] neg_lo:[0,1] neg_hi:[0,1]
	v_mov_b32_e32 v81, v1
	v_mov_b32_e32 v88, v1
	v_mov_b32_e32 v101, v1
	v_mov_b32_e32 v102, v1
	v_pk_mul_f32 v[168:169], v[124:125], v[164:165] op_sel:[0,1] op_sel_hi:[1,0]
	v_pk_fma_f32 v[82:83], v[82:83], s[4:5], v[90:91] op_sel_hi:[1,0,1]
	v_mul_f32_e32 v89, 0xbf3504f3, v80
	s_waitcnt vmcnt(16)
	v_sub_f32_e32 v78, v117, v111
	v_pk_add_f32 v[90:91], v[116:117], v[110:111]
	v_mov_b32_e32 v100, v113
	v_mul_f32_e32 v103, 0xbf3504f3, v113
	v_mov_b32_e32 v79, v1
	v_mov_b32_e32 v86, v1
	v_pk_fma_f32 v[168:169], v[164:165], v[106:107], v[168:169] op_sel_hi:[1,0,1]
	v_sub_f32_e32 v75, v114, v122
	v_pk_fma_f32 v[80:81], v[80:81], s[8:9], v[88:89] op_sel_hi:[1,0,1]
	v_mul_f32_e32 v87, 0xbec3ef15, v78
	v_pk_add_f32 v[88:89], v[66:67], v[82:83]
	v_pk_add_f32 v[66:67], v[66:67], v[82:83] neg_lo:[0,1] neg_hi:[0,1]
	v_pk_fma_f32 v[82:83], v[100:101], s[10:11], v[102:103] op_sel_hi:[1,0,1]
	v_pk_add_f32 v[100:101], v[68:69], v[90:91] neg_lo:[0,1] neg_hi:[0,1]
	v_mov_b32_e32 v74, v1
	v_mov_b32_e32 v97, v1
	v_mov_b32_e32 v98, v1
	v_pk_mul_f32 v[174:175], v[124:125], v[168:169] op_sel:[0,1] op_sel_hi:[1,0]
	v_xor_b32_e32 v75, 0x80000000, v75
	v_pk_add_f32 v[76:77], v[108:109], v[76:77]
	v_pk_add_f32 v[68:69], v[68:69], v[90:91]
	v_pk_fma_f32 v[78:79], v[78:79], s[12:13], v[86:87] op_sel_hi:[1,0,1]
	v_pk_add_f32 v[90:91], v[70:71], v[80:81]
	v_pk_add_f32 v[70:71], v[70:71], v[80:81] neg_lo:[0,1] neg_hi:[0,1]
	v_mov_b32_e32 v96, v101
	v_mul_f32_e32 v99, 0xbf3504f3, v101
	v_pk_fma_f32 v[174:175], v[168:169], v[106:107], v[174:175] op_sel_hi:[1,0,1]
	v_pk_add_f32 v[84:85], v[0:1], v[74:75]
	v_pk_add_f32 v[80:81], v[76:77], v[68:69] neg_lo:[0,1] neg_hi:[0,1]
	v_pk_add_f32 v[68:69], v[76:77], v[68:69]
	v_xor_b32_e32 v77, 0x80000000, v70
	v_mov_b32_e32 v76, v71
	v_pk_add_f32 v[70:71], v[72:73], v[78:79]
	v_pk_add_f32 v[72:73], v[72:73], v[78:79] neg_lo:[0,1] neg_hi:[0,1]
	v_pk_fma_f32 v[78:79], v[96:97], s[8:9], v[98:99] op_sel_hi:[1,0,1]
	v_mov_b32_e32 v94, v1
	v_pk_mul_f32 v[178:179], v[124:125], v[174:175] op_sel:[0,1] op_sel_hi:[1,0]
	v_pk_add_f32 v[74:75], v[0:1], v[74:75] neg_lo:[0,1] neg_hi:[0,1]
	v_mov_b32_e32 v0, v112
	v_pk_mul_f32 v[86:87], v[66:67], s[16:17]
	v_xor_b32_e32 v95, 0x80000000, v100
	v_mov_b32_e32 v92, v80
	v_pk_add_f32 v[80:81], v[80:81], 0 neg_lo:[1,1] neg_hi:[1,1]
	v_pk_add_f32 v[96:97], v[84:85], v[90:91]
	v_pk_add_f32 v[84:85], v[84:85], v[90:91] neg_lo:[0,1] neg_hi:[0,1]
	v_pk_add_f32 v[90:91], v[68:69], v[68:69] op_sel:[0,1] op_sel_hi:[1,0]
	v_pk_mul_f32 v[98:99], v[72:73], s[16:17]
	v_pk_add_f32 v[100:101], v[82:83], v[78:79]
	v_pk_add_f32 v[78:79], v[82:83], v[78:79] neg_lo:[0,1] neg_hi:[0,1]
	v_pk_add_f32 v[82:83], v[88:89], v[70:71]
	v_pk_add_f32 v[70:71], v[88:89], v[70:71] neg_lo:[0,1] neg_hi:[0,1]
	v_mov_b32_e32 v93, v1
	v_mov_b32_e32 v126, v107
	v_pk_add_f32 v[130:131], v[128:129], 0 neg_lo:[1,1] neg_hi:[1,1]
	v_pk_add_f32 v[158:159], v[156:157], 0 neg_lo:[1,1] neg_hi:[1,1]
	v_pk_fma_f32 v[178:179], v[174:175], v[106:107], v[178:179] op_sel_hi:[1,0,1]
	v_pk_fma_f32 v[66:67], v[66:67], s[10:11], v[86:87] op_sel:[0,0,1] op_sel_hi:[1,0,0]
	v_pk_add_f32 v[86:87], v[0:1], v[94:95]
	v_pk_add_f32 v[94:95], v[0:1], v[94:95] neg_lo:[0,1] neg_hi:[0,1]
	v_mov_b32_e32 v80, v1
	v_pk_add_f32 v[88:89], v[74:75], v[76:77]
	v_pk_add_f32 v[74:75], v[74:75], v[76:77] neg_lo:[0,1] neg_hi:[0,1]
	v_mov_b32_e32 v91, v1
	v_pk_fma_f32 v[72:73], v[72:73], s[8:9], v[98:99] op_sel:[0,0,1] op_sel_hi:[1,0,0]
	v_xor_b32_e32 v77, 0x80000000, v78
	v_mov_b32_e32 v76, v79
	v_xor_b32_e32 v79, 0x80000000, v70
	v_mov_b32_e32 v78, v71
	v_pk_add_f32 v[98:99], v[96:97], v[82:83]
	v_mov_b32_e32 v130, v129
	v_pk_add_f32 v[134:135], v[132:133], 0 neg_lo:[1,1] neg_hi:[1,1]
	v_pk_add_f32 v[142:143], v[140:141], 0 neg_lo:[1,1] neg_hi:[1,1]
	v_mov_b32_e32 v158, v157
	v_pk_mul_f32 v[124:125], v[124:125], v[178:179] op_sel:[0,1] op_sel_hi:[1,0]
	v_pk_add_f32 v[70:71], v[92:93], v[80:81]
	v_pk_add_f32 v[80:81], v[92:93], v[80:81] neg_lo:[0,1] neg_hi:[0,1]
	v_pk_add_f32 v[92:93], v[86:87], v[100:101]
	v_pk_add_f32 v[82:83], v[96:97], v[82:83] neg_lo:[0,1] neg_hi:[0,1]
	ds_write_b64 v127, v[90:91]
	v_pk_add_f32 v[90:91], v[66:67], v[72:73]
	v_pk_add_f32 v[112:113], v[66:67], v[72:73] op_sel:[1,1] op_sel_hi:[0,0] neg_lo:[0,1] neg_hi:[1,0]
	v_pk_add_f32 v[72:73], v[94:95], v[76:77]
	v_pk_add_f32 v[76:77], v[94:95], v[76:77] neg_lo:[0,1] neg_hi:[0,1]
	v_pk_add_f32 v[94:95], v[84:85], v[78:79]
	v_pk_add_f32 v[78:79], v[84:85], v[78:79] neg_lo:[0,1] neg_hi:[0,1]
	v_pk_mul_f32 v[84:85], v[126:127], v[98:99] op_sel:[0,1] op_sel_hi:[0,0] neg_hi:[1,0]
	v_mov_b32_e32 v134, v133
	v_pk_add_f32 v[138:139], v[136:137], 0 neg_lo:[1,1] neg_hi:[1,1]
	v_mov_b32_e32 v142, v141
	v_pk_add_f32 v[146:147], v[144:145], 0 neg_lo:[1,1] neg_hi:[1,1]
	v_pk_add_f32 v[150:151], v[148:149], 0 neg_lo:[1,1] neg_hi:[1,1]
	v_pk_add_f32 v[166:167], v[164:165], 0 neg_lo:[1,1] neg_hi:[1,1]
	v_pk_fma_f32 v[124:125], v[178:179], v[106:107], v[124:125] op_sel_hi:[1,0,1]
	v_pk_mul_f32 v[96:97], v[92:93], v[130:131] op_sel:[1,0] op_sel_hi:[0,1]
	v_pk_mul_f32 v[102:103], v[82:83], v[158:159] op_sel:[1,0] op_sel_hi:[0,1]
	v_pk_add_f32 v[66:67], v[88:89], v[90:91]
	v_pk_fma_f32 v[84:85], v[98:99], v[106:107], v[84:85] op_sel_hi:[1,0,1]
	v_mov_b32_e32 v138, v137
	v_mov_b32_e32 v146, v145
	v_mov_b32_e32 v150, v149
	v_pk_add_f32 v[154:155], v[152:153], 0 neg_lo:[1,1] neg_hi:[1,1]
	v_pk_add_f32 v[162:163], v[160:161], 0 neg_lo:[1,1] neg_hi:[1,1]
	v_mov_b32_e32 v166, v165
	v_pk_add_f32 v[172:173], v[168:169], 0 neg_lo:[1,1] neg_hi:[1,1]
	v_pk_add_f32 v[176:177], v[174:175], 0 neg_lo:[1,1] neg_hi:[1,1]
	v_pk_add_f32 v[180:181], v[178:179], 0 neg_lo:[1,1] neg_hi:[1,1]
	v_pk_add_f32 v[182:183], v[124:125], 0 neg_lo:[1,1] neg_hi:[1,1]
	v_pk_add_f32 v[68:69], v[68:69], v[68:69] op_sel:[0,1] op_sel_hi:[1,0] neg_lo:[0,1] neg_hi:[0,1]
	v_pk_add_f32 v[88:89], v[88:89], v[90:91] neg_lo:[0,1] neg_hi:[0,1]
	v_pk_fma_f32 v[90:91], v[92:93], v[128:129], v[96:97] op_sel_hi:[1,0,1]
	v_pk_mul_f32 v[92:93], v[94:95], v[142:143] op_sel:[1,0] op_sel_hi:[0,1]
	v_pk_fma_f32 v[82:83], v[82:83], v[156:157], v[102:103] op_sel_hi:[1,0,1]
	v_pk_add_f32 v[102:103], v[74:75], v[112:113]
	ds_write_b64 v127, v[84:85] offset:8448
	ds_write_b64 v127, v[90:91] offset:16896
	v_pk_mul_f32 v[84:85], v[66:67], v[134:135] op_sel:[1,0] op_sel_hi:[0,1]
	v_mov_b32_e32 v154, v153
	v_mov_b32_e32 v162, v161
	v_mov_b32_e32 v172, v169
	v_mov_b32_e32 v176, v175
	v_mov_b32_e32 v180, v179
	v_mov_b32_e32 v182, v125
	v_mov_b32_e32 v0, v68
	v_pk_mov_b32 v[68:69], s[2:3], v[68:69] op_sel:[1,0]
	v_pk_add_f32 v[86:87], v[86:87], v[100:101] neg_lo:[0,1] neg_hi:[0,1]
	v_pk_mul_f32 v[100:101], v[70:71], v[138:139] op_sel:[1,0] op_sel_hi:[0,1]
	v_pk_mul_f32 v[96:97], v[72:73], v[146:147] op_sel:[1,0] op_sel_hi:[0,1]
	v_pk_add_f32 v[74:75], v[74:75], v[112:113] neg_lo:[0,1] neg_hi:[0,1]
	v_pk_fma_f32 v[90:91], v[94:95], v[140:141], v[92:93] op_sel_hi:[1,0,1]
	v_pk_mul_f32 v[92:93], v[88:89], v[166:167] op_sel:[1,0] op_sel_hi:[0,1]
	v_pk_fma_f32 v[66:67], v[66:67], v[132:133], v[84:85] op_sel_hi:[1,0,1]
	v_pk_mul_f32 v[84:85], v[102:103], v[150:151] op_sel:[1,0] op_sel_hi:[0,1]
	s_mov_b64 s[46:47], 0
	s_and_b64 vcc, exec, s[0:1]
	v_pk_mul_f32 v[68:69], v[68:69], v[154:155]
	v_pk_mul_f32 v[108:109], v[86:87], v[162:163] op_sel:[1,0] op_sel_hi:[0,1]
	v_pk_mul_f32 v[110:111], v[80:81], v[172:173] op_sel:[1,0] op_sel_hi:[0,1]
	v_pk_fma_f32 v[70:71], v[70:71], v[136:137], v[100:101] op_sel_hi:[1,0,1]
	v_pk_mul_f32 v[98:99], v[78:79], v[176:177] op_sel:[1,0] op_sel_hi:[0,1]
	v_pk_mul_f32 v[100:101], v[76:77], v[180:181] op_sel:[1,0] op_sel_hi:[0,1]
	v_pk_fma_f32 v[72:73], v[72:73], v[144:145], v[96:97] op_sel_hi:[1,0,1]
	v_pk_fma_f32 v[88:89], v[88:89], v[164:165], v[92:93] op_sel_hi:[1,0,1]
	v_pk_mul_f32 v[92:93], v[74:75], v[182:183] op_sel:[1,0] op_sel_hi:[0,1]
	ds_write_b64 v127, v[66:67] offset:25344
	ds_write_b64 v127, v[70:71] offset:33792
	ds_write_b64 v127, v[90:91] offset:42240
	ds_write_b64 v127, v[72:73] offset:50688
	v_pk_fma_f32 v[66:67], v[102:103], v[148:149], v[84:85] op_sel_hi:[1,0,1]
	v_pk_fma_f32 v[68:69], v[0:1], v[152:153], v[68:69] op_sel_hi:[1,0,1]
	v_pk_fma_f32 v[86:87], v[86:87], v[160:161], v[108:109] op_sel_hi:[1,0,1]
	v_pk_fma_f32 v[80:81], v[80:81], v[168:169], v[110:111] op_sel_hi:[1,0,1]
	v_pk_fma_f32 v[78:79], v[78:79], v[174:175], v[98:99] op_sel_hi:[1,0,1]
	v_pk_fma_f32 v[76:77], v[76:77], v[178:179], v[100:101] op_sel_hi:[1,0,1]
	v_pk_fma_f32 v[70:71], v[74:75], v[124:125], v[92:93] op_sel_hi:[1,0,1]
	ds_write_b64 v127, v[66:67] offset:59136
	ds_write_b64 v220, v[68:69]
	ds_write_b64 v220, v[82:83] offset:8448
	ds_write_b64 v220, v[86:87] offset:16896
	ds_write_b64 v220, v[88:89] offset:25344
	ds_write_b64 v220, v[80:81] offset:33792
	ds_write_b64 v220, v[78:79] offset:42240
	ds_write_b64 v220, v[76:77] offset:50688
	ds_write_b64 v220, v[70:71] offset:59136
	s_cbranch_vccz .LBB0_359
	s_waitcnt lgkmcnt(0)
	s_barrier
	v_mov_b32 v0, 0
	s_mov_b32 s5, s14
	v_add_u32_e32 v74, v0, v170
	v_lshlrev_b32_e32 v0, 5, v74
	v_and_b32_e32 v71, 0xfffffc00, v0
	v_and_b32_e32 v70, 31, v74
	v_lshlrev_b32_e32 v78, 3, v71
	v_lshlrev_b32_e32 v79, 3, v70
	v_or_b32_e32 v67, 32, v71
	v_ashrrev_i32_e32 v67, 2, v67
	v_add_u32_e32 v67, 0, v67
	v_add3_u32 v114, v67, v78, v79
	v_ashrrev_i32_e32 v66, 2, v71
	v_add_u32_e32 v66, 0, v66
	v_add3_u32 v66, v66, v78, v79
	v_mov_b32_e32 v221, v114
	ds_read_b64 v[66:67], v66
	ds_read_b64 v[68:69], v221 offset:256
	ds_read_b64 v[72:73], v221 offset:520
	ds_read_b64 v[76:77], v221 offset:784
	ds_read_b64 v[80:81], v221 offset:1048
	ds_read_b64 v[82:83], v221 offset:1312
	ds_read_b64 v[116:117], v221 offset:1576
	ds_read_b64 v[118:119], v221 offset:1840
	ds_read_b64 v[120:121], v221 offset:2104
	ds_read_b64 v[122:123], v221 offset:2368
	ds_read_b64 v[124:125], v221 offset:2632
	ds_read_b64 v[126:127], v221 offset:2896
	ds_read_b64 v[128:129], v221 offset:3160
	ds_read_b64 v[130:131], v221 offset:3424
	ds_read_b64 v[132:133], v221 offset:3688
	ds_read_b64 v[134:135], v221 offset:3952
	ds_read_b64 v[136:137], v221 offset:4216
	ds_read_b64 v[138:139], v221 offset:4480
	ds_read_b64 v[140:141], v221 offset:4744
	ds_read_b64 v[142:143], v221 offset:5008
	s_waitcnt lgkmcnt(3)
	v_pk_add_f32 v[168:169], v[66:67], v[136:137]
	v_pk_add_f32 v[66:67], v[66:67], v[136:137] neg_lo:[0,1] neg_hi:[0,1]
	s_waitcnt lgkmcnt(2)
	v_pk_add_f32 v[136:137], v[68:69], v[138:139]
	v_pk_add_f32 v[68:69], v[68:69], v[138:139] neg_lo:[0,1] neg_hi:[0,1]
	v_pk_mul_f32 v[138:139], v[68:69], s[18:19]
	v_pk_fma_f32 v[68:69], v[68:69], s[20:21], v[138:139] op_sel:[0,0,1] op_sel_hi:[1,0,0]
	s_waitcnt lgkmcnt(1)
	v_pk_add_f32 v[138:139], v[72:73], v[140:141]
	v_pk_add_f32 v[72:73], v[72:73], v[140:141] neg_lo:[0,1] neg_hi:[0,1]
	v_pk_mul_f32 v[140:141], v[72:73], s[4:5]
	ds_read_b64 v[144:145], v221 offset:5272
	ds_read_b64 v[146:147], v221 offset:5536
	ds_read_b64 v[148:149], v221 offset:5800
	ds_read_b64 v[150:151], v221 offset:6064
	v_pk_fma_f32 v[72:73], v[72:73], s[6:7], v[140:141] op_sel:[0,0,1] op_sel_hi:[1,0,0]
	s_waitcnt lgkmcnt(4)
	v_pk_add_f32 v[140:141], v[76:77], v[142:143]
	v_pk_add_f32 v[76:77], v[76:77], v[142:143] neg_lo:[0,1] neg_hi:[0,1]
	v_pk_mul_f32 v[142:143], v[76:77], s[22:23]
	v_pk_fma_f32 v[76:77], v[76:77], s[24:25], v[142:143] op_sel:[0,0,1] op_sel_hi:[1,0,0]
	s_waitcnt lgkmcnt(3)
	v_pk_add_f32 v[142:143], v[80:81], v[144:145]
	v_pk_add_f32 v[80:81], v[80:81], v[144:145] neg_lo:[0,1] neg_hi:[0,1]
	s_mov_b32 s9, s10
	v_pk_mul_f32 v[144:145], v[80:81], s[8:9]
	v_pk_fma_f32 v[80:81], v[80:81], s[10:11], v[144:145] op_sel:[0,0,1] op_sel_hi:[1,0,0]
	s_waitcnt lgkmcnt(2)
	v_pk_add_f32 v[144:145], v[82:83], v[146:147]
	v_pk_add_f32 v[82:83], v[82:83], v[146:147] neg_lo:[0,1] neg_hi:[0,1]
	s_mov_b32 s27, s24
	v_pk_mul_f32 v[146:147], v[82:83], s[26:27]
	s_mov_b32 s0, s23
	v_pk_fma_f32 v[82:83], v[82:83], s[0:1], v[146:147] op_sel:[0,0,1] op_sel_hi:[1,0,0]
	s_waitcnt lgkmcnt(1)
	v_pk_add_f32 v[146:147], v[116:117], v[148:149]
	v_pk_add_f32 v[116:117], v[116:117], v[148:149] neg_lo:[0,1] neg_hi:[0,1]
	s_mov_b32 s13, s6
	v_pk_mul_f32 v[148:149], v[116:117], s[12:13]
	ds_read_b64 v[152:153], v221 offset:6328
	ds_read_b64 v[154:155], v221 offset:6592
	ds_read_b64 v[156:157], v221 offset:6856
	ds_read_b64 v[158:159], v221 offset:7120
	v_pk_fma_f32 v[116:117], v[116:117], s[14:15], v[148:149] op_sel:[0,0,1] op_sel_hi:[1,0,0]
	s_waitcnt lgkmcnt(4)
	v_pk_add_f32 v[148:149], v[118:119], v[150:151]
	v_pk_add_f32 v[118:119], v[118:119], v[150:151] neg_lo:[0,1] neg_hi:[0,1]
	s_mov_b32 s35, s20
	v_pk_mul_f32 v[150:151], v[118:119], s[34:35]
	s_mov_b32 s44, s19
	v_pk_fma_f32 v[118:119], v[118:119], s[44:45], v[150:151] op_sel:[0,0,1] op_sel_hi:[1,0,0]
	s_waitcnt lgkmcnt(3)
	v_pk_add_f32 v[150:151], v[120:121], v[152:153]
	v_pk_add_f32 v[152:153], v[120:121], v[152:153] op_sel:[1,1] op_sel_hi:[0,0] neg_lo:[0,1] neg_hi:[1,0]
	s_waitcnt lgkmcnt(2)
	v_pk_add_f32 v[120:121], v[122:123], v[154:155]
	v_pk_add_f32 v[122:123], v[122:123], v[154:155] neg_lo:[0,1] neg_hi:[0,1]
	v_pk_mul_f32 v[154:155], v[122:123], s[34:35]
	v_pk_fma_f32 v[122:123], v[122:123], s[18:19], v[154:155] op_sel:[0,0,1] op_sel_hi:[1,0,0]
	s_waitcnt lgkmcnt(1)
	v_pk_add_f32 v[154:155], v[124:125], v[156:157]
	v_pk_add_f32 v[124:125], v[124:125], v[156:157] neg_lo:[0,1] neg_hi:[0,1]
	v_pk_mul_f32 v[156:157], v[124:125], s[12:13]
	ds_read_b64 v[160:161], v221 offset:7384
	ds_read_b64 v[162:163], v221 offset:7648
	ds_read_b64 v[164:165], v221 offset:7912
	ds_read_b64 v[166:167], v221 offset:8176
	v_pk_fma_f32 v[124:125], v[124:125], s[4:5], v[156:157] op_sel:[0,0,1] op_sel_hi:[1,0,0]
	s_waitcnt lgkmcnt(4)
	v_pk_add_f32 v[156:157], v[126:127], v[158:159]
	v_pk_add_f32 v[126:127], v[126:127], v[158:159] neg_lo:[0,1] neg_hi:[0,1]
	v_lshlrev_b32_e32 v70, 4, v70
	v_pk_mul_f32 v[158:159], v[126:127], s[26:27]
	v_cvt_f32_u32_e32 v75, v70
	v_pk_fma_f32 v[126:127], v[126:127], s[22:23], v[158:159] op_sel:[0,0,1] op_sel_hi:[1,0,0]
	s_waitcnt lgkmcnt(3)
	v_pk_add_f32 v[158:159], v[128:129], v[160:161]
	v_pk_add_f32 v[128:129], v[128:129], v[160:161] neg_lo:[0,1] neg_hi:[0,1]
	v_and_b32_e32 v74, 0x1fffffe0, v74
	v_pk_mul_f32 v[160:161], v[128:129], s[8:9]
	v_mul_f32_e32 v115, 0x38800000, v75
	v_pk_fma_f32 v[128:129], v[128:129], s[8:9], v[160:161] op_sel:[0,0,1] op_sel_hi:[1,0,0]
	s_waitcnt lgkmcnt(2)
	v_pk_add_f32 v[160:161], v[130:131], v[162:163]
	v_pk_add_f32 v[130:131], v[130:131], v[162:163] neg_lo:[0,1] neg_hi:[0,1]
	v_lshl_add_u32 v74, v74, 3, 0
	v_pk_mul_f32 v[162:163], v[130:131], s[22:23]
	v_sin_f32_e32 v75, v115
	v_pk_fma_f32 v[130:131], v[130:131], s[26:27], v[162:163] op_sel:[0,0,1] op_sel_hi:[1,0,0]
	s_waitcnt lgkmcnt(1)
	v_pk_add_f32 v[162:163], v[132:133], v[164:165]
	v_pk_add_f32 v[132:133], v[132:133], v[164:165] neg_lo:[0,1] neg_hi:[0,1]
	v_add3_u32 v74, v74, v78, v79
	v_pk_mul_f32 v[164:165], v[132:133], s[4:5]
	v_xor_b32_e32 v78, 0x80000000, v75
	v_pk_fma_f32 v[132:133], v[132:133], s[12:13], v[164:165] op_sel:[0,0,1] op_sel_hi:[1,0,0]
	s_waitcnt lgkmcnt(0)
	v_pk_add_f32 v[164:165], v[134:135], v[166:167]
	v_pk_add_f32 v[134:135], v[134:135], v[166:167] neg_lo:[0,1] neg_hi:[0,1]
	v_mov_b32_e32 v79, v75
	v_pk_mul_f32 v[166:167], v[134:135], s[18:19]
	s_add_u32 s41, s56, s42
	v_pk_fma_f32 v[134:135], v[134:135], s[34:35], v[166:167] op_sel:[0,0,1] op_sel_hi:[1,0,0]
	v_pk_add_f32 v[166:167], v[168:169], v[150:151]
	v_pk_add_f32 v[150:151], v[168:169], v[150:151] neg_lo:[0,1] neg_hi:[0,1]
	v_pk_add_f32 v[168:169], v[136:137], v[120:121]
	v_pk_add_f32 v[120:121], v[136:137], v[120:121] neg_lo:[0,1] neg_hi:[0,1]
	s_addc_u32 s61, s57, s43
	v_pk_mul_f32 v[136:137], v[120:121], s[4:5]
	s_nop 0
	v_pk_fma_f32 v[120:121], v[120:121], s[6:7], v[136:137] op_sel:[0,0,1] op_sel_hi:[1,0,0]
	v_pk_add_f32 v[136:137], v[138:139], v[154:155]
	v_pk_add_f32 v[138:139], v[138:139], v[154:155] neg_lo:[0,1] neg_hi:[0,1]
	s_nop 0
	v_pk_mul_f32 v[154:155], v[138:139], s[8:9]
	s_nop 0
	v_pk_fma_f32 v[138:139], v[138:139], s[10:11], v[154:155] op_sel:[0,0,1] op_sel_hi:[1,0,0]
	v_pk_add_f32 v[154:155], v[140:141], v[156:157]
	v_pk_add_f32 v[140:141], v[140:141], v[156:157] neg_lo:[0,1] neg_hi:[0,1]
	s_nop 0
	v_pk_mul_f32 v[156:157], v[140:141], s[12:13]
	s_nop 0
	v_pk_fma_f32 v[140:141], v[140:141], s[14:15], v[156:157] op_sel:[0,0,1] op_sel_hi:[1,0,0]
	v_pk_add_f32 v[156:157], v[142:143], v[158:159]
	v_pk_add_f32 v[158:159], v[142:143], v[158:159] op_sel:[1,1] op_sel_hi:[0,0] neg_lo:[0,1] neg_hi:[1,0]
	s_nop 0
	v_pk_add_f32 v[142:143], v[144:145], v[160:161]
	v_pk_add_f32 v[144:145], v[144:145], v[160:161] neg_lo:[0,1] neg_hi:[0,1]
	s_nop 0
	v_pk_mul_f32 v[160:161], v[144:145], s[12:13]
	s_nop 0
	v_pk_fma_f32 v[144:145], v[144:145], s[4:5], v[160:161] op_sel:[0,0,1] op_sel_hi:[1,0,0]
	v_pk_add_f32 v[160:161], v[146:147], v[162:163]
	v_pk_add_f32 v[146:147], v[146:147], v[162:163] neg_lo:[0,1] neg_hi:[0,1]
	s_nop 0
	v_pk_mul_f32 v[162:163], v[146:147], s[8:9]
	s_nop 0
	v_pk_fma_f32 v[146:147], v[146:147], s[8:9], v[162:163] op_sel:[0,0,1] op_sel_hi:[1,0,0]
	v_pk_add_f32 v[162:163], v[148:149], v[164:165]
	v_pk_add_f32 v[148:149], v[148:149], v[164:165] neg_lo:[0,1] neg_hi:[0,1]
	s_nop 0
	v_pk_mul_f32 v[164:165], v[148:149], s[4:5]
	s_nop 0
	v_pk_fma_f32 v[148:149], v[148:149], s[12:13], v[164:165] op_sel:[0,0,1] op_sel_hi:[1,0,0]
	v_pk_add_f32 v[164:165], v[66:67], v[152:153]
	v_pk_add_f32 v[66:67], v[66:67], v[152:153] neg_lo:[0,1] neg_hi:[0,1]
	v_pk_add_f32 v[152:153], v[68:69], v[122:123]
	v_pk_add_f32 v[68:69], v[68:69], v[122:123] neg_lo:[0,1] neg_hi:[0,1]
	s_nop 0
	v_pk_mul_f32 v[122:123], v[68:69], s[4:5]
	s_nop 0
	v_pk_fma_f32 v[68:69], v[68:69], s[6:7], v[122:123] op_sel:[0,0,1] op_sel_hi:[1,0,0]
	v_pk_add_f32 v[122:123], v[72:73], v[124:125]
	v_pk_add_f32 v[72:73], v[72:73], v[124:125] neg_lo:[0,1] neg_hi:[0,1]
	s_nop 0
	v_pk_mul_f32 v[124:125], v[72:73], s[8:9]
	s_nop 0
	v_pk_fma_f32 v[72:73], v[72:73], s[10:11], v[124:125] op_sel:[0,0,1] op_sel_hi:[1,0,0]
	v_pk_add_f32 v[124:125], v[76:77], v[126:127]
	v_pk_add_f32 v[76:77], v[76:77], v[126:127] neg_lo:[0,1] neg_hi:[0,1]
	s_nop 0
	v_pk_mul_f32 v[126:127], v[76:77], s[12:13]
	s_nop 0
	v_pk_fma_f32 v[76:77], v[76:77], s[14:15], v[126:127] op_sel:[0,0,1] op_sel_hi:[1,0,0]
	v_pk_add_f32 v[126:127], v[80:81], v[128:129]
	v_pk_add_f32 v[128:129], v[80:81], v[128:129] op_sel:[1,1] op_sel_hi:[0,0] neg_lo:[0,1] neg_hi:[1,0]
	s_nop 0
	v_pk_add_f32 v[80:81], v[82:83], v[130:131]
	v_pk_add_f32 v[82:83], v[82:83], v[130:131] neg_lo:[0,1] neg_hi:[0,1]
	s_nop 0
	v_pk_mul_f32 v[130:131], v[82:83], s[12:13]
	s_nop 0
	v_pk_fma_f32 v[82:83], v[82:83], s[4:5], v[130:131] op_sel:[0,0,1] op_sel_hi:[1,0,0]
	v_pk_add_f32 v[130:131], v[116:117], v[132:133]
	v_pk_add_f32 v[116:117], v[116:117], v[132:133] neg_lo:[0,1] neg_hi:[0,1]
	s_nop 0
	v_pk_mul_f32 v[132:133], v[116:117], s[8:9]
	s_nop 0
	v_pk_fma_f32 v[116:117], v[116:117], s[8:9], v[132:133] op_sel:[0,0,1] op_sel_hi:[1,0,0]
	v_pk_add_f32 v[132:133], v[118:119], v[134:135]
	v_pk_add_f32 v[118:119], v[118:119], v[134:135] neg_lo:[0,1] neg_hi:[0,1]
	s_nop 0
	v_pk_mul_f32 v[134:135], v[118:119], s[4:5]
	s_nop 0
	v_pk_fma_f32 v[118:119], v[118:119], s[12:13], v[134:135] op_sel:[0,0,1] op_sel_hi:[1,0,0]
	v_pk_add_f32 v[134:135], v[166:167], v[156:157]
	v_pk_add_f32 v[156:157], v[166:167], v[156:157] neg_lo:[0,1] neg_hi:[0,1]
	v_pk_add_f32 v[166:167], v[168:169], v[142:143]
	v_pk_add_f32 v[142:143], v[168:169], v[142:143] neg_lo:[0,1] neg_hi:[0,1]
	s_nop 0
	v_pk_mul_f32 v[168:169], v[142:143], s[8:9]
	s_nop 0
	v_pk_fma_f32 v[142:143], v[142:143], s[10:11], v[168:169] op_sel:[0,0,1] op_sel_hi:[1,0,0]
	v_pk_add_f32 v[168:169], v[136:137], v[160:161]
	v_pk_add_f32 v[160:161], v[136:137], v[160:161] op_sel:[1,1] op_sel_hi:[0,0] neg_lo:[0,1] neg_hi:[1,0]
	s_nop 0
	v_pk_add_f32 v[136:137], v[154:155], v[162:163]
	v_pk_add_f32 v[154:155], v[154:155], v[162:163] neg_lo:[0,1] neg_hi:[0,1]
	s_nop 0
	v_pk_mul_f32 v[162:163], v[154:155], s[8:9]
	s_nop 0
	v_pk_fma_f32 v[154:155], v[154:155], s[8:9], v[162:163] op_sel:[0,0,1] op_sel_hi:[1,0,0]
	v_pk_add_f32 v[162:163], v[150:151], v[158:159]
	v_pk_add_f32 v[150:151], v[150:151], v[158:159] neg_lo:[0,1] neg_hi:[0,1]
	v_pk_add_f32 v[158:159], v[120:121], v[144:145]
	v_pk_add_f32 v[120:121], v[120:121], v[144:145] neg_lo:[0,1] neg_hi:[0,1]
	s_nop 0
	v_pk_mul_f32 v[144:145], v[120:121], s[8:9]
	s_nop 0
	v_pk_fma_f32 v[120:121], v[120:121], s[10:11], v[144:145] op_sel:[0,0,1] op_sel_hi:[1,0,0]
	v_pk_add_f32 v[144:145], v[138:139], v[146:147]
	v_pk_add_f32 v[146:147], v[138:139], v[146:147] op_sel:[1,1] op_sel_hi:[0,0] neg_lo:[0,1] neg_hi:[1,0]
	s_nop 0
	v_pk_add_f32 v[138:139], v[140:141], v[148:149]
	v_pk_add_f32 v[140:141], v[140:141], v[148:149] neg_lo:[0,1] neg_hi:[0,1]
	s_nop 0
	v_pk_mul_f32 v[148:149], v[140:141], s[8:9]
	s_nop 0
	v_pk_fma_f32 v[140:141], v[140:141], s[8:9], v[148:149] op_sel:[0,0,1] op_sel_hi:[1,0,0]
	v_pk_add_f32 v[148:149], v[164:165], v[126:127]
	v_pk_add_f32 v[126:127], v[164:165], v[126:127] neg_lo:[0,1] neg_hi:[0,1]
	v_pk_add_f32 v[164:165], v[152:153], v[80:81]
	v_pk_add_f32 v[80:81], v[152:153], v[80:81] neg_lo:[0,1] neg_hi:[0,1]
	s_nop 0
	v_pk_mul_f32 v[152:153], v[80:81], s[8:9]
	s_nop 0
	v_pk_fma_f32 v[80:81], v[80:81], s[10:11], v[152:153] op_sel:[0,0,1] op_sel_hi:[1,0,0]
	v_pk_add_f32 v[152:153], v[122:123], v[130:131]
	v_pk_add_f32 v[130:131], v[122:123], v[130:131] op_sel:[1,1] op_sel_hi:[0,0] neg_lo:[0,1] neg_hi:[1,0]
	s_nop 0
	v_pk_add_f32 v[122:123], v[124:125], v[132:133]
	v_pk_add_f32 v[124:125], v[124:125], v[132:133] neg_lo:[0,1] neg_hi:[0,1]
	s_nop 0
	v_pk_mul_f32 v[132:133], v[124:125], s[8:9]
	s_nop 0
	v_pk_fma_f32 v[124:125], v[124:125], s[8:9], v[132:133] op_sel:[0,0,1] op_sel_hi:[1,0,0]
	v_pk_add_f32 v[132:133], v[66:67], v[128:129]
	v_pk_add_f32 v[66:67], v[66:67], v[128:129] neg_lo:[0,1] neg_hi:[0,1]
	v_pk_add_f32 v[128:129], v[68:69], v[82:83]
	v_pk_add_f32 v[68:69], v[68:69], v[82:83] neg_lo:[0,1] neg_hi:[0,1]
	s_nop 0
	v_pk_mul_f32 v[82:83], v[68:69], s[8:9]
	s_nop 0
	v_pk_fma_f32 v[68:69], v[68:69], s[10:11], v[82:83] op_sel:[0,0,1] op_sel_hi:[1,0,0]
	v_pk_add_f32 v[82:83], v[72:73], v[116:117]
	v_pk_add_f32 v[116:117], v[72:73], v[116:117] op_sel:[1,1] op_sel_hi:[0,0] neg_lo:[0,1] neg_hi:[1,0]
	s_nop 0
	v_pk_add_f32 v[72:73], v[76:77], v[118:119]
	v_pk_add_f32 v[76:77], v[76:77], v[118:119] neg_lo:[0,1] neg_hi:[0,1]
	v_pk_add_f32 v[174:175], v[66:67], v[116:117]
	v_pk_mul_f32 v[118:119], v[76:77], s[8:9]
	v_pk_add_f32 v[116:117], v[66:67], v[116:117] neg_lo:[0,1] neg_hi:[0,1]
	v_pk_fma_f32 v[76:77], v[76:77], s[8:9], v[118:119] op_sel:[0,0,1] op_sel_hi:[1,0,0]
	v_pk_add_f32 v[118:119], v[134:135], v[168:169]
	v_pk_add_f32 v[134:135], v[134:135], v[168:169] neg_lo:[0,1] neg_hi:[0,1]
	v_pk_add_f32 v[168:169], v[166:167], v[136:137]
	v_pk_add_f32 v[166:167], v[166:167], v[136:137] op_sel:[1,1] op_sel_hi:[0,0] neg_lo:[0,1] neg_hi:[1,0]
	v_pk_add_f32 v[180:181], v[118:119], v[168:169]
	v_pk_add_f32 v[136:137], v[156:157], v[160:161]
	v_pk_add_f32 v[156:157], v[156:157], v[160:161] neg_lo:[0,1] neg_hi:[0,1]
	v_pk_add_f32 v[160:161], v[142:143], v[154:155]
	v_pk_add_f32 v[154:155], v[142:143], v[154:155] op_sel:[1,1] op_sel_hi:[0,0] neg_lo:[0,1] neg_hi:[1,0]
	v_pk_add_f32 v[178:179], v[68:69], v[76:77] op_sel:[1,1] op_sel_hi:[0,0] neg_lo:[0,1] neg_hi:[1,0]
	v_pk_add_f32 v[142:143], v[162:163], v[144:145]
	v_pk_add_f32 v[144:145], v[162:163], v[144:145] neg_lo:[0,1] neg_hi:[0,1]
	v_pk_add_f32 v[162:163], v[158:159], v[138:139]
	v_pk_add_f32 v[158:159], v[158:159], v[138:139] op_sel:[1,1] op_sel_hi:[0,0] neg_lo:[0,1] neg_hi:[1,0]
	ds_write_b64 v74, v[180:181]
	v_pk_add_f32 v[138:139], v[150:151], v[146:147]
	v_pk_add_f32 v[146:147], v[150:151], v[146:147] neg_lo:[0,1] neg_hi:[0,1]
	v_pk_add_f32 v[150:151], v[120:121], v[140:141]
	v_pk_add_f32 v[140:141], v[120:121], v[140:141] op_sel:[1,1] op_sel_hi:[0,0] neg_lo:[0,1] neg_hi:[1,0]
	v_cos_f32_e32 v74, v115
	v_pk_add_f32 v[120:121], v[148:149], v[152:153]
	v_pk_add_f32 v[148:149], v[148:149], v[152:153] neg_lo:[0,1] neg_hi:[0,1]
	v_pk_add_f32 v[152:153], v[164:165], v[122:123]
	v_pk_add_f32 v[164:165], v[164:165], v[122:123] op_sel:[1,1] op_sel_hi:[0,0] neg_lo:[0,1] neg_hi:[1,0]
	v_pk_add_f32 v[122:123], v[126:127], v[130:131]
	v_pk_add_f32 v[126:127], v[126:127], v[130:131] neg_lo:[0,1] neg_hi:[0,1]
	v_pk_add_f32 v[130:131], v[80:81], v[124:125]
	v_pk_add_f32 v[124:125], v[80:81], v[124:125] op_sel:[1,1] op_sel_hi:[0,0] neg_lo:[0,1] neg_hi:[1,0]
	v_pk_add_f32 v[80:81], v[132:133], v[82:83]
	v_pk_add_f32 v[132:133], v[132:133], v[82:83] neg_lo:[0,1] neg_hi:[0,1]
	v_pk_add_f32 v[176:177], v[68:69], v[76:77]
	v_pk_add_f32 v[118:119], v[118:119], v[168:169] neg_lo:[0,1] neg_hi:[0,1]
	v_pk_add_f32 v[168:169], v[134:135], v[166:167]
	v_pk_add_f32 v[82:83], v[134:135], v[166:167] neg_lo:[0,1] neg_hi:[0,1]
	v_pk_add_f32 v[134:135], v[136:137], v[160:161]
	v_pk_add_f32 v[136:137], v[136:137], v[160:161] neg_lo:[0,1] neg_hi:[0,1]
	v_pk_add_f32 v[160:161], v[156:157], v[154:155]
	v_pk_add_f32 v[68:69], v[156:157], v[154:155] neg_lo:[0,1] neg_hi:[0,1]
	v_pk_add_f32 v[154:155], v[142:143], v[162:163]
	v_pk_add_f32 v[142:143], v[142:143], v[162:163] neg_lo:[0,1] neg_hi:[0,1]
	v_pk_add_f32 v[156:157], v[144:145], v[158:159]
	v_pk_add_f32 v[76:77], v[144:145], v[158:159] neg_lo:[0,1] neg_hi:[0,1]
	v_pk_add_f32 v[144:145], v[138:139], v[150:151]
	v_pk_add_f32 v[138:139], v[138:139], v[150:151] neg_lo:[0,1] neg_hi:[0,1]
	v_pk_add_f32 v[150:151], v[146:147], v[140:141]
	v_pk_add_f32 v[66:67], v[146:147], v[140:141] neg_lo:[0,1] neg_hi:[0,1]
	v_pk_add_f32 v[140:141], v[120:121], v[152:153]
	v_pk_add_f32 v[162:163], v[116:117], v[178:179]
	v_pk_add_f32 v[70:71], v[116:117], v[178:179] neg_lo:[0,1] neg_hi:[0,1]
	v_mov_b32_e32 v116, v75
	v_pk_mul_f32 v[116:117], v[116:117], v[140:141] op_sel:[0,1] op_sel_hi:[0,0] neg_hi:[1,0]
	v_pk_fma_f32 v[116:117], v[140:141], v[74:75], v[116:117] op_sel_hi:[1,0,1]
	ds_write_b64 v221, v[116:117] offset:256
	v_pk_mul_f32 v[114:115], v[78:79], v[74:75] op_sel:[0,1] op_sel_hi:[1,0]
	v_pk_add_f32 v[172:173], v[128:129], v[72:73]
	v_pk_fma_f32 v[114:115], v[74:75], v[74:75], v[114:115] op_sel_hi:[1,0,1]
	v_pk_add_f32 v[128:129], v[128:129], v[72:73] op_sel:[1,1] op_sel_hi:[0,0] neg_lo:[0,1] neg_hi:[1,0]
	v_pk_mul_f32 v[116:117], v[154:155], v[114:115] op_sel:[1,1] op_sel_hi:[0,1] neg_hi:[0,1]
	v_pk_fma_f32 v[116:117], v[154:155], v[114:115], v[116:117] op_sel_hi:[1,0,1]
	ds_write_b64 v221, v[116:117] offset:520
	v_pk_mul_f32 v[116:117], v[78:79], v[114:115] op_sel:[0,1] op_sel_hi:[1,0]
	v_pk_add_f32 v[120:121], v[120:121], v[152:153] neg_lo:[0,1] neg_hi:[0,1]
	v_pk_fma_f32 v[114:115], v[114:115], v[74:75], v[116:117] op_sel_hi:[1,0,1]
	v_pk_add_f32 v[152:153], v[122:123], v[130:131]
	v_pk_add_f32 v[122:123], v[122:123], v[130:131] neg_lo:[0,1] neg_hi:[0,1]
	v_pk_add_f32 v[130:131], v[126:127], v[124:125]
	v_pk_add_f32 v[72:73], v[126:127], v[124:125] neg_lo:[0,1] neg_hi:[0,1]
	v_pk_add_f32 v[124:125], v[80:81], v[172:173]
	v_pk_mul_f32 v[116:117], v[124:125], v[114:115] op_sel:[1,1] op_sel_hi:[0,1] neg_hi:[0,1]
	v_pk_add_f32 v[126:127], v[80:81], v[172:173] neg_lo:[0,1] neg_hi:[0,1]
	v_pk_fma_f32 v[116:117], v[124:125], v[114:115], v[116:117] op_sel_hi:[1,0,1]
	ds_write_b64 v221, v[116:117] offset:784
	v_pk_mul_f32 v[112:113], v[78:79], v[114:115] op_sel:[0,1] op_sel_hi:[1,0]
	v_pk_add_f32 v[158:159], v[132:133], v[128:129]
	v_pk_fma_f32 v[112:113], v[114:115], v[74:75], v[112:113] op_sel_hi:[1,0,1]
	v_pk_add_f32 v[80:81], v[132:133], v[128:129] neg_lo:[0,1] neg_hi:[0,1]
	v_pk_add_f32 v[128:129], v[174:175], v[176:177]
	v_pk_mul_f32 v[114:115], v[134:135], v[112:113] op_sel:[1,1] op_sel_hi:[0,1] neg_hi:[0,1]
	v_pk_add_f32 v[146:147], v[148:149], v[164:165]
	v_pk_fma_f32 v[114:115], v[134:135], v[112:113], v[114:115] op_sel_hi:[1,0,1]
	ds_write_b64 v221, v[114:115] offset:1048
	v_pk_mul_f32 v[114:115], v[78:79], v[112:113] op_sel:[0,1] op_sel_hi:[1,0]
	v_pk_add_f32 v[132:133], v[174:175], v[176:177] neg_lo:[0,1] neg_hi:[0,1]
	v_pk_fma_f32 v[112:113], v[112:113], v[74:75], v[114:115] op_sel_hi:[1,0,1]
	v_pk_add_f32 v[148:149], v[148:149], v[164:165] neg_lo:[0,1] neg_hi:[0,1]
	s_nop 0
	v_pk_mul_f32 v[114:115], v[152:153], v[112:113] op_sel:[1,1] op_sel_hi:[0,1] neg_hi:[0,1]
	s_nop 0
	v_pk_fma_f32 v[114:115], v[152:153], v[112:113], v[114:115] op_sel_hi:[1,0,1]
	ds_write_b64 v221, v[114:115] offset:1312
	v_pk_mul_f32 v[110:111], v[78:79], v[112:113] op_sel:[0,1] op_sel_hi:[1,0]
	s_nop 0
	v_pk_fma_f32 v[110:111], v[112:113], v[74:75], v[110:111] op_sel_hi:[1,0,1]
	s_nop 0
	s_nop 0
	v_pk_mul_f32 v[112:113], v[144:145], v[110:111] op_sel:[1,1] op_sel_hi:[0,1] neg_hi:[0,1]
	s_nop 0
	v_pk_fma_f32 v[112:113], v[144:145], v[110:111], v[112:113] op_sel_hi:[1,0,1]
	ds_write_b64 v221, v[112:113] offset:1576
	v_pk_mul_f32 v[112:113], v[78:79], v[110:111] op_sel:[0,1] op_sel_hi:[1,0]
	s_nop 0
	v_pk_fma_f32 v[110:111], v[110:111], v[74:75], v[112:113] op_sel_hi:[1,0,1]
	s_nop 0
	s_nop 0
	v_pk_mul_f32 v[112:113], v[128:129], v[110:111] op_sel:[1,1] op_sel_hi:[0,1] neg_hi:[0,1]
	s_nop 0
	v_pk_fma_f32 v[112:113], v[128:129], v[110:111], v[112:113] op_sel_hi:[1,0,1]
	ds_write_b64 v221, v[112:113] offset:1840
	v_pk_mul_f32 v[108:109], v[78:79], v[110:111] op_sel:[0,1] op_sel_hi:[1,0]
	s_nop 0
	v_pk_fma_f32 v[108:109], v[110:111], v[74:75], v[108:109] op_sel_hi:[1,0,1]
	s_nop 0
	s_nop 0
	v_pk_mul_f32 v[110:111], v[168:169], v[108:109] op_sel:[1,1] op_sel_hi:[0,1] neg_hi:[0,1]
	s_nop 0
	v_pk_fma_f32 v[110:111], v[168:169], v[108:109], v[110:111] op_sel_hi:[1,0,1]
	ds_write_b64 v221, v[110:111] offset:2104
	v_pk_mul_f32 v[110:111], v[78:79], v[108:109] op_sel:[0,1] op_sel_hi:[1,0]
	s_nop 0
	v_pk_fma_f32 v[108:109], v[108:109], v[74:75], v[110:111] op_sel_hi:[1,0,1]
	s_nop 0
	s_nop 0
	v_pk_mul_f32 v[110:111], v[146:147], v[108:109] op_sel:[1,1] op_sel_hi:[0,1] neg_hi:[0,1]
	s_nop 0
	v_pk_fma_f32 v[110:111], v[146:147], v[108:109], v[110:111] op_sel_hi:[1,0,1]
	ds_write_b64 v221, v[110:111] offset:2368
	v_pk_mul_f32 v[106:107], v[78:79], v[108:109] op_sel:[0,1] op_sel_hi:[1,0]
	s_nop 0
	v_pk_fma_f32 v[106:107], v[108:109], v[74:75], v[106:107] op_sel_hi:[1,0,1]
	s_nop 0
	s_nop 0
	v_pk_mul_f32 v[108:109], v[156:157], v[106:107] op_sel:[1,1] op_sel_hi:[0,1] neg_hi:[0,1]
	s_nop 0
	v_pk_fma_f32 v[108:109], v[156:157], v[106:107], v[108:109] op_sel_hi:[1,0,1]
	ds_write_b64 v221, v[108:109] offset:2632
	v_pk_mul_f32 v[108:109], v[78:79], v[106:107] op_sel:[0,1] op_sel_hi:[1,0]
	s_nop 0
	v_pk_fma_f32 v[106:107], v[106:107], v[74:75], v[108:109] op_sel_hi:[1,0,1]
	s_nop 0
	s_nop 0
	v_pk_mul_f32 v[108:109], v[158:159], v[106:107] op_sel:[1,1] op_sel_hi:[0,1] neg_hi:[0,1]
	s_nop 0
	v_pk_fma_f32 v[108:109], v[158:159], v[106:107], v[108:109] op_sel_hi:[1,0,1]
	ds_write_b64 v221, v[108:109] offset:2896
	v_pk_mul_f32 v[108:109], v[78:79], v[106:107] op_sel:[0,1] op_sel_hi:[1,0]
	s_nop 0
	v_pk_fma_f32 v[106:107], v[106:107], v[74:75], v[108:109] op_sel_hi:[1,0,1]
	s_nop 0
	s_nop 0
	v_pk_mul_f32 v[108:109], v[160:161], v[106:107] op_sel:[1,1] op_sel_hi:[0,1] neg_hi:[0,1]
	s_nop 0
	v_pk_fma_f32 v[108:109], v[160:161], v[106:107], v[108:109] op_sel_hi:[1,0,1]
	ds_write_b64 v221, v[108:109] offset:3160
	v_pk_mul_f32 v[102:103], v[78:79], v[106:107] op_sel:[0,1] op_sel_hi:[1,0]
	s_nop 0
	v_pk_fma_f32 v[102:103], v[106:107], v[74:75], v[102:103] op_sel_hi:[1,0,1]
	s_nop 0
	s_nop 0
	v_pk_mul_f32 v[106:107], v[130:131], v[102:103] op_sel:[1,1] op_sel_hi:[0,1] neg_hi:[0,1]
	s_nop 0
	v_pk_fma_f32 v[106:107], v[130:131], v[102:103], v[106:107] op_sel_hi:[1,0,1]
	ds_write_b64 v221, v[106:107] offset:3424
	v_pk_mul_f32 v[106:107], v[78:79], v[102:103] op_sel:[0,1] op_sel_hi:[1,0]
	s_nop 0
	v_pk_fma_f32 v[102:103], v[102:103], v[74:75], v[106:107] op_sel_hi:[1,0,1]
	s_nop 0
	s_nop 0
	v_pk_mul_f32 v[106:107], v[150:151], v[102:103] op_sel:[1,1] op_sel_hi:[0,1] neg_hi:[0,1]
	v_pk_fma_f32 v[106:107], v[150:151], v[102:103], v[106:107] op_sel_hi:[1,0,1]
	ds_write_b64 v221, v[106:107] offset:3688
	v_pk_mul_f32 v[100:101], v[78:79], v[102:103] op_sel:[0,1] op_sel_hi:[1,0]
	s_nop 0
	v_pk_fma_f32 v[100:101], v[102:103], v[74:75], v[100:101] op_sel_hi:[1,0,1]
	s_nop 0
	s_nop 0
	v_pk_mul_f32 v[102:103], v[162:163], v[100:101] op_sel:[1,1] op_sel_hi:[0,1] neg_hi:[0,1]
	v_pk_fma_f32 v[102:103], v[162:163], v[100:101], v[102:103] op_sel_hi:[1,0,1]
	ds_write_b64 v221, v[102:103] offset:3952
	v_pk_mul_f32 v[102:103], v[78:79], v[100:101] op_sel:[0,1] op_sel_hi:[1,0]
	s_nop 0
	v_pk_fma_f32 v[100:101], v[100:101], v[74:75], v[102:103] op_sel_hi:[1,0,1]
	s_nop 0
	s_nop 0
	v_pk_mul_f32 v[102:103], v[118:119], v[100:101] op_sel:[1,1] op_sel_hi:[0,1] neg_hi:[0,1]
	v_pk_fma_f32 v[102:103], v[118:119], v[100:101], v[102:103] op_sel_hi:[1,0,1]
	ds_write_b64 v221, v[102:103] offset:4216
	v_pk_mul_f32 v[98:99], v[78:79], v[100:101] op_sel:[0,1] op_sel_hi:[1,0]
	s_nop 0
	v_pk_fma_f32 v[98:99], v[100:101], v[74:75], v[98:99] op_sel_hi:[1,0,1]
	s_nop 0
	s_nop 0
	v_pk_mul_f32 v[100:101], v[120:121], v[98:99] op_sel:[1,1] op_sel_hi:[0,1] neg_hi:[0,1]
	v_pk_fma_f32 v[100:101], v[120:121], v[98:99], v[100:101] op_sel_hi:[1,0,1]
	ds_write_b64 v221, v[100:101] offset:4480
	v_pk_mul_f32 v[100:101], v[78:79], v[98:99] op_sel:[0,1] op_sel_hi:[1,0]
	s_nop 0
	v_pk_fma_f32 v[98:99], v[98:99], v[74:75], v[100:101] op_sel_hi:[1,0,1]
	s_nop 0
	s_nop 0
	v_pk_mul_f32 v[100:101], v[142:143], v[98:99] op_sel:[1,1] op_sel_hi:[0,1] neg_hi:[0,1]
	v_pk_fma_f32 v[100:101], v[142:143], v[98:99], v[100:101] op_sel_hi:[1,0,1]
	ds_write_b64 v221, v[100:101] offset:4744
	v_pk_mul_f32 v[96:97], v[78:79], v[98:99] op_sel:[0,1] op_sel_hi:[1,0]
	s_nop 0
	v_pk_fma_f32 v[96:97], v[98:99], v[74:75], v[96:97] op_sel_hi:[1,0,1]
	s_nop 0
	s_nop 0
	v_pk_mul_f32 v[98:99], v[126:127], v[96:97] op_sel:[1,1] op_sel_hi:[0,1] neg_hi:[0,1]
	v_pk_fma_f32 v[98:99], v[126:127], v[96:97], v[98:99] op_sel_hi:[1,0,1]
	ds_write_b64 v221, v[98:99] offset:5008
	v_pk_mul_f32 v[98:99], v[78:79], v[96:97] op_sel:[0,1] op_sel_hi:[1,0]
	s_nop 0
	v_pk_fma_f32 v[96:97], v[96:97], v[74:75], v[98:99] op_sel_hi:[1,0,1]
	s_nop 0
	s_nop 0
	v_pk_mul_f32 v[98:99], v[136:137], v[96:97] op_sel:[1,1] op_sel_hi:[0,1] neg_hi:[0,1]
	v_pk_fma_f32 v[98:99], v[136:137], v[96:97], v[98:99] op_sel_hi:[1,0,1]
	ds_write_b64 v221, v[98:99] offset:5272
	v_pk_mul_f32 v[94:95], v[78:79], v[96:97] op_sel:[0,1] op_sel_hi:[1,0]
	s_nop 0
	v_pk_fma_f32 v[94:95], v[96:97], v[74:75], v[94:95] op_sel_hi:[1,0,1]
	s_nop 0
	s_nop 0
	v_pk_mul_f32 v[96:97], v[122:123], v[94:95] op_sel:[1,1] op_sel_hi:[0,1] neg_hi:[0,1]
	v_pk_fma_f32 v[96:97], v[122:123], v[94:95], v[96:97] op_sel_hi:[1,0,1]
	ds_write_b64 v221, v[96:97] offset:5536
	v_pk_mul_f32 v[96:97], v[78:79], v[94:95] op_sel:[0,1] op_sel_hi:[1,0]
	s_nop 0
	v_pk_fma_f32 v[94:95], v[94:95], v[74:75], v[96:97] op_sel_hi:[1,0,1]
	s_nop 0
	s_nop 0
	v_pk_mul_f32 v[96:97], v[138:139], v[94:95] op_sel:[1,1] op_sel_hi:[0,1] neg_hi:[0,1]
	v_pk_fma_f32 v[96:97], v[138:139], v[94:95], v[96:97] op_sel_hi:[1,0,1]
	ds_write_b64 v221, v[96:97] offset:5800
	v_pk_mul_f32 v[92:93], v[78:79], v[94:95] op_sel:[0,1] op_sel_hi:[1,0]
	s_nop 0
	v_pk_fma_f32 v[92:93], v[94:95], v[74:75], v[92:93] op_sel_hi:[1,0,1]
	s_nop 0
	s_nop 0
	v_pk_mul_f32 v[94:95], v[132:133], v[92:93] op_sel:[1,1] op_sel_hi:[0,1] neg_hi:[0,1]
	v_pk_fma_f32 v[94:95], v[132:133], v[92:93], v[94:95] op_sel_hi:[1,0,1]
	ds_write_b64 v221, v[94:95] offset:6064
	v_pk_mul_f32 v[94:95], v[78:79], v[92:93] op_sel:[0,1] op_sel_hi:[1,0]
	s_nop 0
	v_pk_fma_f32 v[92:93], v[92:93], v[74:75], v[94:95] op_sel_hi:[1,0,1]
	s_nop 0
	s_nop 0
	v_pk_mul_f32 v[94:95], v[82:83], v[92:93] op_sel:[1,1] op_sel_hi:[0,1] neg_hi:[0,1]
	v_pk_fma_f32 v[82:83], v[82:83], v[92:93], v[94:95] op_sel_hi:[1,0,1]
	ds_write_b64 v221, v[82:83] offset:6328
	v_pk_mul_f32 v[82:83], v[78:79], v[92:93] op_sel:[0,1] op_sel_hi:[1,0]
	s_nop 0
	v_pk_fma_f32 v[82:83], v[92:93], v[74:75], v[82:83] op_sel_hi:[1,0,1]
	s_nop 0
	s_nop 0
	v_pk_mul_f32 v[90:91], v[148:149], v[82:83] op_sel:[1,1] op_sel_hi:[0,1] neg_hi:[0,1]
	v_pk_fma_f32 v[90:91], v[148:149], v[82:83], v[90:91] op_sel_hi:[1,0,1]
	ds_write_b64 v221, v[90:91] offset:6592
	v_pk_mul_f32 v[90:91], v[78:79], v[82:83] op_sel:[0,1] op_sel_hi:[1,0]
	s_nop 0
	v_pk_fma_f32 v[82:83], v[82:83], v[74:75], v[90:91] op_sel_hi:[1,0,1]
	s_nop 0
	s_nop 0
	v_pk_mul_f32 v[90:91], v[76:77], v[82:83] op_sel:[1,1] op_sel_hi:[0,1] neg_hi:[0,1]
	v_pk_fma_f32 v[76:77], v[76:77], v[82:83], v[90:91] op_sel_hi:[1,0,1]
	ds_write_b64 v221, v[76:77] offset:6856
	v_pk_mul_f32 v[76:77], v[78:79], v[82:83] op_sel:[0,1] op_sel_hi:[1,0]
	s_nop 0
	v_pk_fma_f32 v[76:77], v[82:83], v[74:75], v[76:77] op_sel_hi:[1,0,1]
	s_nop 0
	s_nop 0
	v_pk_mul_f32 v[82:83], v[80:81], v[76:77] op_sel:[1,1] op_sel_hi:[0,1] neg_hi:[0,1]
	v_pk_fma_f32 v[80:81], v[80:81], v[76:77], v[82:83] op_sel_hi:[1,0,1]
	ds_write_b64 v221, v[80:81] offset:7120
	v_pk_mul_f32 v[80:81], v[78:79], v[76:77] op_sel:[0,1] op_sel_hi:[1,0]
	s_nop 0
	v_pk_fma_f32 v[76:77], v[76:77], v[74:75], v[80:81] op_sel_hi:[1,0,1]
	s_nop 0
	s_nop 0
	v_pk_mul_f32 v[80:81], v[68:69], v[76:77] op_sel:[1,1] op_sel_hi:[0,1] neg_hi:[0,1]
	v_pk_fma_f32 v[68:69], v[68:69], v[76:77], v[80:81] op_sel_hi:[1,0,1]
	ds_write_b64 v221, v[68:69] offset:7384
	v_pk_mul_f32 v[68:69], v[78:79], v[76:77] op_sel:[0,1] op_sel_hi:[1,0]
	s_nop 0
	v_pk_fma_f32 v[68:69], v[76:77], v[74:75], v[68:69] op_sel_hi:[1,0,1]
	s_nop 0
	s_nop 0
	v_pk_mul_f32 v[76:77], v[72:73], v[68:69] op_sel:[1,1] op_sel_hi:[0,1] neg_hi:[0,1]
	v_pk_fma_f32 v[72:73], v[72:73], v[68:69], v[76:77] op_sel_hi:[1,0,1]
	ds_write_b64 v221, v[72:73] offset:7648
	v_pk_mul_f32 v[72:73], v[78:79], v[68:69] op_sel:[0,1] op_sel_hi:[1,0]
	s_nop 0
	v_pk_fma_f32 v[68:69], v[68:69], v[74:75], v[72:73] op_sel_hi:[1,0,1]
	s_nop 0
	s_nop 0
	v_pk_mul_f32 v[72:73], v[66:67], v[68:69] op_sel:[1,1] op_sel_hi:[0,1] neg_hi:[0,1]
	v_pk_fma_f32 v[66:67], v[66:67], v[68:69], v[72:73] op_sel_hi:[1,0,1]
	ds_write_b64 v221, v[66:67] offset:7912
	v_pk_mul_f32 v[66:67], v[78:79], v[68:69] op_sel:[0,1] op_sel_hi:[1,0]
	s_nop 0
	v_pk_fma_f32 v[66:67], v[68:69], v[74:75], v[66:67] op_sel_hi:[1,0,1]
	s_nop 0
	s_nop 0
	v_pk_mul_f32 v[68:69], v[70:71], v[66:67] op_sel:[1,1] op_sel_hi:[0,1] neg_hi:[0,1]
	v_pk_fma_f32 v[66:67], v[70:71], v[66:67], v[68:69] op_sel_hi:[1,0,1]
	ds_write_b64 v221, v[66:67] offset:8176
	s_waitcnt lgkmcnt(0)
	s_barrier
	ds_read2_b64 v[66:69], v104 offset1:1
	ds_read2_b64 v[70:73], v104 offset0:2 offset1:3
	ds_read2_b64 v[74:77], v104 offset0:4 offset1:5
	ds_read2_b64 v[78:81], v104 offset0:6 offset1:7
	ds_read2_b64 v[82:85], v104 offset0:8 offset1:9
	ds_read2_b64 v[86:89], v104 offset0:10 offset1:11
	ds_read2_b64 v[90:93], v104 offset0:12 offset1:13
	ds_read2_b64 v[94:97], v104 offset0:14 offset1:15
	ds_read2_b64 v[98:101], v104 offset0:16 offset1:17
	ds_read2_b64 v[106:109], v104 offset0:18 offset1:19
	ds_read2_b64 v[110:113], v104 offset0:20 offset1:21
	ds_read2_b64 v[114:117], v104 offset0:22 offset1:23
	ds_read2_b64 v[118:121], v104 offset0:24 offset1:25
	ds_read2_b64 v[122:125], v104 offset0:26 offset1:27
	ds_read2_b64 v[126:129], v104 offset0:28 offset1:29
	ds_read2_b64 v[130:133], v104 offset0:30 offset1:31
	s_waitcnt lgkmcnt(7)
	v_pk_add_f32 v[102:103], v[66:67], v[98:99]
	v_pk_add_f32 v[66:67], v[66:67], v[98:99] neg_lo:[0,1] neg_hi:[0,1]
	v_pk_add_f32 v[98:99], v[68:69], v[100:101]
	v_pk_add_f32 v[68:69], v[68:69], v[100:101] neg_lo:[0,1] neg_hi:[0,1]
	s_nop 0
	v_pk_mul_f32 v[100:101], v[68:69], s[18:19]
	s_nop 0
	v_pk_fma_f32 v[68:69], v[68:69], s[20:21], v[100:101] op_sel:[0,0,1] op_sel_hi:[1,0,0]
	s_waitcnt lgkmcnt(6)
	v_pk_add_f32 v[100:101], v[70:71], v[106:107]
	v_pk_add_f32 v[70:71], v[70:71], v[106:107] neg_lo:[0,1] neg_hi:[0,1]
	s_nop 0
	v_pk_mul_f32 v[106:107], v[70:71], s[4:5]
	s_nop 0
	v_pk_fma_f32 v[70:71], v[70:71], s[6:7], v[106:107] op_sel:[0,0,1] op_sel_hi:[1,0,0]
	v_pk_add_f32 v[106:107], v[72:73], v[108:109]
	v_pk_add_f32 v[72:73], v[72:73], v[108:109] neg_lo:[0,1] neg_hi:[0,1]
	s_nop 0
	v_pk_mul_f32 v[108:109], v[72:73], s[22:23]
	s_nop 0
	v_pk_fma_f32 v[72:73], v[72:73], s[24:25], v[108:109] op_sel:[0,0,1] op_sel_hi:[1,0,0]
	s_waitcnt lgkmcnt(5)
	v_pk_add_f32 v[108:109], v[74:75], v[110:111]
	v_pk_add_f32 v[74:75], v[74:75], v[110:111] neg_lo:[0,1] neg_hi:[0,1]
	s_nop 0
	v_pk_mul_f32 v[110:111], v[74:75], s[8:9]
	s_nop 0
	v_pk_fma_f32 v[74:75], v[74:75], s[10:11], v[110:111] op_sel:[0,0,1] op_sel_hi:[1,0,0]
	v_pk_add_f32 v[110:111], v[76:77], v[112:113]
	v_pk_add_f32 v[76:77], v[76:77], v[112:113] neg_lo:[0,1] neg_hi:[0,1]
	s_nop 0
	v_pk_mul_f32 v[112:113], v[76:77], s[26:27]
	s_nop 0
	v_pk_fma_f32 v[76:77], v[76:77], s[0:1], v[112:113] op_sel:[0,0,1] op_sel_hi:[1,0,0]
	s_waitcnt lgkmcnt(4)
	v_pk_add_f32 v[112:113], v[78:79], v[114:115]
	v_pk_add_f32 v[78:79], v[78:79], v[114:115] neg_lo:[0,1] neg_hi:[0,1]
	s_mov_b64 s[0:1], 0
	v_pk_mul_f32 v[114:115], v[78:79], s[12:13]
	s_nop 0
	v_pk_fma_f32 v[78:79], v[78:79], s[14:15], v[114:115] op_sel:[0,0,1] op_sel_hi:[1,0,0]
	v_pk_add_f32 v[114:115], v[80:81], v[116:117]
	v_pk_add_f32 v[80:81], v[80:81], v[116:117] neg_lo:[0,1] neg_hi:[0,1]
	s_nop 0
	v_pk_mul_f32 v[116:117], v[80:81], s[34:35]
	s_nop 0
	v_pk_fma_f32 v[80:81], v[80:81], s[44:45], v[116:117] op_sel:[0,0,1] op_sel_hi:[1,0,0]
	s_waitcnt lgkmcnt(3)
	v_pk_add_f32 v[116:117], v[82:83], v[118:119]
	v_pk_add_f32 v[118:119], v[82:83], v[118:119] op_sel:[1,1] op_sel_hi:[0,0] neg_lo:[0,1] neg_hi:[1,0]
	s_mov_b64 s[44:45], -1
	v_pk_add_f32 v[82:83], v[84:85], v[120:121]
	v_pk_add_f32 v[84:85], v[84:85], v[120:121] neg_lo:[0,1] neg_hi:[0,1]
	s_nop 0
	v_pk_mul_f32 v[120:121], v[84:85], s[34:35]
	s_nop 0
	v_pk_fma_f32 v[84:85], v[84:85], s[18:19], v[120:121] op_sel:[0,0,1] op_sel_hi:[1,0,0]
	s_waitcnt lgkmcnt(2)
	v_pk_add_f32 v[120:121], v[86:87], v[122:123]
	v_pk_add_f32 v[86:87], v[86:87], v[122:123] neg_lo:[0,1] neg_hi:[0,1]
	s_nop 0
	v_pk_mul_f32 v[122:123], v[86:87], s[12:13]
	s_nop 0
	v_pk_fma_f32 v[86:87], v[86:87], s[4:5], v[122:123] op_sel:[0,0,1] op_sel_hi:[1,0,0]
	v_pk_add_f32 v[122:123], v[88:89], v[124:125]
	v_pk_add_f32 v[88:89], v[88:89], v[124:125] neg_lo:[0,1] neg_hi:[0,1]
	s_nop 0
	v_pk_mul_f32 v[124:125], v[88:89], s[26:27]
	s_nop 0
	v_pk_fma_f32 v[88:89], v[88:89], s[22:23], v[124:125] op_sel:[0,0,1] op_sel_hi:[1,0,0]
	s_waitcnt lgkmcnt(1)
	v_pk_add_f32 v[124:125], v[90:91], v[126:127]
	v_pk_add_f32 v[90:91], v[90:91], v[126:127] neg_lo:[0,1] neg_hi:[0,1]
	s_nop 0
	v_pk_mul_f32 v[126:127], v[90:91], s[8:9]
	s_nop 0
	v_pk_fma_f32 v[90:91], v[90:91], s[8:9], v[126:127] op_sel:[0,0,1] op_sel_hi:[1,0,0]
	v_pk_add_f32 v[126:127], v[92:93], v[128:129]
	v_pk_add_f32 v[92:93], v[92:93], v[128:129] neg_lo:[0,1] neg_hi:[0,1]
	s_nop 0
	v_pk_mul_f32 v[128:129], v[92:93], s[22:23]
	s_nop 0
	v_pk_fma_f32 v[92:93], v[92:93], s[26:27], v[128:129] op_sel:[0,0,1] op_sel_hi:[1,0,0]
	s_waitcnt lgkmcnt(0)
	v_pk_add_f32 v[128:129], v[94:95], v[130:131]
	v_pk_add_f32 v[94:95], v[94:95], v[130:131] neg_lo:[0,1] neg_hi:[0,1]
	s_nop 0
	v_pk_mul_f32 v[130:131], v[94:95], s[4:5]
	s_nop 0
	v_pk_fma_f32 v[94:95], v[94:95], s[12:13], v[130:131] op_sel:[0,0,1] op_sel_hi:[1,0,0]
	v_pk_add_f32 v[130:131], v[96:97], v[132:133]
	v_pk_add_f32 v[96:97], v[96:97], v[132:133] neg_lo:[0,1] neg_hi:[0,1]
	s_nop 0
	v_pk_mul_f32 v[132:133], v[96:97], s[18:19]
	s_nop 0
	v_pk_fma_f32 v[96:97], v[96:97], s[34:35], v[132:133] op_sel:[0,0,1] op_sel_hi:[1,0,0]
	v_pk_add_f32 v[132:133], v[102:103], v[116:117]
	v_pk_add_f32 v[102:103], v[102:103], v[116:117] neg_lo:[0,1] neg_hi:[0,1]
	v_pk_add_f32 v[116:117], v[98:99], v[82:83]
	v_pk_add_f32 v[82:83], v[98:99], v[82:83] neg_lo:[0,1] neg_hi:[0,1]
	s_nop 0
	v_pk_mul_f32 v[98:99], v[82:83], s[4:5]
	s_nop 0
	v_pk_fma_f32 v[82:83], v[82:83], s[6:7], v[98:99] op_sel:[0,0,1] op_sel_hi:[1,0,0]
	v_pk_add_f32 v[98:99], v[100:101], v[120:121]
	v_pk_add_f32 v[100:101], v[100:101], v[120:121] neg_lo:[0,1] neg_hi:[0,1]
	s_nop 0
	v_pk_mul_f32 v[120:121], v[100:101], s[8:9]
	s_nop 0
	v_pk_fma_f32 v[100:101], v[100:101], s[10:11], v[120:121] op_sel:[0,0,1] op_sel_hi:[1,0,0]
	v_pk_add_f32 v[120:121], v[106:107], v[122:123]
	v_pk_add_f32 v[106:107], v[106:107], v[122:123] neg_lo:[0,1] neg_hi:[0,1]
	s_nop 0
	v_pk_mul_f32 v[122:123], v[106:107], s[12:13]
	s_nop 0
	v_pk_fma_f32 v[106:107], v[106:107], s[14:15], v[122:123] op_sel:[0,0,1] op_sel_hi:[1,0,0]
	v_pk_add_f32 v[122:123], v[108:109], v[124:125]
	v_pk_add_f32 v[124:125], v[108:109], v[124:125] op_sel:[1,1] op_sel_hi:[0,0] neg_lo:[0,1] neg_hi:[1,0]
	s_nop 0
	v_pk_add_f32 v[108:109], v[110:111], v[126:127]
	v_pk_add_f32 v[110:111], v[110:111], v[126:127] neg_lo:[0,1] neg_hi:[0,1]
	s_nop 0
	v_pk_mul_f32 v[126:127], v[110:111], s[12:13]
	s_nop 0
	v_pk_fma_f32 v[110:111], v[110:111], s[4:5], v[126:127] op_sel:[0,0,1] op_sel_hi:[1,0,0]
	v_pk_add_f32 v[126:127], v[112:113], v[128:129]
	v_pk_add_f32 v[112:113], v[112:113], v[128:129] neg_lo:[0,1] neg_hi:[0,1]
	s_nop 0
	v_pk_mul_f32 v[128:129], v[112:113], s[8:9]
	s_nop 0
	v_pk_fma_f32 v[112:113], v[112:113], s[8:9], v[128:129] op_sel:[0,0,1] op_sel_hi:[1,0,0]
	v_pk_add_f32 v[128:129], v[114:115], v[130:131]
	v_pk_add_f32 v[114:115], v[114:115], v[130:131] neg_lo:[0,1] neg_hi:[0,1]
	s_nop 0
	v_pk_mul_f32 v[130:131], v[114:115], s[4:5]
	s_nop 0
	v_pk_fma_f32 v[114:115], v[114:115], s[12:13], v[130:131] op_sel:[0,0,1] op_sel_hi:[1,0,0]
	v_pk_add_f32 v[130:131], v[66:67], v[118:119]
	v_pk_add_f32 v[66:67], v[66:67], v[118:119] neg_lo:[0,1] neg_hi:[0,1]
	v_pk_add_f32 v[118:119], v[68:69], v[84:85]
	v_pk_add_f32 v[68:69], v[68:69], v[84:85] neg_lo:[0,1] neg_hi:[0,1]
	s_nop 0
	v_pk_mul_f32 v[84:85], v[68:69], s[4:5]
	s_nop 0
	v_pk_fma_f32 v[68:69], v[68:69], s[6:7], v[84:85] op_sel:[0,0,1] op_sel_hi:[1,0,0]
	v_pk_add_f32 v[84:85], v[70:71], v[86:87]
	v_pk_add_f32 v[70:71], v[70:71], v[86:87] neg_lo:[0,1] neg_hi:[0,1]
	s_nop 0
	v_pk_mul_f32 v[86:87], v[70:71], s[8:9]
	s_nop 0
	v_pk_fma_f32 v[70:71], v[70:71], s[10:11], v[86:87] op_sel:[0,0,1] op_sel_hi:[1,0,0]
	v_pk_add_f32 v[86:87], v[72:73], v[88:89]
	v_pk_add_f32 v[72:73], v[72:73], v[88:89] neg_lo:[0,1] neg_hi:[0,1]
	s_nop 0
	v_pk_mul_f32 v[88:89], v[72:73], s[12:13]
	s_nop 0
	v_pk_fma_f32 v[72:73], v[72:73], s[14:15], v[88:89] op_sel:[0,0,1] op_sel_hi:[1,0,0]
	v_pk_add_f32 v[88:89], v[74:75], v[90:91]
	v_pk_add_f32 v[90:91], v[74:75], v[90:91] op_sel:[1,1] op_sel_hi:[0,0] neg_lo:[0,1] neg_hi:[1,0]
	s_nop 0
	v_pk_add_f32 v[74:75], v[76:77], v[92:93]
	v_pk_add_f32 v[76:77], v[76:77], v[92:93] neg_lo:[0,1] neg_hi:[0,1]
	s_nop 0
	v_pk_mul_f32 v[92:93], v[76:77], s[12:13]
	s_nop 0
	v_pk_fma_f32 v[76:77], v[76:77], s[4:5], v[92:93] op_sel:[0,0,1] op_sel_hi:[1,0,0]
	v_pk_add_f32 v[92:93], v[78:79], v[94:95]
	v_pk_add_f32 v[78:79], v[78:79], v[94:95] neg_lo:[0,1] neg_hi:[0,1]
	s_nop 0
	v_pk_mul_f32 v[94:95], v[78:79], s[8:9]
	s_nop 0
	v_pk_fma_f32 v[78:79], v[78:79], s[8:9], v[94:95] op_sel:[0,0,1] op_sel_hi:[1,0,0]
	v_pk_add_f32 v[94:95], v[80:81], v[96:97]
	v_pk_add_f32 v[80:81], v[80:81], v[96:97] neg_lo:[0,1] neg_hi:[0,1]
	s_nop 0
	v_pk_mul_f32 v[96:97], v[80:81], s[4:5]
	s_nop 0
	v_pk_fma_f32 v[80:81], v[80:81], s[12:13], v[96:97] op_sel:[0,0,1] op_sel_hi:[1,0,0]
	v_pk_add_f32 v[96:97], v[132:133], v[122:123]
	v_pk_add_f32 v[122:123], v[132:133], v[122:123] neg_lo:[0,1] neg_hi:[0,1]
	v_pk_add_f32 v[132:133], v[116:117], v[108:109]
	v_pk_add_f32 v[108:109], v[116:117], v[108:109] neg_lo:[0,1] neg_hi:[0,1]
	s_nop 0
	v_pk_mul_f32 v[116:117], v[108:109], s[8:9]
	s_nop 0
	v_pk_fma_f32 v[108:109], v[108:109], s[10:11], v[116:117] op_sel:[0,0,1] op_sel_hi:[1,0,0]
	v_pk_add_f32 v[116:117], v[98:99], v[126:127]
	v_pk_add_f32 v[126:127], v[98:99], v[126:127] op_sel:[1,1] op_sel_hi:[0,0] neg_lo:[0,1] neg_hi:[1,0]
	s_nop 0
	v_pk_add_f32 v[98:99], v[120:121], v[128:129]
	v_pk_add_f32 v[120:121], v[120:121], v[128:129] neg_lo:[0,1] neg_hi:[0,1]
	s_nop 0
	v_pk_mul_f32 v[128:129], v[120:121], s[8:9]
	s_nop 0
	v_pk_fma_f32 v[120:121], v[120:121], s[8:9], v[128:129] op_sel:[0,0,1] op_sel_hi:[1,0,0]
	v_pk_add_f32 v[128:129], v[102:103], v[124:125]
	v_pk_add_f32 v[102:103], v[102:103], v[124:125] neg_lo:[0,1] neg_hi:[0,1]
	v_pk_add_f32 v[124:125], v[82:83], v[110:111]
	v_pk_add_f32 v[82:83], v[82:83], v[110:111] neg_lo:[0,1] neg_hi:[0,1]
	s_nop 0
	v_pk_mul_f32 v[110:111], v[82:83], s[8:9]
	s_nop 0
	v_pk_fma_f32 v[82:83], v[82:83], s[10:11], v[110:111] op_sel:[0,0,1] op_sel_hi:[1,0,0]
	v_pk_add_f32 v[110:111], v[100:101], v[112:113]
	v_pk_add_f32 v[112:113], v[100:101], v[112:113] op_sel:[1,1] op_sel_hi:[0,0] neg_lo:[0,1] neg_hi:[1,0]
	s_nop 0
	v_pk_add_f32 v[100:101], v[106:107], v[114:115]
	v_pk_add_f32 v[106:107], v[106:107], v[114:115] neg_lo:[0,1] neg_hi:[0,1]
	s_nop 0
	v_pk_mul_f32 v[114:115], v[106:107], s[8:9]
	s_nop 0
	v_pk_fma_f32 v[106:107], v[106:107], s[8:9], v[114:115] op_sel:[0,0,1] op_sel_hi:[1,0,0]
	v_pk_add_f32 v[114:115], v[130:131], v[88:89]
	v_pk_add_f32 v[88:89], v[130:131], v[88:89] neg_lo:[0,1] neg_hi:[0,1]
	v_pk_add_f32 v[130:131], v[118:119], v[74:75]
	v_pk_add_f32 v[74:75], v[118:119], v[74:75] neg_lo:[0,1] neg_hi:[0,1]
	s_nop 0
	v_pk_mul_f32 v[118:119], v[74:75], s[8:9]
	s_nop 0
	v_pk_fma_f32 v[74:75], v[74:75], s[10:11], v[118:119] op_sel:[0,0,1] op_sel_hi:[1,0,0]
	v_pk_add_f32 v[118:119], v[84:85], v[92:93]
	v_pk_add_f32 v[92:93], v[84:85], v[92:93] op_sel:[1,1] op_sel_hi:[0,0] neg_lo:[0,1] neg_hi:[1,0]
	s_nop 0
	v_pk_add_f32 v[84:85], v[86:87], v[94:95]
	v_pk_add_f32 v[86:87], v[86:87], v[94:95] neg_lo:[0,1] neg_hi:[0,1]
	s_nop 0
	v_pk_mul_f32 v[94:95], v[86:87], s[8:9]
	s_nop 0
	v_pk_fma_f32 v[86:87], v[86:87], s[8:9], v[94:95] op_sel:[0,0,1] op_sel_hi:[1,0,0]
	v_pk_add_f32 v[94:95], v[66:67], v[90:91]
	v_pk_add_f32 v[66:67], v[66:67], v[90:91] neg_lo:[0,1] neg_hi:[0,1]
	v_pk_add_f32 v[90:91], v[68:69], v[76:77]
	v_pk_add_f32 v[68:69], v[68:69], v[76:77] neg_lo:[0,1] neg_hi:[0,1]
	s_nop 0
	v_pk_mul_f32 v[76:77], v[68:69], s[8:9]
	s_nop 0
	v_pk_fma_f32 v[68:69], v[68:69], s[10:11], v[76:77] op_sel:[0,0,1] op_sel_hi:[1,0,0]
	v_pk_add_f32 v[76:77], v[70:71], v[78:79]
	v_pk_add_f32 v[78:79], v[70:71], v[78:79] op_sel:[1,1] op_sel_hi:[0,0] neg_lo:[0,1] neg_hi:[1,0]
	s_nop 0
	v_pk_add_f32 v[70:71], v[72:73], v[80:81]
	v_pk_add_f32 v[72:73], v[72:73], v[80:81] neg_lo:[0,1] neg_hi:[0,1]
	s_nop 0
	v_pk_mul_f32 v[80:81], v[72:73], s[8:9]
	s_nop 0
	v_pk_fma_f32 v[72:73], v[72:73], s[8:9], v[80:81] op_sel:[0,0,1] op_sel_hi:[1,0,0]
	v_pk_add_f32 v[80:81], v[96:97], v[116:117]
	v_pk_add_f32 v[96:97], v[96:97], v[116:117] neg_lo:[0,1] neg_hi:[0,1]
	v_pk_add_f32 v[116:117], v[132:133], v[98:99]
	v_pk_add_f32 v[132:133], v[132:133], v[98:99] op_sel:[1,1] op_sel_hi:[0,0] neg_lo:[0,1] neg_hi:[1,0]
	s_nop 0
	v_pk_add_f32 v[98:99], v[122:123], v[126:127]
	v_pk_add_f32 v[122:123], v[122:123], v[126:127] neg_lo:[0,1] neg_hi:[0,1]
	v_pk_add_f32 v[126:127], v[108:109], v[120:121]
	v_pk_add_f32 v[120:121], v[108:109], v[120:121] op_sel:[1,1] op_sel_hi:[0,0] neg_lo:[0,1] neg_hi:[1,0]
	s_nop 0
	v_pk_add_f32 v[108:109], v[128:129], v[110:111]
	v_pk_add_f32 v[110:111], v[128:129], v[110:111] neg_lo:[0,1] neg_hi:[0,1]
	v_pk_add_f32 v[128:129], v[124:125], v[100:101]
	v_pk_add_f32 v[124:125], v[124:125], v[100:101] op_sel:[1,1] op_sel_hi:[0,0] neg_lo:[0,1] neg_hi:[1,0]
	s_nop 0
	v_pk_add_f32 v[100:101], v[102:103], v[112:113]
	v_pk_add_f32 v[102:103], v[102:103], v[112:113] neg_lo:[0,1] neg_hi:[0,1]
	v_pk_add_f32 v[112:113], v[82:83], v[106:107]
	v_pk_add_f32 v[106:107], v[82:83], v[106:107] op_sel:[1,1] op_sel_hi:[0,0] neg_lo:[0,1] neg_hi:[1,0]
	s_nop 0
	v_pk_add_f32 v[82:83], v[114:115], v[118:119]
	v_pk_add_f32 v[114:115], v[114:115], v[118:119] neg_lo:[0,1] neg_hi:[0,1]
	v_pk_add_f32 v[118:119], v[130:131], v[84:85]
	v_pk_add_f32 v[130:131], v[130:131], v[84:85] op_sel:[1,1] op_sel_hi:[0,0] neg_lo:[0,1] neg_hi:[1,0]
	s_nop 0
	v_pk_add_f32 v[84:85], v[88:89], v[92:93]
	v_pk_add_f32 v[88:89], v[88:89], v[92:93] neg_lo:[0,1] neg_hi:[0,1]
	v_pk_add_f32 v[92:93], v[74:75], v[86:87]
	v_pk_add_f32 v[86:87], v[74:75], v[86:87] op_sel:[1,1] op_sel_hi:[0,0] neg_lo:[0,1] neg_hi:[1,0]
	s_nop 0
	v_pk_add_f32 v[74:75], v[94:95], v[76:77]
	v_pk_add_f32 v[76:77], v[94:95], v[76:77] neg_lo:[0,1] neg_hi:[0,1]
	v_pk_add_f32 v[94:95], v[90:91], v[70:71]
	v_pk_add_f32 v[90:91], v[90:91], v[70:71] op_sel:[1,1] op_sel_hi:[0,0] neg_lo:[0,1] neg_hi:[1,0]
	s_nop 0
	v_pk_add_f32 v[70:71], v[66:67], v[78:79]
	v_pk_add_f32 v[66:67], v[66:67], v[78:79] neg_lo:[0,1] neg_hi:[0,1]
	v_pk_add_f32 v[78:79], v[68:69], v[72:73]
	v_pk_add_f32 v[72:73], v[68:69], v[72:73] op_sel:[1,1] op_sel_hi:[0,0] neg_lo:[0,1] neg_hi:[1,0]
	s_nop 0
	v_pk_add_f32 v[68:69], v[80:81], v[116:117]
	v_pk_add_f32 v[80:81], v[80:81], v[116:117] neg_lo:[0,1] neg_hi:[0,1]
	v_pk_add_f32 v[116:117], v[96:97], v[132:133]
	v_pk_add_f32 v[96:97], v[96:97], v[132:133] neg_lo:[0,1] neg_hi:[0,1]
	v_pk_add_f32 v[132:133], v[98:99], v[126:127]
	v_pk_add_f32 v[98:99], v[98:99], v[126:127] neg_lo:[0,1] neg_hi:[0,1]
	v_pk_add_f32 v[126:127], v[122:123], v[120:121]
	v_pk_add_f32 v[120:121], v[122:123], v[120:121] neg_lo:[0,1] neg_hi:[0,1]
	v_pk_add_f32 v[122:123], v[108:109], v[128:129]
	v_pk_add_f32 v[108:109], v[108:109], v[128:129] neg_lo:[0,1] neg_hi:[0,1]
	v_pk_add_f32 v[128:129], v[110:111], v[124:125]
	v_pk_add_f32 v[110:111], v[110:111], v[124:125] neg_lo:[0,1] neg_hi:[0,1]
	v_pk_add_f32 v[124:125], v[100:101], v[112:113]
	v_pk_add_f32 v[100:101], v[100:101], v[112:113] neg_lo:[0,1] neg_hi:[0,1]
	v_pk_add_f32 v[112:113], v[102:103], v[106:107]
	v_pk_add_f32 v[102:103], v[102:103], v[106:107] neg_lo:[0,1] neg_hi:[0,1]
	v_pk_add_f32 v[106:107], v[82:83], v[118:119]
	v_pk_mul_f32 v[68:69], v[68:69], s[2:3] op_sel_hi:[1,0]
	global_store_dwordx2 v[2:3], v[68:69], off
	v_pk_mul_f32 v[68:69], v[106:107], s[2:3] op_sel_hi:[1,0]
	v_pk_add_f32 v[82:83], v[82:83], v[118:119] neg_lo:[0,1] neg_hi:[0,1]
	v_pk_add_f32 v[118:119], v[114:115], v[130:131]
	v_pk_add_f32 v[114:115], v[114:115], v[130:131] neg_lo:[0,1] neg_hi:[0,1]
	v_pk_add_f32 v[130:131], v[84:85], v[92:93]
	v_pk_add_f32 v[84:85], v[84:85], v[92:93] neg_lo:[0,1] neg_hi:[0,1]
	v_pk_add_f32 v[92:93], v[88:89], v[86:87]
	v_pk_add_f32 v[86:87], v[88:89], v[86:87] neg_lo:[0,1] neg_hi:[0,1]
	v_pk_add_f32 v[88:89], v[74:75], v[94:95]
	global_store_dwordx2 v[4:5], v[68:69], off
	v_pk_mul_f32 v[68:69], v[122:123], s[2:3] op_sel_hi:[1,0]
	global_store_dwordx2 v[6:7], v[68:69], off
	v_pk_mul_f32 v[68:69], v[88:89], s[2:3] op_sel_hi:[1,0]
	global_store_dwordx2 v[8:9], v[68:69], off
	v_pk_mul_f32 v[68:69], v[132:133], s[2:3] op_sel_hi:[1,0]
	global_store_dwordx2 v[10:11], v[68:69], off
	v_pk_mul_f32 v[68:69], v[130:131], s[2:3] op_sel_hi:[1,0]
	v_pk_add_f32 v[74:75], v[74:75], v[94:95] neg_lo:[0,1] neg_hi:[0,1]
	v_pk_add_f32 v[94:95], v[76:77], v[90:91]
	v_pk_add_f32 v[76:77], v[76:77], v[90:91] neg_lo:[0,1] neg_hi:[0,1]
	v_pk_add_f32 v[90:91], v[70:71], v[78:79]
	global_store_dwordx2 v[12:13], v[68:69], off
	v_pk_mul_f32 v[68:69], v[124:125], s[2:3] op_sel_hi:[1,0]
	global_store_dwordx2 v[14:15], v[68:69], off
	v_pk_mul_f32 v[68:69], v[90:91], s[2:3] op_sel_hi:[1,0]
	global_store_dwordx2 v[16:17], v[68:69], off
	v_pk_mul_f32 v[68:69], v[116:117], s[2:3] op_sel_hi:[1,0]
	global_store_dwordx2 v[18:19], v[68:69], off
	v_pk_mul_f32 v[68:69], v[118:119], s[2:3] op_sel_hi:[1,0]
	global_store_dwordx2 v[20:21], v[68:69], off
	v_pk_mul_f32 v[68:69], v[128:129], s[2:3] op_sel_hi:[1,0]
	global_store_dwordx2 v[22:23], v[68:69], off
	v_pk_mul_f32 v[68:69], v[94:95], s[2:3] op_sel_hi:[1,0]
	global_store_dwordx2 v[24:25], v[68:69], off
	v_pk_mul_f32 v[68:69], v[126:127], s[2:3] op_sel_hi:[1,0]
	global_store_dwordx2 v[26:27], v[68:69], off
	v_pk_mul_f32 v[68:69], v[92:93], s[2:3] op_sel_hi:[1,0]
	v_pk_add_f32 v[70:71], v[70:71], v[78:79] neg_lo:[0,1] neg_hi:[0,1]
	v_pk_add_f32 v[78:79], v[66:67], v[72:73]
	global_store_dwordx2 v[28:29], v[68:69], off
	v_pk_mul_f32 v[68:69], v[112:113], s[2:3] op_sel_hi:[1,0]
	global_store_dwordx2 v[30:31], v[68:69], off
	v_pk_mul_f32 v[68:69], v[78:79], s[2:3] op_sel_hi:[1,0]
	global_store_dwordx2 v[32:33], v[68:69], off
	v_pk_mul_f32 v[68:69], v[80:81], s[2:3] op_sel_hi:[1,0]
	global_store_dwordx2 v[34:35], v[68:69], off
	v_pk_mul_f32 v[68:69], v[82:83], s[2:3] op_sel_hi:[1,0]
	global_store_dwordx2 v[36:37], v[68:69], off
	v_pk_mul_f32 v[68:69], v[108:109], s[2:3] op_sel_hi:[1,0]
	global_store_dwordx2 v[38:39], v[68:69], off
	v_pk_mul_f32 v[68:69], v[74:75], s[2:3] op_sel_hi:[1,0]
	global_store_dwordx2 v[40:41], v[68:69], off
	v_pk_mul_f32 v[68:69], v[98:99], s[2:3] op_sel_hi:[1,0]
	global_store_dwordx2 v[42:43], v[68:69], off
	v_pk_mul_f32 v[68:69], v[84:85], s[2:3] op_sel_hi:[1,0]
	global_store_dwordx2 v[44:45], v[68:69], off
	v_pk_mul_f32 v[68:69], v[100:101], s[2:3] op_sel_hi:[1,0]
	global_store_dwordx2 v[46:47], v[68:69], off
	v_pk_mul_f32 v[68:69], v[70:71], s[2:3] op_sel_hi:[1,0]
	global_store_dwordx2 v[48:49], v[68:69], off
	v_pk_mul_f32 v[68:69], v[96:97], s[2:3] op_sel_hi:[1,0]
	global_store_dwordx2 v[50:51], v[68:69], off
	v_pk_mul_f32 v[68:69], v[114:115], s[2:3] op_sel_hi:[1,0]
	global_store_dwordx2 v[52:53], v[68:69], off
	v_pk_mul_f32 v[68:69], v[110:111], s[2:3] op_sel_hi:[1,0]
	global_store_dwordx2 v[54:55], v[68:69], off
	v_pk_mul_f32 v[68:69], v[76:77], s[2:3] op_sel_hi:[1,0]
	global_store_dwordx2 v[56:57], v[68:69], off
	v_pk_mul_f32 v[68:69], v[120:121], s[2:3] op_sel_hi:[1,0]
	v_pk_add_f32 v[66:67], v[66:67], v[72:73] neg_lo:[0,1] neg_hi:[0,1]
	global_store_dwordx2 v[58:59], v[68:69], off
	v_pk_mul_f32 v[68:69], v[86:87], s[2:3] op_sel_hi:[1,0]
	global_store_dwordx2 v[60:61], v[68:69], off
	v_pk_mul_f32 v[68:69], v[102:103], s[2:3] op_sel_hi:[1,0]
	v_pk_mul_f32 v[66:67], v[66:67], s[2:3] op_sel_hi:[1,0]
	global_store_dwordx2 v[62:63], v[68:69], off
	global_store_dwordx2 v[64:65], v[66:67], off
	s_barrier

.Lmy_fft_hj:
	v_mov_b32 v66, 0
	s_movk_i32 s5, 0x200
	v_add_u32_e32 v0, v66, v0
	v_cvt_f32_i32_e32 v68, v0
	v_ashrrev_i32_e32 v66, 5, v0
	v_lshlrev_b32_e32 v67, 3, v0
	v_lshlrev_b32_e32 v66, 3, v66
	v_add3_u32 v171, 0, v66, v67
	v_add_u32_e32 v216, 0x10800, v171
	v_mul_f32_e32 v0, 0x38800000, v68
	v_sin_f32_e32 v67, v0
	v_cos_f32_e32 v66, v0
	v_xor_b32_e32 v68, 0x80000000, v67
	v_mov_b32_e32 v69, v67
	v_pk_mul_f32 v[70:71], v[68:69], v[66:67] op_sel:[0,1] op_sel_hi:[1,0]
	v_pk_fma_f32 v[70:71], v[66:67], v[66:67], v[70:71] op_sel_hi:[1,0,1]
	v_pk_mul_f32 v[74:75], v[68:69], v[70:71] op_sel:[0,1] op_sel_hi:[1,0]
	v_pk_fma_f32 v[74:75], v[70:71], v[66:67], v[74:75] op_sel_hi:[1,0,1]
	v_pk_mul_f32 v[78:79], v[68:69], v[74:75] op_sel:[0,1] op_sel_hi:[1,0]
	v_pk_fma_f32 v[78:79], v[74:75], v[66:67], v[78:79] op_sel_hi:[1,0,1]
	v_pk_mul_f32 v[82:83], v[68:69], v[78:79] op_sel:[0,1] op_sel_hi:[1,0]
	v_pk_fma_f32 v[82:83], v[78:79], v[66:67], v[82:83] op_sel_hi:[1,0,1]
	v_pk_mul_f32 v[86:87], v[68:69], v[82:83] op_sel:[0,1] op_sel_hi:[1,0]
	s_waitcnt vmcnt(31)
	v_lshlrev_b32_e32 v126, 16, v105
	v_pk_fma_f32 v[86:87], v[82:83], v[66:67], v[86:87] op_sel_hi:[1,0,1]
	s_waitcnt vmcnt(30)
	v_lshlrev_b32_e32 v127, 16, v127
	v_pk_mul_f32 v[90:91], v[68:69], v[86:87] op_sel:[0,1] op_sel_hi:[1,0]
	s_waitcnt vmcnt(29)
	v_lshlrev_b32_e32 v129, 16, v128
	v_pk_fma_f32 v[90:91], v[86:87], v[66:67], v[90:91] op_sel_hi:[1,0,1]
	s_waitcnt vmcnt(24)
	v_lshlrev_b32_e32 v128, 16, v134
	v_pk_mul_f32 v[94:95], v[68:69], v[90:91] op_sel:[0,1] op_sel_hi:[1,0]
	v_lshlrev_b32_e32 v130, 16, v130
	v_pk_fma_f32 v[94:95], v[90:91], v[66:67], v[94:95] op_sel_hi:[1,0,1]
	v_lshlrev_b32_e32 v131, 16, v131
	v_pk_mul_f32 v[98:99], v[68:69], v[94:95] op_sel:[0,1] op_sel_hi:[1,0]
	v_lshlrev_b32_e32 v132, 16, v132
	v_pk_fma_f32 v[98:99], v[94:95], v[66:67], v[98:99] op_sel_hi:[1,0,1]
	v_lshlrev_b32_e32 v133, 16, v133
	v_pk_mul_f32 v[102:103], v[68:69], v[98:99] op_sel:[0,1] op_sel_hi:[1,0]
	s_waitcnt vmcnt(22)
	v_lshlrev_b32_e32 v135, 16, v135
	v_pk_fma_f32 v[102:103], v[98:99], v[66:67], v[102:103] op_sel_hi:[1,0,1]
	v_lshlrev_b32_e32 v134, 16, v136
	v_pk_mul_f32 v[108:109], v[68:69], v[102:103] op_sel:[0,1] op_sel_hi:[1,0]
	s_waitcnt vmcnt(21)
	v_lshlrev_b32_e32 v136, 16, v137
	v_pk_fma_f32 v[108:109], v[102:103], v[66:67], v[108:109] op_sel_hi:[1,0,1]
	s_waitcnt vmcnt(20)
	v_lshlrev_b32_e32 v137, 16, v138
	v_pk_mul_f32 v[112:113], v[68:69], v[108:109] op_sel:[0,1] op_sel_hi:[1,0]
	s_waitcnt vmcnt(19)
	v_lshlrev_b32_e32 v138, 16, v139
	s_waitcnt vmcnt(18)
	v_lshlrev_b32_e32 v139, 16, v140
	s_waitcnt vmcnt(17)
	v_lshlrev_b32_e32 v140, 16, v141
	s_waitcnt vmcnt(16)
	v_lshlrev_b32_e32 v141, 16, v142
	v_pk_fma_f32 v[112:113], v[108:109], v[66:67], v[112:113] op_sel_hi:[1,0,1]
	v_pk_add_f32 v[142:143], v[126:127], 0 op_sel_hi:[1,0]
	v_pk_add_f32 v[144:145], v[128:129], 0 op_sel_hi:[1,0]
	v_pk_mul_f32 v[146:147], v[128:129], s[36:37]
	v_pk_add_f32 v[148:149], v[130:131], 0 op_sel_hi:[1,0]
	v_pk_mul_f32 v[150:151], v[130:131], s[16:17]
	v_pk_add_f32 v[152:153], v[132:133], 0 op_sel_hi:[1,0]
	v_pk_mul_f32 v[154:155], v[132:133], s[38:39]
	v_pk_add_f32 v[156:157], v[134:135], 0 op_sel_hi:[1,0]
	v_xor_b32_e32 v159, 0x80000000, v134
	v_mov_b32_e32 v158, v135
	v_pk_add_f32 v[134:135], v[136:137], 0 op_sel_hi:[1,0]
	v_pk_mul_f32 v[160:161], v[136:137], s[38:39]
	v_pk_add_f32 v[162:163], v[138:139], 0 op_sel_hi:[1,0]
	v_pk_mul_f32 v[164:165], v[138:139], s[16:17]
	v_pk_add_f32 v[166:167], v[140:141], 0 op_sel_hi:[1,0]
	v_pk_mul_f32 v[168:169], v[140:141], s[36:37]
	v_pk_mul_f32 v[116:117], v[68:69], v[112:113] op_sel:[0,1] op_sel_hi:[1,0]
	v_pk_fma_f32 v[128:129], v[128:129], s[6:7], v[146:147] op_sel:[0,0,1] op_sel_hi:[1,0,0]
	v_pk_fma_f32 v[130:131], v[130:131], s[10:11], v[150:151] op_sel:[0,0,1] op_sel_hi:[1,0,0]
	v_pk_fma_f32 v[132:133], v[132:133], s[14:15], v[154:155] op_sel:[0,0,1] op_sel_hi:[1,0,0]
	v_pk_fma_f32 v[136:137], v[136:137], s[4:5], v[160:161] op_sel:[0,0,1] op_sel_hi:[1,0,0]
	v_pk_fma_f32 v[138:139], v[138:139], s[8:9], v[164:165] op_sel:[0,0,1] op_sel_hi:[1,0,0]
	v_pk_fma_f32 v[140:141], v[140:141], s[12:13], v[168:169] op_sel:[0,0,1] op_sel_hi:[1,0,0]
	v_pk_add_f32 v[146:147], v[142:143], v[156:157]
	v_pk_add_f32 v[150:151], v[144:145], v[134:135]
	v_pk_add_f32 v[134:135], v[144:145], v[134:135] neg_lo:[0,1] neg_hi:[0,1]
	v_pk_add_f32 v[144:145], v[148:149], v[162:163]
	v_pk_add_f32 v[160:161], v[148:149], v[162:163] op_sel:[1,1] op_sel_hi:[0,0] neg_lo:[0,1] neg_hi:[1,0]
	v_pk_add_f32 v[154:155], v[152:153], v[166:167]
	v_pk_add_f32 v[152:153], v[152:153], v[166:167] neg_lo:[0,1] neg_hi:[0,1]
	v_pk_fma_f32 v[116:117], v[112:113], v[66:67], v[116:117] op_sel_hi:[1,0,1]
	v_pk_add_f32 v[142:143], v[142:143], v[156:157] neg_lo:[0,1] neg_hi:[0,1]
	v_pk_add_f32 v[156:157], v[158:159], v[126:127]
	v_pk_add_f32 v[126:127], v[126:127], v[158:159] neg_lo:[0,1] neg_hi:[0,1]
	v_pk_mul_f32 v[158:159], v[134:135], s[16:17]
	v_pk_mul_f32 v[148:149], v[152:153], s[16:17]
	v_pk_add_f32 v[162:163], v[128:129], v[136:137]
	v_pk_add_f32 v[128:129], v[128:129], v[136:137] neg_lo:[0,1] neg_hi:[0,1]
	v_pk_add_f32 v[136:137], v[130:131], v[138:139]
	v_pk_add_f32 v[130:131], v[130:131], v[138:139] neg_lo:[0,1] neg_hi:[0,1]
	v_pk_add_f32 v[138:139], v[132:133], v[140:141]
	v_pk_add_f32 v[132:133], v[132:133], v[140:141] neg_lo:[0,1] neg_hi:[0,1]
	v_pk_add_f32 v[140:141], v[146:147], v[144:145]
	v_pk_add_f32 v[144:145], v[146:147], v[144:145] neg_lo:[0,1] neg_hi:[0,1]
	v_pk_add_f32 v[146:147], v[150:151], v[154:155]
	v_pk_add_f32 v[150:151], v[150:151], v[154:155] neg_lo:[0,1] neg_hi:[0,1]
	v_pk_mul_f32 v[120:121], v[68:69], v[116:117] op_sel:[0,1] op_sel_hi:[1,0]
	v_pk_fma_f32 v[134:135], v[134:135], s[10:11], v[158:159] op_sel:[0,0,1] op_sel_hi:[1,0,0]
	v_pk_fma_f32 v[148:149], v[152:153], s[8:9], v[148:149] op_sel:[0,0,1] op_sel_hi:[1,0,0]
	v_pk_mul_f32 v[152:153], v[128:129], s[16:17]
	v_xor_b32_e32 v155, 0x80000000, v130
	v_mov_b32_e32 v154, v131
	v_pk_mul_f32 v[130:131], v[132:133], s[16:17]
	v_xor_b32_e32 v159, 0x80000000, v150
	v_mov_b32_e32 v158, v151
	v_pk_add_f32 v[150:151], v[142:143], v[160:161]
	v_pk_add_f32 v[142:143], v[142:143], v[160:161] neg_lo:[0,1] neg_hi:[0,1]
	v_pk_add_f32 v[160:161], v[156:157], v[136:137]
	v_pk_add_f32 v[136:137], v[156:157], v[136:137] neg_lo:[0,1] neg_hi:[0,1]
	v_pk_add_f32 v[156:157], v[162:163], v[138:139]
	v_pk_add_f32 v[138:139], v[162:163], v[138:139] neg_lo:[0,1] neg_hi:[0,1]
	v_mov_b32_e32 v0, v67
	v_pk_fma_f32 v[120:121], v[116:117], v[66:67], v[120:121] op_sel_hi:[1,0,1]
	v_pk_add_f32 v[162:163], v[140:141], v[146:147]
	v_pk_add_f32 v[140:141], v[140:141], v[146:147] neg_lo:[0,1] neg_hi:[0,1]
	v_pk_fma_f32 v[128:129], v[128:129], s[10:11], v[152:153] op_sel:[0,0,1] op_sel_hi:[1,0,0]
	v_pk_fma_f32 v[130:131], v[132:133], s[8:9], v[130:131] op_sel:[0,0,1] op_sel_hi:[1,0,0]
	v_pk_add_f32 v[132:133], v[134:135], v[148:149]
	v_pk_add_f32 v[134:135], v[134:135], v[148:149] neg_lo:[0,1] neg_hi:[0,1]
	v_xor_b32_e32 v147, 0x80000000, v138
	v_mov_b32_e32 v146, v139
	v_pk_add_f32 v[152:153], v[160:161], v[156:157]
	v_pk_mul_f32 v[68:69], v[68:69], v[120:121] op_sel:[0,1] op_sel_hi:[1,0]
	v_pk_add_f32 v[138:139], v[126:127], v[154:155]
	v_pk_add_f32 v[126:127], v[126:127], v[154:155] neg_lo:[0,1] neg_hi:[0,1]
	v_pk_add_f32 v[148:149], v[144:145], v[158:159]
	v_pk_add_f32 v[144:145], v[144:145], v[158:159] neg_lo:[0,1] neg_hi:[0,1]
	v_pk_add_f32 v[154:155], v[160:161], v[156:157] neg_lo:[0,1] neg_hi:[0,1]
	v_pk_mul_f32 v[96:97], v[140:141], v[94:95] op_sel:[1,1] op_sel_hi:[0,1] neg_hi:[0,1]
	v_xor_b32_e32 v157, 0x80000000, v134
	v_mov_b32_e32 v156, v135
	v_pk_add_f32 v[134:135], v[128:129], v[130:131]
	v_pk_add_f32 v[128:129], v[128:129], v[130:131] neg_lo:[0,1] neg_hi:[0,1]
	v_pk_add_f32 v[130:131], v[150:151], v[132:133]
	v_pk_add_f32 v[132:133], v[150:151], v[132:133] neg_lo:[0,1] neg_hi:[0,1]
	v_pk_add_f32 v[150:151], v[136:137], v[146:147]
	v_pk_add_f32 v[136:137], v[136:137], v[146:147] neg_lo:[0,1] neg_hi:[0,1]
	v_pk_mul_f32 v[146:147], v[0:1], v[152:153] op_sel:[0,1] op_sel_hi:[0,0] neg_hi:[1,0]
	v_pk_add_f32 v[92:93], v[90:91], 0 neg_lo:[1,1] neg_hi:[1,1]
	v_pk_fma_f32 v[68:69], v[120:121], v[66:67], v[68:69] op_sel_hi:[1,0,1]
	v_pk_mul_f32 v[80:81], v[148:149], v[78:79] op_sel:[1,1] op_sel_hi:[0,1] neg_hi:[0,1]
	v_pk_fma_f32 v[94:95], v[140:141], v[94:95], v[96:97] op_sel_hi:[1,0,1]
	v_pk_mul_f32 v[96:97], v[154:155], v[98:99] op_sel:[1,1] op_sel_hi:[0,1] neg_hi:[0,1]
	v_pk_mul_f32 v[100:101], v[144:145], v[112:113] op_sel:[1,1] op_sel_hi:[0,1] neg_hi:[0,1]
	v_xor_b32_e32 v115, 0x80000000, v128
	v_mov_b32_e32 v114, v129
	v_pk_add_f32 v[128:129], v[142:143], v[156:157]
	v_pk_add_f32 v[140:141], v[142:143], v[156:157] neg_lo:[0,1] neg_hi:[0,1]
	v_pk_add_f32 v[142:143], v[138:139], v[134:135]
	v_pk_fma_f32 v[66:67], v[152:153], v[66:67], v[146:147] op_sel_hi:[1,0,1]
	v_pk_mul_f32 v[72:73], v[130:131], v[70:71] op_sel:[1,1] op_sel_hi:[0,1] neg_hi:[0,1]
	v_mov_b32_e32 v92, v91
	v_pk_add_f32 v[110:111], v[108:109], 0 neg_lo:[1,1] neg_hi:[1,1]
	v_pk_add_f32 v[118:119], v[116:117], 0 neg_lo:[1,1] neg_hi:[1,1]
	v_pk_add_f32 v[122:123], v[120:121], 0 neg_lo:[1,1] neg_hi:[1,1]
	v_pk_add_f32 v[124:125], v[68:69], 0 neg_lo:[1,1] neg_hi:[1,1]
	ds_write_b64 v171, v[162:163]
	v_pk_fma_f32 v[78:79], v[148:149], v[78:79], v[80:81] op_sel_hi:[1,0,1]
	v_pk_mul_f32 v[80:81], v[150:151], v[82:83] op_sel:[1,1] op_sel_hi:[0,1] neg_hi:[0,1]
	v_pk_fma_f32 v[84:85], v[154:155], v[98:99], v[96:97] op_sel_hi:[1,0,1]
	v_pk_mul_f32 v[96:97], v[132:133], v[102:103] op_sel:[1,1] op_sel_hi:[0,1] neg_hi:[0,1]
	v_pk_add_f32 v[106:107], v[126:127], v[114:115]
	ds_write_b64 v171, v[66:67] offset:8448
	v_pk_fma_f32 v[66:67], v[130:131], v[70:71], v[72:73] op_sel_hi:[1,0,1]
	v_pk_mul_f32 v[70:71], v[142:143], v[74:75] op_sel:[1,1] op_sel_hi:[0,1] neg_hi:[0,1]
	v_mov_b32_e32 v110, v109
	v_mov_b32_e32 v118, v117
	v_mov_b32_e32 v122, v121
	v_mov_b32_e32 v124, v69
	v_pk_add_f32 v[134:135], v[138:139], v[134:135] neg_lo:[0,1] neg_hi:[0,1]
	v_pk_fma_f32 v[98:99], v[144:145], v[112:113], v[100:101] op_sel_hi:[1,0,1]
	v_pk_add_f32 v[112:113], v[126:127], v[114:115] neg_lo:[0,1] neg_hi:[0,1]
	v_pk_mul_f32 v[76:77], v[128:129], v[86:87] op_sel:[1,1] op_sel_hi:[0,1] neg_hi:[0,1]
	ds_write_b64 v171, v[66:67] offset:16896
	v_pk_fma_f32 v[66:67], v[142:143], v[74:75], v[70:71] op_sel_hi:[1,0,1]
	v_pk_mul_f32 v[74:75], v[106:107], v[92:93] op_sel:[1,0] op_sel_hi:[0,1]
	s_mov_b64 s[48:49], 0
	s_and_b64 vcc, exec, vcc
	v_pk_mul_f32 v[100:101], v[136:137], v[118:119] op_sel:[1,0] op_sel_hi:[0,1]
	v_pk_fma_f32 v[72:73], v[150:151], v[82:83], v[80:81] op_sel_hi:[1,0,1]
	v_pk_fma_f32 v[80:81], v[132:133], v[102:103], v[96:97] op_sel_hi:[1,0,1]
	v_pk_mul_f32 v[82:83], v[134:135], v[110:111] op_sel:[1,0] op_sel_hi:[0,1]
	v_pk_mul_f32 v[96:97], v[140:141], v[122:123] op_sel:[1,0] op_sel_hi:[0,1]
	v_pk_fma_f32 v[70:71], v[128:129], v[86:87], v[76:77] op_sel_hi:[1,0,1]
	v_pk_mul_f32 v[86:87], v[112:113], v[124:125] op_sel:[1,0] op_sel_hi:[0,1]
	ds_write_b64 v171, v[66:67] offset:25344
	ds_write_b64 v171, v[78:79] offset:33792
	ds_write_b64 v171, v[72:73] offset:42240
	ds_write_b64 v171, v[70:71] offset:50688
	v_pk_fma_f32 v[66:67], v[106:107], v[90:91], v[74:75] op_sel_hi:[1,0,1]
	v_pk_fma_f32 v[88:89], v[136:137], v[116:117], v[100:101] op_sel_hi:[1,0,1]
	v_pk_fma_f32 v[76:77], v[134:135], v[108:109], v[82:83] op_sel_hi:[1,0,1]
	v_pk_fma_f32 v[82:83], v[140:141], v[120:121], v[96:97] op_sel_hi:[1,0,1]
	v_pk_fma_f32 v[68:69], v[112:113], v[68:69], v[86:87] op_sel_hi:[1,0,1]
	ds_write_b64 v171, v[66:67] offset:59136
	ds_write_b64 v216, v[94:95]
	ds_write_b64 v216, v[84:85] offset:8448
	ds_write_b64 v216, v[80:81] offset:16896
	ds_write_b64 v216, v[76:77] offset:25344
	ds_write_b64 v216, v[98:99] offset:33792
	ds_write_b64 v216, v[88:89] offset:42240
	ds_write_b64 v216, v[82:83] offset:50688
	ds_write_b64 v216, v[68:69] offset:59136
	s_cbranch_vccz .LBB0_362
	s_waitcnt lgkmcnt(0)
	s_barrier
	v_mov_b32 v0, 0
	s_mov_b32 s5, s14
	v_add_u32_e32 v74, v0, v170
	v_lshlrev_b32_e32 v0, 5, v74
	v_and_b32_e32 v71, 0xfffffc00, v0
	v_and_b32_e32 v70, 31, v74
	v_lshlrev_b32_e32 v78, 3, v71
	v_lshlrev_b32_e32 v79, 3, v70
	v_or_b32_e32 v67, 32, v71
	v_ashrrev_i32_e32 v67, 2, v67
	v_add_u32_e32 v67, 0, v67
	v_add3_u32 v114, v67, v78, v79
	v_ashrrev_i32_e32 v66, 2, v71
	v_add_u32_e32 v66, 0, v66
	v_add3_u32 v66, v66, v78, v79
	v_mov_b32_e32 v222, v114
	ds_read_b64 v[66:67], v66
	ds_read_b64 v[68:69], v222 offset:256
	ds_read_b64 v[72:73], v222 offset:520
	ds_read_b64 v[76:77], v222 offset:784
	ds_read_b64 v[80:81], v222 offset:1048
	ds_read_b64 v[82:83], v222 offset:1312
	ds_read_b64 v[116:117], v222 offset:1576
	ds_read_b64 v[118:119], v222 offset:1840
	ds_read_b64 v[120:121], v222 offset:2104
	ds_read_b64 v[122:123], v222 offset:2368
	ds_read_b64 v[124:125], v222 offset:2632
	ds_read_b64 v[126:127], v222 offset:2896
	ds_read_b64 v[128:129], v222 offset:3160
	ds_read_b64 v[130:131], v222 offset:3424
	ds_read_b64 v[132:133], v222 offset:3688
	ds_read_b64 v[134:135], v222 offset:3952
	ds_read_b64 v[136:137], v222 offset:4216
	ds_read_b64 v[138:139], v222 offset:4480
	ds_read_b64 v[140:141], v222 offset:4744
	ds_read_b64 v[142:143], v222 offset:5008
	s_waitcnt lgkmcnt(3)
	v_pk_add_f32 v[168:169], v[66:67], v[136:137]
	v_pk_add_f32 v[66:67], v[66:67], v[136:137] neg_lo:[0,1] neg_hi:[0,1]
	s_waitcnt lgkmcnt(2)
	v_pk_add_f32 v[136:137], v[68:69], v[138:139]
	v_pk_add_f32 v[68:69], v[68:69], v[138:139] neg_lo:[0,1] neg_hi:[0,1]
	v_pk_mul_f32 v[138:139], v[68:69], s[18:19]
	v_pk_fma_f32 v[68:69], v[68:69], s[20:21], v[138:139] op_sel:[0,0,1] op_sel_hi:[1,0,0]
	s_waitcnt lgkmcnt(1)
	v_pk_add_f32 v[138:139], v[72:73], v[140:141]
	v_pk_add_f32 v[72:73], v[72:73], v[140:141] neg_lo:[0,1] neg_hi:[0,1]
	v_pk_mul_f32 v[140:141], v[72:73], s[4:5]
	ds_read_b64 v[144:145], v222 offset:5272
	ds_read_b64 v[146:147], v222 offset:5536
	ds_read_b64 v[148:149], v222 offset:5800
	ds_read_b64 v[150:151], v222 offset:6064
	v_pk_fma_f32 v[72:73], v[72:73], s[6:7], v[140:141] op_sel:[0,0,1] op_sel_hi:[1,0,0]
	s_waitcnt lgkmcnt(4)
	v_pk_add_f32 v[140:141], v[76:77], v[142:143]
	v_pk_add_f32 v[76:77], v[76:77], v[142:143] neg_lo:[0,1] neg_hi:[0,1]
	v_pk_mul_f32 v[142:143], v[76:77], s[22:23]
	v_pk_fma_f32 v[76:77], v[76:77], s[24:25], v[142:143] op_sel:[0,0,1] op_sel_hi:[1,0,0]
	s_waitcnt lgkmcnt(3)
	v_pk_add_f32 v[142:143], v[80:81], v[144:145]
	v_pk_add_f32 v[80:81], v[80:81], v[144:145] neg_lo:[0,1] neg_hi:[0,1]
	s_mov_b32 s9, s10
	v_pk_mul_f32 v[144:145], v[80:81], s[8:9]
	v_pk_fma_f32 v[80:81], v[80:81], s[10:11], v[144:145] op_sel:[0,0,1] op_sel_hi:[1,0,0]
	s_waitcnt lgkmcnt(2)
	v_pk_add_f32 v[144:145], v[82:83], v[146:147]
	v_pk_add_f32 v[82:83], v[82:83], v[146:147] neg_lo:[0,1] neg_hi:[0,1]
	s_mov_b32 s27, s24
	v_pk_mul_f32 v[146:147], v[82:83], s[26:27]
	s_mov_b32 s0, s23
	v_pk_fma_f32 v[82:83], v[82:83], s[0:1], v[146:147] op_sel:[0,0,1] op_sel_hi:[1,0,0]
	s_waitcnt lgkmcnt(1)
	v_pk_add_f32 v[146:147], v[116:117], v[148:149]
	v_pk_add_f32 v[116:117], v[116:117], v[148:149] neg_lo:[0,1] neg_hi:[0,1]
	s_mov_b32 s13, s6
	v_pk_mul_f32 v[148:149], v[116:117], s[12:13]
	ds_read_b64 v[152:153], v222 offset:6328
	ds_read_b64 v[154:155], v222 offset:6592
	ds_read_b64 v[156:157], v222 offset:6856
	ds_read_b64 v[158:159], v222 offset:7120
	v_pk_fma_f32 v[116:117], v[116:117], s[14:15], v[148:149] op_sel:[0,0,1] op_sel_hi:[1,0,0]
	s_waitcnt lgkmcnt(4)
	v_pk_add_f32 v[148:149], v[118:119], v[150:151]
	v_pk_add_f32 v[118:119], v[118:119], v[150:151] neg_lo:[0,1] neg_hi:[0,1]
	s_mov_b32 s35, s20
	v_pk_mul_f32 v[150:151], v[118:119], s[34:35]
	s_mov_b32 s48, s19
	v_pk_fma_f32 v[118:119], v[118:119], s[48:49], v[150:151] op_sel:[0,0,1] op_sel_hi:[1,0,0]
	s_waitcnt lgkmcnt(3)
	v_pk_add_f32 v[150:151], v[120:121], v[152:153]
	v_pk_add_f32 v[152:153], v[120:121], v[152:153] op_sel:[1,1] op_sel_hi:[0,0] neg_lo:[0,1] neg_hi:[1,0]
	s_waitcnt lgkmcnt(2)
	v_pk_add_f32 v[120:121], v[122:123], v[154:155]
	v_pk_add_f32 v[122:123], v[122:123], v[154:155] neg_lo:[0,1] neg_hi:[0,1]
	v_pk_mul_f32 v[154:155], v[122:123], s[34:35]
	v_pk_fma_f32 v[122:123], v[122:123], s[18:19], v[154:155] op_sel:[0,0,1] op_sel_hi:[1,0,0]
	s_waitcnt lgkmcnt(1)
	v_pk_add_f32 v[154:155], v[124:125], v[156:157]
	v_pk_add_f32 v[124:125], v[124:125], v[156:157] neg_lo:[0,1] neg_hi:[0,1]
	v_pk_mul_f32 v[156:157], v[124:125], s[12:13]
	ds_read_b64 v[160:161], v222 offset:7384
	ds_read_b64 v[162:163], v222 offset:7648
	ds_read_b64 v[164:165], v222 offset:7912
	ds_read_b64 v[166:167], v222 offset:8176
	v_pk_fma_f32 v[124:125], v[124:125], s[4:5], v[156:157] op_sel:[0,0,1] op_sel_hi:[1,0,0]
	s_waitcnt lgkmcnt(4)
	v_pk_add_f32 v[156:157], v[126:127], v[158:159]
	v_pk_add_f32 v[126:127], v[126:127], v[158:159] neg_lo:[0,1] neg_hi:[0,1]
	v_lshlrev_b32_e32 v70, 4, v70
	v_pk_mul_f32 v[158:159], v[126:127], s[26:27]
	v_cvt_f32_u32_e32 v75, v70
	v_pk_fma_f32 v[126:127], v[126:127], s[22:23], v[158:159] op_sel:[0,0,1] op_sel_hi:[1,0,0]
	s_waitcnt lgkmcnt(3)
	v_pk_add_f32 v[158:159], v[128:129], v[160:161]
	v_pk_add_f32 v[128:129], v[128:129], v[160:161] neg_lo:[0,1] neg_hi:[0,1]
	v_and_b32_e32 v74, 0x1fffffe0, v74
	v_pk_mul_f32 v[160:161], v[128:129], s[8:9]
	v_mul_f32_e32 v115, 0x38800000, v75
	v_pk_fma_f32 v[128:129], v[128:129], s[8:9], v[160:161] op_sel:[0,0,1] op_sel_hi:[1,0,0]
	s_waitcnt lgkmcnt(2)
	v_pk_add_f32 v[160:161], v[130:131], v[162:163]
	v_pk_add_f32 v[130:131], v[130:131], v[162:163] neg_lo:[0,1] neg_hi:[0,1]
	v_lshl_add_u32 v74, v74, 3, 0
	v_pk_mul_f32 v[162:163], v[130:131], s[22:23]
	v_sin_f32_e32 v75, v115
	v_pk_fma_f32 v[130:131], v[130:131], s[26:27], v[162:163] op_sel:[0,0,1] op_sel_hi:[1,0,0]
	s_waitcnt lgkmcnt(1)
	v_pk_add_f32 v[162:163], v[132:133], v[164:165]
	v_pk_add_f32 v[132:133], v[132:133], v[164:165] neg_lo:[0,1] neg_hi:[0,1]
	v_add3_u32 v74, v74, v78, v79
	v_pk_mul_f32 v[164:165], v[132:133], s[4:5]
	v_xor_b32_e32 v78, 0x80000000, v75
	v_pk_fma_f32 v[132:133], v[132:133], s[12:13], v[164:165] op_sel:[0,0,1] op_sel_hi:[1,0,0]
	s_waitcnt lgkmcnt(0)
	v_pk_add_f32 v[164:165], v[134:135], v[166:167]
	v_pk_add_f32 v[134:135], v[134:135], v[166:167] neg_lo:[0,1] neg_hi:[0,1]
	v_mov_b32_e32 v79, v75
	v_pk_mul_f32 v[166:167], v[134:135], s[18:19]
	s_mov_b32 s50, s19
	v_pk_fma_f32 v[134:135], v[134:135], s[34:35], v[166:167] op_sel:[0,0,1] op_sel_hi:[1,0,0]
	v_pk_add_f32 v[166:167], v[168:169], v[150:151]
	v_pk_add_f32 v[150:151], v[168:169], v[150:151] neg_lo:[0,1] neg_hi:[0,1]
	v_pk_add_f32 v[168:169], v[136:137], v[120:121]
	v_pk_add_f32 v[120:121], v[136:137], v[120:121] neg_lo:[0,1] neg_hi:[0,1]
	s_mov_b32 s51, s18
	v_pk_mul_f32 v[136:137], v[120:121], s[4:5]
	s_mov_b32 s52, s23
	v_pk_fma_f32 v[120:121], v[120:121], s[6:7], v[136:137] op_sel:[0,0,1] op_sel_hi:[1,0,0]
	v_pk_add_f32 v[136:137], v[138:139], v[154:155]
	v_pk_add_f32 v[138:139], v[138:139], v[154:155] neg_lo:[0,1] neg_hi:[0,1]
	s_mov_b32 s53, s22
	v_pk_mul_f32 v[154:155], v[138:139], s[8:9]
	s_nop 0
	v_pk_fma_f32 v[138:139], v[138:139], s[10:11], v[154:155] op_sel:[0,0,1] op_sel_hi:[1,0,0]
	v_pk_add_f32 v[154:155], v[140:141], v[156:157]
	v_pk_add_f32 v[140:141], v[140:141], v[156:157] neg_lo:[0,1] neg_hi:[0,1]
	s_nop 0
	v_pk_mul_f32 v[156:157], v[140:141], s[12:13]
	s_nop 0
	v_pk_fma_f32 v[140:141], v[140:141], s[14:15], v[156:157] op_sel:[0,0,1] op_sel_hi:[1,0,0]
	v_pk_add_f32 v[156:157], v[142:143], v[158:159]
	v_pk_add_f32 v[158:159], v[142:143], v[158:159] op_sel:[1,1] op_sel_hi:[0,0] neg_lo:[0,1] neg_hi:[1,0]
	s_nop 0
	v_pk_add_f32 v[142:143], v[144:145], v[160:161]
	v_pk_add_f32 v[144:145], v[144:145], v[160:161] neg_lo:[0,1] neg_hi:[0,1]
	s_nop 0
	v_pk_mul_f32 v[160:161], v[144:145], s[12:13]
	s_nop 0
	v_pk_fma_f32 v[144:145], v[144:145], s[4:5], v[160:161] op_sel:[0,0,1] op_sel_hi:[1,0,0]
	v_pk_add_f32 v[160:161], v[146:147], v[162:163]
	v_pk_add_f32 v[146:147], v[146:147], v[162:163] neg_lo:[0,1] neg_hi:[0,1]
	s_nop 0
	v_pk_mul_f32 v[162:163], v[146:147], s[8:9]
	s_nop 0
	v_pk_fma_f32 v[146:147], v[146:147], s[8:9], v[162:163] op_sel:[0,0,1] op_sel_hi:[1,0,0]
	v_pk_add_f32 v[162:163], v[148:149], v[164:165]
	v_pk_add_f32 v[148:149], v[148:149], v[164:165] neg_lo:[0,1] neg_hi:[0,1]
	s_nop 0
	v_pk_mul_f32 v[164:165], v[148:149], s[4:5]
	s_nop 0
	v_pk_fma_f32 v[148:149], v[148:149], s[12:13], v[164:165] op_sel:[0,0,1] op_sel_hi:[1,0,0]
	v_pk_add_f32 v[164:165], v[66:67], v[152:153]
	v_pk_add_f32 v[66:67], v[66:67], v[152:153] neg_lo:[0,1] neg_hi:[0,1]
	v_pk_add_f32 v[152:153], v[68:69], v[122:123]
	v_pk_add_f32 v[68:69], v[68:69], v[122:123] neg_lo:[0,1] neg_hi:[0,1]
	s_nop 0
	v_pk_mul_f32 v[122:123], v[68:69], s[4:5]
	s_nop 0
	v_pk_fma_f32 v[68:69], v[68:69], s[6:7], v[122:123] op_sel:[0,0,1] op_sel_hi:[1,0,0]
	v_pk_add_f32 v[122:123], v[72:73], v[124:125]
	v_pk_add_f32 v[72:73], v[72:73], v[124:125] neg_lo:[0,1] neg_hi:[0,1]
	s_nop 0
	v_pk_mul_f32 v[124:125], v[72:73], s[8:9]
	s_nop 0
	v_pk_fma_f32 v[72:73], v[72:73], s[10:11], v[124:125] op_sel:[0,0,1] op_sel_hi:[1,0,0]
	v_pk_add_f32 v[124:125], v[76:77], v[126:127]
	v_pk_add_f32 v[76:77], v[76:77], v[126:127] neg_lo:[0,1] neg_hi:[0,1]
	s_nop 0
	v_pk_mul_f32 v[126:127], v[76:77], s[12:13]
	s_nop 0
	v_pk_fma_f32 v[76:77], v[76:77], s[14:15], v[126:127] op_sel:[0,0,1] op_sel_hi:[1,0,0]
	v_pk_add_f32 v[126:127], v[80:81], v[128:129]
	v_pk_add_f32 v[128:129], v[80:81], v[128:129] op_sel:[1,1] op_sel_hi:[0,0] neg_lo:[0,1] neg_hi:[1,0]
	s_nop 0
	v_pk_add_f32 v[80:81], v[82:83], v[130:131]
	v_pk_add_f32 v[82:83], v[82:83], v[130:131] neg_lo:[0,1] neg_hi:[0,1]
	s_nop 0
	v_pk_mul_f32 v[130:131], v[82:83], s[12:13]
	s_nop 0
	v_pk_fma_f32 v[82:83], v[82:83], s[4:5], v[130:131] op_sel:[0,0,1] op_sel_hi:[1,0,0]
	v_pk_add_f32 v[130:131], v[116:117], v[132:133]
	v_pk_add_f32 v[116:117], v[116:117], v[132:133] neg_lo:[0,1] neg_hi:[0,1]
	s_nop 0
	v_pk_mul_f32 v[132:133], v[116:117], s[8:9]
	s_nop 0
	v_pk_fma_f32 v[116:117], v[116:117], s[8:9], v[132:133] op_sel:[0,0,1] op_sel_hi:[1,0,0]
	v_pk_add_f32 v[132:133], v[118:119], v[134:135]
	v_pk_add_f32 v[118:119], v[118:119], v[134:135] neg_lo:[0,1] neg_hi:[0,1]
	s_nop 0
	v_pk_mul_f32 v[134:135], v[118:119], s[4:5]
	s_nop 0
	v_pk_fma_f32 v[118:119], v[118:119], s[12:13], v[134:135] op_sel:[0,0,1] op_sel_hi:[1,0,0]
	v_pk_add_f32 v[134:135], v[166:167], v[156:157]
	v_pk_add_f32 v[156:157], v[166:167], v[156:157] neg_lo:[0,1] neg_hi:[0,1]
	v_pk_add_f32 v[166:167], v[168:169], v[142:143]
	v_pk_add_f32 v[142:143], v[168:169], v[142:143] neg_lo:[0,1] neg_hi:[0,1]
	s_nop 0
	v_pk_mul_f32 v[168:169], v[142:143], s[8:9]
	s_nop 0
	v_pk_fma_f32 v[142:143], v[142:143], s[10:11], v[168:169] op_sel:[0,0,1] op_sel_hi:[1,0,0]
	v_pk_add_f32 v[168:169], v[136:137], v[160:161]
	v_pk_add_f32 v[160:161], v[136:137], v[160:161] op_sel:[1,1] op_sel_hi:[0,0] neg_lo:[0,1] neg_hi:[1,0]
	s_nop 0
	v_pk_add_f32 v[136:137], v[154:155], v[162:163]
	v_pk_add_f32 v[154:155], v[154:155], v[162:163] neg_lo:[0,1] neg_hi:[0,1]
	s_nop 0
	v_pk_mul_f32 v[162:163], v[154:155], s[8:9]
	s_nop 0
	v_pk_fma_f32 v[154:155], v[154:155], s[8:9], v[162:163] op_sel:[0,0,1] op_sel_hi:[1,0,0]
	v_pk_add_f32 v[162:163], v[150:151], v[158:159]
	v_pk_add_f32 v[150:151], v[150:151], v[158:159] neg_lo:[0,1] neg_hi:[0,1]
	v_pk_add_f32 v[158:159], v[120:121], v[144:145]
	v_pk_add_f32 v[120:121], v[120:121], v[144:145] neg_lo:[0,1] neg_hi:[0,1]
	s_nop 0
	v_pk_mul_f32 v[144:145], v[120:121], s[8:9]
	s_nop 0
	v_pk_fma_f32 v[120:121], v[120:121], s[10:11], v[144:145] op_sel:[0,0,1] op_sel_hi:[1,0,0]
	v_pk_add_f32 v[144:145], v[138:139], v[146:147]
	v_pk_add_f32 v[146:147], v[138:139], v[146:147] op_sel:[1,1] op_sel_hi:[0,0] neg_lo:[0,1] neg_hi:[1,0]
	s_nop 0
	v_pk_add_f32 v[138:139], v[140:141], v[148:149]
	v_pk_add_f32 v[140:141], v[140:141], v[148:149] neg_lo:[0,1] neg_hi:[0,1]
	s_nop 0
	v_pk_mul_f32 v[148:149], v[140:141], s[8:9]
	s_nop 0
	v_pk_fma_f32 v[140:141], v[140:141], s[8:9], v[148:149] op_sel:[0,0,1] op_sel_hi:[1,0,0]
	v_pk_add_f32 v[148:149], v[164:165], v[126:127]
	v_pk_add_f32 v[126:127], v[164:165], v[126:127] neg_lo:[0,1] neg_hi:[0,1]
	v_pk_add_f32 v[164:165], v[152:153], v[80:81]
	v_pk_add_f32 v[80:81], v[152:153], v[80:81] neg_lo:[0,1] neg_hi:[0,1]
	s_nop 0
	v_pk_mul_f32 v[152:153], v[80:81], s[8:9]
	s_nop 0
	v_pk_fma_f32 v[80:81], v[80:81], s[10:11], v[152:153] op_sel:[0,0,1] op_sel_hi:[1,0,0]
	v_pk_add_f32 v[152:153], v[122:123], v[130:131]
	v_pk_add_f32 v[130:131], v[122:123], v[130:131] op_sel:[1,1] op_sel_hi:[0,0] neg_lo:[0,1] neg_hi:[1,0]
	s_nop 0
	v_pk_add_f32 v[122:123], v[124:125], v[132:133]
	v_pk_add_f32 v[124:125], v[124:125], v[132:133] neg_lo:[0,1] neg_hi:[0,1]
	s_nop 0
	v_pk_mul_f32 v[132:133], v[124:125], s[8:9]
	s_nop 0
	v_pk_fma_f32 v[124:125], v[124:125], s[8:9], v[132:133] op_sel:[0,0,1] op_sel_hi:[1,0,0]
	v_pk_add_f32 v[132:133], v[66:67], v[128:129]
	v_pk_add_f32 v[66:67], v[66:67], v[128:129] neg_lo:[0,1] neg_hi:[0,1]
	v_pk_add_f32 v[128:129], v[68:69], v[82:83]
	v_pk_add_f32 v[68:69], v[68:69], v[82:83] neg_lo:[0,1] neg_hi:[0,1]
	s_nop 0
	v_pk_mul_f32 v[82:83], v[68:69], s[8:9]
	s_nop 0
	v_pk_fma_f32 v[68:69], v[68:69], s[10:11], v[82:83] op_sel:[0,0,1] op_sel_hi:[1,0,0]
	v_pk_add_f32 v[82:83], v[72:73], v[116:117]
	v_pk_add_f32 v[116:117], v[72:73], v[116:117] op_sel:[1,1] op_sel_hi:[0,0] neg_lo:[0,1] neg_hi:[1,0]
	s_nop 0
	v_pk_add_f32 v[72:73], v[76:77], v[118:119]
	v_pk_add_f32 v[76:77], v[76:77], v[118:119] neg_lo:[0,1] neg_hi:[0,1]
	v_pk_add_f32 v[174:175], v[66:67], v[116:117]
	v_pk_mul_f32 v[118:119], v[76:77], s[8:9]
	v_pk_add_f32 v[116:117], v[66:67], v[116:117] neg_lo:[0,1] neg_hi:[0,1]
	v_pk_fma_f32 v[76:77], v[76:77], s[8:9], v[118:119] op_sel:[0,0,1] op_sel_hi:[1,0,0]
	v_pk_add_f32 v[118:119], v[134:135], v[168:169]
	v_pk_add_f32 v[134:135], v[134:135], v[168:169] neg_lo:[0,1] neg_hi:[0,1]
	v_pk_add_f32 v[168:169], v[166:167], v[136:137]
	v_pk_add_f32 v[166:167], v[166:167], v[136:137] op_sel:[1,1] op_sel_hi:[0,0] neg_lo:[0,1] neg_hi:[1,0]
	v_pk_add_f32 v[180:181], v[118:119], v[168:169]
	v_pk_add_f32 v[136:137], v[156:157], v[160:161]
	v_pk_add_f32 v[156:157], v[156:157], v[160:161] neg_lo:[0,1] neg_hi:[0,1]
	v_pk_add_f32 v[160:161], v[142:143], v[154:155]
	v_pk_add_f32 v[154:155], v[142:143], v[154:155] op_sel:[1,1] op_sel_hi:[0,0] neg_lo:[0,1] neg_hi:[1,0]
	v_pk_add_f32 v[178:179], v[68:69], v[76:77] op_sel:[1,1] op_sel_hi:[0,0] neg_lo:[0,1] neg_hi:[1,0]
	v_pk_add_f32 v[142:143], v[162:163], v[144:145]
	v_pk_add_f32 v[144:145], v[162:163], v[144:145] neg_lo:[0,1] neg_hi:[0,1]
	v_pk_add_f32 v[162:163], v[158:159], v[138:139]
	v_pk_add_f32 v[158:159], v[158:159], v[138:139] op_sel:[1,1] op_sel_hi:[0,0] neg_lo:[0,1] neg_hi:[1,0]
	ds_write_b64 v74, v[180:181]
	v_pk_add_f32 v[138:139], v[150:151], v[146:147]
	v_pk_add_f32 v[146:147], v[150:151], v[146:147] neg_lo:[0,1] neg_hi:[0,1]
	v_pk_add_f32 v[150:151], v[120:121], v[140:141]
	v_pk_add_f32 v[140:141], v[120:121], v[140:141] op_sel:[1,1] op_sel_hi:[0,0] neg_lo:[0,1] neg_hi:[1,0]
	v_cos_f32_e32 v74, v115
	v_pk_add_f32 v[120:121], v[148:149], v[152:153]
	v_pk_add_f32 v[148:149], v[148:149], v[152:153] neg_lo:[0,1] neg_hi:[0,1]
	v_pk_add_f32 v[152:153], v[164:165], v[122:123]
	v_pk_add_f32 v[164:165], v[164:165], v[122:123] op_sel:[1,1] op_sel_hi:[0,0] neg_lo:[0,1] neg_hi:[1,0]
	v_pk_add_f32 v[122:123], v[126:127], v[130:131]
	v_pk_add_f32 v[126:127], v[126:127], v[130:131] neg_lo:[0,1] neg_hi:[0,1]
	v_pk_add_f32 v[130:131], v[80:81], v[124:125]
	v_pk_add_f32 v[124:125], v[80:81], v[124:125] op_sel:[1,1] op_sel_hi:[0,0] neg_lo:[0,1] neg_hi:[1,0]
	v_pk_add_f32 v[80:81], v[132:133], v[82:83]
	v_pk_add_f32 v[132:133], v[132:133], v[82:83] neg_lo:[0,1] neg_hi:[0,1]
	v_pk_add_f32 v[176:177], v[68:69], v[76:77]
	v_pk_add_f32 v[118:119], v[118:119], v[168:169] neg_lo:[0,1] neg_hi:[0,1]
	v_pk_add_f32 v[168:169], v[134:135], v[166:167]
	v_pk_add_f32 v[82:83], v[134:135], v[166:167] neg_lo:[0,1] neg_hi:[0,1]
	v_pk_add_f32 v[134:135], v[136:137], v[160:161]
	v_pk_add_f32 v[136:137], v[136:137], v[160:161] neg_lo:[0,1] neg_hi:[0,1]
	v_pk_add_f32 v[160:161], v[156:157], v[154:155]
	v_pk_add_f32 v[68:69], v[156:157], v[154:155] neg_lo:[0,1] neg_hi:[0,1]
	v_pk_add_f32 v[154:155], v[142:143], v[162:163]
	v_pk_add_f32 v[142:143], v[142:143], v[162:163] neg_lo:[0,1] neg_hi:[0,1]
	v_pk_add_f32 v[156:157], v[144:145], v[158:159]
	v_pk_add_f32 v[76:77], v[144:145], v[158:159] neg_lo:[0,1] neg_hi:[0,1]
	v_pk_add_f32 v[144:145], v[138:139], v[150:151]
	v_pk_add_f32 v[138:139], v[138:139], v[150:151] neg_lo:[0,1] neg_hi:[0,1]
	v_pk_add_f32 v[150:151], v[146:147], v[140:141]
	v_pk_add_f32 v[66:67], v[146:147], v[140:141] neg_lo:[0,1] neg_hi:[0,1]
	v_pk_add_f32 v[140:141], v[120:121], v[152:153]
	v_pk_add_f32 v[162:163], v[116:117], v[178:179]
	v_pk_add_f32 v[70:71], v[116:117], v[178:179] neg_lo:[0,1] neg_hi:[0,1]
	v_mov_b32_e32 v116, v75
	v_pk_mul_f32 v[116:117], v[116:117], v[140:141] op_sel:[0,1] op_sel_hi:[0,0] neg_hi:[1,0]
	v_pk_fma_f32 v[116:117], v[140:141], v[74:75], v[116:117] op_sel_hi:[1,0,1]
	ds_write_b64 v222, v[116:117] offset:256
	v_pk_mul_f32 v[114:115], v[78:79], v[74:75] op_sel:[0,1] op_sel_hi:[1,0]
	v_pk_add_f32 v[172:173], v[128:129], v[72:73]
	v_pk_fma_f32 v[114:115], v[74:75], v[74:75], v[114:115] op_sel_hi:[1,0,1]
	v_pk_add_f32 v[128:129], v[128:129], v[72:73] op_sel:[1,1] op_sel_hi:[0,0] neg_lo:[0,1] neg_hi:[1,0]
	v_pk_mul_f32 v[116:117], v[154:155], v[114:115] op_sel:[1,1] op_sel_hi:[0,1] neg_hi:[0,1]
	v_pk_fma_f32 v[116:117], v[154:155], v[114:115], v[116:117] op_sel_hi:[1,0,1]
	ds_write_b64 v222, v[116:117] offset:520
	v_pk_mul_f32 v[116:117], v[78:79], v[114:115] op_sel:[0,1] op_sel_hi:[1,0]
	v_pk_add_f32 v[120:121], v[120:121], v[152:153] neg_lo:[0,1] neg_hi:[0,1]
	v_pk_fma_f32 v[114:115], v[114:115], v[74:75], v[116:117] op_sel_hi:[1,0,1]
	v_pk_add_f32 v[152:153], v[122:123], v[130:131]
	v_pk_add_f32 v[122:123], v[122:123], v[130:131] neg_lo:[0,1] neg_hi:[0,1]
	v_pk_add_f32 v[130:131], v[126:127], v[124:125]
	v_pk_add_f32 v[72:73], v[126:127], v[124:125] neg_lo:[0,1] neg_hi:[0,1]
	v_pk_add_f32 v[124:125], v[80:81], v[172:173]
	v_pk_mul_f32 v[116:117], v[124:125], v[114:115] op_sel:[1,1] op_sel_hi:[0,1] neg_hi:[0,1]
	v_pk_add_f32 v[126:127], v[80:81], v[172:173] neg_lo:[0,1] neg_hi:[0,1]
	v_pk_fma_f32 v[116:117], v[124:125], v[114:115], v[116:117] op_sel_hi:[1,0,1]
	ds_write_b64 v222, v[116:117] offset:784
	v_pk_mul_f32 v[112:113], v[78:79], v[114:115] op_sel:[0,1] op_sel_hi:[1,0]
	v_pk_add_f32 v[158:159], v[132:133], v[128:129]
	v_pk_fma_f32 v[112:113], v[114:115], v[74:75], v[112:113] op_sel_hi:[1,0,1]
	v_pk_add_f32 v[80:81], v[132:133], v[128:129] neg_lo:[0,1] neg_hi:[0,1]
	v_pk_add_f32 v[128:129], v[174:175], v[176:177]
	v_pk_mul_f32 v[114:115], v[134:135], v[112:113] op_sel:[1,1] op_sel_hi:[0,1] neg_hi:[0,1]
	v_pk_add_f32 v[146:147], v[148:149], v[164:165]
	v_pk_fma_f32 v[114:115], v[134:135], v[112:113], v[114:115] op_sel_hi:[1,0,1]
	ds_write_b64 v222, v[114:115] offset:1048
	v_pk_mul_f32 v[114:115], v[78:79], v[112:113] op_sel:[0,1] op_sel_hi:[1,0]
	v_pk_add_f32 v[132:133], v[174:175], v[176:177] neg_lo:[0,1] neg_hi:[0,1]
	v_pk_fma_f32 v[112:113], v[112:113], v[74:75], v[114:115] op_sel_hi:[1,0,1]
	v_pk_add_f32 v[148:149], v[148:149], v[164:165] neg_lo:[0,1] neg_hi:[0,1]
	s_nop 0
	v_pk_mul_f32 v[114:115], v[152:153], v[112:113] op_sel:[1,1] op_sel_hi:[0,1] neg_hi:[0,1]
	s_nop 0
	v_pk_fma_f32 v[114:115], v[152:153], v[112:113], v[114:115] op_sel_hi:[1,0,1]
	ds_write_b64 v222, v[114:115] offset:1312
	v_pk_mul_f32 v[110:111], v[78:79], v[112:113] op_sel:[0,1] op_sel_hi:[1,0]
	s_nop 0
	v_pk_fma_f32 v[110:111], v[112:113], v[74:75], v[110:111] op_sel_hi:[1,0,1]
	s_nop 0
	s_nop 0
	v_pk_mul_f32 v[112:113], v[144:145], v[110:111] op_sel:[1,1] op_sel_hi:[0,1] neg_hi:[0,1]
	s_nop 0
	v_pk_fma_f32 v[112:113], v[144:145], v[110:111], v[112:113] op_sel_hi:[1,0,1]
	ds_write_b64 v222, v[112:113] offset:1576
	v_pk_mul_f32 v[112:113], v[78:79], v[110:111] op_sel:[0,1] op_sel_hi:[1,0]
	s_nop 0
	v_pk_fma_f32 v[110:111], v[110:111], v[74:75], v[112:113] op_sel_hi:[1,0,1]
	s_nop 0
	s_nop 0
	v_pk_mul_f32 v[112:113], v[128:129], v[110:111] op_sel:[1,1] op_sel_hi:[0,1] neg_hi:[0,1]
	s_nop 0
	v_pk_fma_f32 v[112:113], v[128:129], v[110:111], v[112:113] op_sel_hi:[1,0,1]
	ds_write_b64 v222, v[112:113] offset:1840
	v_pk_mul_f32 v[108:109], v[78:79], v[110:111] op_sel:[0,1] op_sel_hi:[1,0]
	s_nop 0
	v_pk_fma_f32 v[108:109], v[110:111], v[74:75], v[108:109] op_sel_hi:[1,0,1]
	s_nop 0
	s_nop 0
	v_pk_mul_f32 v[110:111], v[168:169], v[108:109] op_sel:[1,1] op_sel_hi:[0,1] neg_hi:[0,1]
	s_nop 0
	v_pk_fma_f32 v[110:111], v[168:169], v[108:109], v[110:111] op_sel_hi:[1,0,1]
	ds_write_b64 v222, v[110:111] offset:2104
	v_pk_mul_f32 v[110:111], v[78:79], v[108:109] op_sel:[0,1] op_sel_hi:[1,0]
	s_nop 0
	v_pk_fma_f32 v[108:109], v[108:109], v[74:75], v[110:111] op_sel_hi:[1,0,1]
	s_nop 0
	s_nop 0
	v_pk_mul_f32 v[110:111], v[146:147], v[108:109] op_sel:[1,1] op_sel_hi:[0,1] neg_hi:[0,1]
	s_nop 0
	v_pk_fma_f32 v[110:111], v[146:147], v[108:109], v[110:111] op_sel_hi:[1,0,1]
	ds_write_b64 v222, v[110:111] offset:2368
	v_pk_mul_f32 v[106:107], v[78:79], v[108:109] op_sel:[0,1] op_sel_hi:[1,0]
	s_nop 0
	v_pk_fma_f32 v[106:107], v[108:109], v[74:75], v[106:107] op_sel_hi:[1,0,1]
	s_nop 0
	s_nop 0
	v_pk_mul_f32 v[108:109], v[156:157], v[106:107] op_sel:[1,1] op_sel_hi:[0,1] neg_hi:[0,1]
	s_nop 0
	v_pk_fma_f32 v[108:109], v[156:157], v[106:107], v[108:109] op_sel_hi:[1,0,1]
	ds_write_b64 v222, v[108:109] offset:2632
	v_pk_mul_f32 v[108:109], v[78:79], v[106:107] op_sel:[0,1] op_sel_hi:[1,0]
	s_nop 0
	v_pk_fma_f32 v[106:107], v[106:107], v[74:75], v[108:109] op_sel_hi:[1,0,1]
	s_nop 0
	s_nop 0
	v_pk_mul_f32 v[108:109], v[158:159], v[106:107] op_sel:[1,1] op_sel_hi:[0,1] neg_hi:[0,1]
	s_nop 0
	v_pk_fma_f32 v[108:109], v[158:159], v[106:107], v[108:109] op_sel_hi:[1,0,1]
	ds_write_b64 v222, v[108:109] offset:2896
	v_pk_mul_f32 v[108:109], v[78:79], v[106:107] op_sel:[0,1] op_sel_hi:[1,0]
	s_nop 0
	v_pk_fma_f32 v[106:107], v[106:107], v[74:75], v[108:109] op_sel_hi:[1,0,1]
	s_nop 0
	s_nop 0
	v_pk_mul_f32 v[108:109], v[160:161], v[106:107] op_sel:[1,1] op_sel_hi:[0,1] neg_hi:[0,1]
	s_nop 0
	v_pk_fma_f32 v[108:109], v[160:161], v[106:107], v[108:109] op_sel_hi:[1,0,1]
	ds_write_b64 v222, v[108:109] offset:3160
	v_pk_mul_f32 v[102:103], v[78:79], v[106:107] op_sel:[0,1] op_sel_hi:[1,0]
	s_nop 0
	v_pk_fma_f32 v[102:103], v[106:107], v[74:75], v[102:103] op_sel_hi:[1,0,1]
	s_nop 0
	s_nop 0
	v_pk_mul_f32 v[106:107], v[130:131], v[102:103] op_sel:[1,1] op_sel_hi:[0,1] neg_hi:[0,1]
	s_nop 0
	v_pk_fma_f32 v[106:107], v[130:131], v[102:103], v[106:107] op_sel_hi:[1,0,1]
	ds_write_b64 v222, v[106:107] offset:3424
	v_pk_mul_f32 v[106:107], v[78:79], v[102:103] op_sel:[0,1] op_sel_hi:[1,0]
	s_nop 0
	v_pk_fma_f32 v[102:103], v[102:103], v[74:75], v[106:107] op_sel_hi:[1,0,1]
	s_nop 0
	s_nop 0
	v_pk_mul_f32 v[106:107], v[150:151], v[102:103] op_sel:[1,1] op_sel_hi:[0,1] neg_hi:[0,1]
	v_pk_fma_f32 v[106:107], v[150:151], v[102:103], v[106:107] op_sel_hi:[1,0,1]
	ds_write_b64 v222, v[106:107] offset:3688
	v_pk_mul_f32 v[100:101], v[78:79], v[102:103] op_sel:[0,1] op_sel_hi:[1,0]
	s_nop 0
	v_pk_fma_f32 v[100:101], v[102:103], v[74:75], v[100:101] op_sel_hi:[1,0,1]
	s_nop 0
	s_nop 0
	v_pk_mul_f32 v[102:103], v[162:163], v[100:101] op_sel:[1,1] op_sel_hi:[0,1] neg_hi:[0,1]
	v_pk_fma_f32 v[102:103], v[162:163], v[100:101], v[102:103] op_sel_hi:[1,0,1]
	ds_write_b64 v222, v[102:103] offset:3952
	v_pk_mul_f32 v[102:103], v[78:79], v[100:101] op_sel:[0,1] op_sel_hi:[1,0]
	s_nop 0
	v_pk_fma_f32 v[100:101], v[100:101], v[74:75], v[102:103] op_sel_hi:[1,0,1]
	s_nop 0
	s_nop 0
	v_pk_mul_f32 v[102:103], v[118:119], v[100:101] op_sel:[1,1] op_sel_hi:[0,1] neg_hi:[0,1]
	v_pk_fma_f32 v[102:103], v[118:119], v[100:101], v[102:103] op_sel_hi:[1,0,1]
	ds_write_b64 v222, v[102:103] offset:4216
	v_pk_mul_f32 v[98:99], v[78:79], v[100:101] op_sel:[0,1] op_sel_hi:[1,0]
	s_nop 0
	v_pk_fma_f32 v[98:99], v[100:101], v[74:75], v[98:99] op_sel_hi:[1,0,1]
	s_nop 0
	s_nop 0
	v_pk_mul_f32 v[100:101], v[120:121], v[98:99] op_sel:[1,1] op_sel_hi:[0,1] neg_hi:[0,1]
	v_pk_fma_f32 v[100:101], v[120:121], v[98:99], v[100:101] op_sel_hi:[1,0,1]
	ds_write_b64 v222, v[100:101] offset:4480
	v_pk_mul_f32 v[100:101], v[78:79], v[98:99] op_sel:[0,1] op_sel_hi:[1,0]
	s_nop 0
	v_pk_fma_f32 v[98:99], v[98:99], v[74:75], v[100:101] op_sel_hi:[1,0,1]
	s_nop 0
	s_nop 0
	v_pk_mul_f32 v[100:101], v[142:143], v[98:99] op_sel:[1,1] op_sel_hi:[0,1] neg_hi:[0,1]
	v_pk_fma_f32 v[100:101], v[142:143], v[98:99], v[100:101] op_sel_hi:[1,0,1]
	ds_write_b64 v222, v[100:101] offset:4744
	v_pk_mul_f32 v[96:97], v[78:79], v[98:99] op_sel:[0,1] op_sel_hi:[1,0]
	s_nop 0
	v_pk_fma_f32 v[96:97], v[98:99], v[74:75], v[96:97] op_sel_hi:[1,0,1]
	s_nop 0
	s_nop 0
	v_pk_mul_f32 v[98:99], v[126:127], v[96:97] op_sel:[1,1] op_sel_hi:[0,1] neg_hi:[0,1]
	v_pk_fma_f32 v[98:99], v[126:127], v[96:97], v[98:99] op_sel_hi:[1,0,1]
	ds_write_b64 v222, v[98:99] offset:5008
	v_pk_mul_f32 v[98:99], v[78:79], v[96:97] op_sel:[0,1] op_sel_hi:[1,0]
	s_nop 0
	v_pk_fma_f32 v[96:97], v[96:97], v[74:75], v[98:99] op_sel_hi:[1,0,1]
	s_nop 0
	s_nop 0
	v_pk_mul_f32 v[98:99], v[136:137], v[96:97] op_sel:[1,1] op_sel_hi:[0,1] neg_hi:[0,1]
	v_pk_fma_f32 v[98:99], v[136:137], v[96:97], v[98:99] op_sel_hi:[1,0,1]
	ds_write_b64 v222, v[98:99] offset:5272
	v_pk_mul_f32 v[94:95], v[78:79], v[96:97] op_sel:[0,1] op_sel_hi:[1,0]
	s_nop 0
	v_pk_fma_f32 v[94:95], v[96:97], v[74:75], v[94:95] op_sel_hi:[1,0,1]
	s_nop 0
	s_nop 0
	v_pk_mul_f32 v[96:97], v[122:123], v[94:95] op_sel:[1,1] op_sel_hi:[0,1] neg_hi:[0,1]
	v_pk_fma_f32 v[96:97], v[122:123], v[94:95], v[96:97] op_sel_hi:[1,0,1]
	ds_write_b64 v222, v[96:97] offset:5536
	v_pk_mul_f32 v[96:97], v[78:79], v[94:95] op_sel:[0,1] op_sel_hi:[1,0]
	s_nop 0
	v_pk_fma_f32 v[94:95], v[94:95], v[74:75], v[96:97] op_sel_hi:[1,0,1]
	s_nop 0
	s_nop 0
	v_pk_mul_f32 v[96:97], v[138:139], v[94:95] op_sel:[1,1] op_sel_hi:[0,1] neg_hi:[0,1]
	v_pk_fma_f32 v[96:97], v[138:139], v[94:95], v[96:97] op_sel_hi:[1,0,1]
	ds_write_b64 v222, v[96:97] offset:5800
	v_pk_mul_f32 v[92:93], v[78:79], v[94:95] op_sel:[0,1] op_sel_hi:[1,0]
	s_nop 0
	v_pk_fma_f32 v[92:93], v[94:95], v[74:75], v[92:93] op_sel_hi:[1,0,1]
	s_nop 0
	s_nop 0
	v_pk_mul_f32 v[94:95], v[132:133], v[92:93] op_sel:[1,1] op_sel_hi:[0,1] neg_hi:[0,1]
	v_pk_fma_f32 v[94:95], v[132:133], v[92:93], v[94:95] op_sel_hi:[1,0,1]
	ds_write_b64 v222, v[94:95] offset:6064
	v_pk_mul_f32 v[94:95], v[78:79], v[92:93] op_sel:[0,1] op_sel_hi:[1,0]
	s_nop 0
	v_pk_fma_f32 v[92:93], v[92:93], v[74:75], v[94:95] op_sel_hi:[1,0,1]
	s_nop 0
	s_nop 0
	v_pk_mul_f32 v[94:95], v[82:83], v[92:93] op_sel:[1,1] op_sel_hi:[0,1] neg_hi:[0,1]
	v_pk_fma_f32 v[82:83], v[82:83], v[92:93], v[94:95] op_sel_hi:[1,0,1]
	ds_write_b64 v222, v[82:83] offset:6328
	v_pk_mul_f32 v[82:83], v[78:79], v[92:93] op_sel:[0,1] op_sel_hi:[1,0]
	s_nop 0
	v_pk_fma_f32 v[82:83], v[92:93], v[74:75], v[82:83] op_sel_hi:[1,0,1]
	s_nop 0
	s_nop 0
	v_pk_mul_f32 v[90:91], v[148:149], v[82:83] op_sel:[1,1] op_sel_hi:[0,1] neg_hi:[0,1]
	v_pk_fma_f32 v[90:91], v[148:149], v[82:83], v[90:91] op_sel_hi:[1,0,1]
	ds_write_b64 v222, v[90:91] offset:6592
	v_pk_mul_f32 v[90:91], v[78:79], v[82:83] op_sel:[0,1] op_sel_hi:[1,0]
	s_nop 0
	v_pk_fma_f32 v[82:83], v[82:83], v[74:75], v[90:91] op_sel_hi:[1,0,1]
	s_nop 0
	s_nop 0
	v_pk_mul_f32 v[90:91], v[76:77], v[82:83] op_sel:[1,1] op_sel_hi:[0,1] neg_hi:[0,1]
	v_pk_fma_f32 v[76:77], v[76:77], v[82:83], v[90:91] op_sel_hi:[1,0,1]
	ds_write_b64 v222, v[76:77] offset:6856
	v_pk_mul_f32 v[76:77], v[78:79], v[82:83] op_sel:[0,1] op_sel_hi:[1,0]
	s_nop 0
	v_pk_fma_f32 v[76:77], v[82:83], v[74:75], v[76:77] op_sel_hi:[1,0,1]
	s_nop 0
	s_nop 0
	v_pk_mul_f32 v[82:83], v[80:81], v[76:77] op_sel:[1,1] op_sel_hi:[0,1] neg_hi:[0,1]
	v_pk_fma_f32 v[80:81], v[80:81], v[76:77], v[82:83] op_sel_hi:[1,0,1]
	ds_write_b64 v222, v[80:81] offset:7120
	v_pk_mul_f32 v[80:81], v[78:79], v[76:77] op_sel:[0,1] op_sel_hi:[1,0]
	s_nop 0
	v_pk_fma_f32 v[76:77], v[76:77], v[74:75], v[80:81] op_sel_hi:[1,0,1]
	s_nop 0
	s_nop 0
	v_pk_mul_f32 v[80:81], v[68:69], v[76:77] op_sel:[1,1] op_sel_hi:[0,1] neg_hi:[0,1]
	v_pk_fma_f32 v[68:69], v[68:69], v[76:77], v[80:81] op_sel_hi:[1,0,1]
	ds_write_b64 v222, v[68:69] offset:7384
	v_pk_mul_f32 v[68:69], v[78:79], v[76:77] op_sel:[0,1] op_sel_hi:[1,0]
	s_nop 0
	v_pk_fma_f32 v[68:69], v[76:77], v[74:75], v[68:69] op_sel_hi:[1,0,1]
	s_nop 0
	s_nop 0
	v_pk_mul_f32 v[76:77], v[72:73], v[68:69] op_sel:[1,1] op_sel_hi:[0,1] neg_hi:[0,1]
	v_pk_fma_f32 v[72:73], v[72:73], v[68:69], v[76:77] op_sel_hi:[1,0,1]
	ds_write_b64 v222, v[72:73] offset:7648
	v_pk_mul_f32 v[72:73], v[78:79], v[68:69] op_sel:[0,1] op_sel_hi:[1,0]
	s_nop 0
	v_pk_fma_f32 v[68:69], v[68:69], v[74:75], v[72:73] op_sel_hi:[1,0,1]
	s_nop 0
	s_nop 0
	v_pk_mul_f32 v[72:73], v[66:67], v[68:69] op_sel:[1,1] op_sel_hi:[0,1] neg_hi:[0,1]
	v_pk_fma_f32 v[66:67], v[66:67], v[68:69], v[72:73] op_sel_hi:[1,0,1]
	ds_write_b64 v222, v[66:67] offset:7912
	v_pk_mul_f32 v[66:67], v[78:79], v[68:69] op_sel:[0,1] op_sel_hi:[1,0]
	s_nop 0
	v_pk_fma_f32 v[66:67], v[68:69], v[74:75], v[66:67] op_sel_hi:[1,0,1]
	s_nop 0
	s_nop 0
	v_pk_mul_f32 v[68:69], v[70:71], v[66:67] op_sel:[1,1] op_sel_hi:[0,1] neg_hi:[0,1]
	v_pk_fma_f32 v[66:67], v[70:71], v[66:67], v[68:69] op_sel_hi:[1,0,1]
	ds_write_b64 v222, v[66:67] offset:8176
	s_waitcnt lgkmcnt(0)
	s_barrier
	ds_read2_b64 v[66:69], v104 offset1:1
	ds_read2_b64 v[70:73], v104 offset0:2 offset1:3
	ds_read2_b64 v[74:77], v104 offset0:4 offset1:5
	ds_read2_b64 v[78:81], v104 offset0:6 offset1:7
	ds_read2_b64 v[82:85], v104 offset0:8 offset1:9
	ds_read2_b64 v[86:89], v104 offset0:10 offset1:11
	ds_read2_b64 v[90:93], v104 offset0:12 offset1:13
	ds_read2_b64 v[94:97], v104 offset0:14 offset1:15
	ds_read2_b64 v[98:101], v104 offset0:16 offset1:17
	ds_read2_b64 v[106:109], v104 offset0:18 offset1:19
	ds_read2_b64 v[110:113], v104 offset0:20 offset1:21
	ds_read2_b64 v[114:117], v104 offset0:22 offset1:23
	ds_read2_b64 v[118:121], v104 offset0:24 offset1:25
	ds_read2_b64 v[122:125], v104 offset0:26 offset1:27
	ds_read2_b64 v[126:129], v104 offset0:28 offset1:29
	ds_read2_b64 v[130:133], v104 offset0:30 offset1:31
	s_waitcnt lgkmcnt(7)
	v_pk_add_f32 v[102:103], v[66:67], v[98:99]
	v_pk_add_f32 v[66:67], v[66:67], v[98:99] neg_lo:[0,1] neg_hi:[0,1]
	v_pk_add_f32 v[98:99], v[68:69], v[100:101]
	v_pk_add_f32 v[68:69], v[68:69], v[100:101] neg_lo:[0,1] neg_hi:[0,1]
	global_load_dwordx2 v[134:135], v[2:3], off
	global_load_dwordx2 v[136:137], v[4:5], off
	global_load_dwordx2 v[138:139], v[6:7], off
	v_pk_mul_f32 v[100:101], v[68:69], s[18:19]
	global_load_dwordx2 v[148:149], v[14:15], off
	global_load_dwordx2 v[154:155], v[16:17], off
	v_pk_fma_f32 v[68:69], v[68:69], s[20:21], v[100:101] op_sel:[0,0,1] op_sel_hi:[1,0,0]
	s_waitcnt lgkmcnt(6)
	v_pk_add_f32 v[100:101], v[70:71], v[106:107]
	v_pk_add_f32 v[70:71], v[70:71], v[106:107] neg_lo:[0,1] neg_hi:[0,1]
	global_load_dwordx2 v[158:159], v[18:19], off
	v_pk_mul_f32 v[106:107], v[70:71], s[4:5]
	global_load_dwordx2 v[160:161], v[28:29], off
	global_load_dwordx2 v[164:165], v[32:33], off
	v_pk_fma_f32 v[70:71], v[70:71], s[6:7], v[106:107] op_sel:[0,0,1] op_sel_hi:[1,0,0]
	v_pk_add_f32 v[106:107], v[72:73], v[108:109]
	v_pk_add_f32 v[72:73], v[72:73], v[108:109] neg_lo:[0,1] neg_hi:[0,1]
	global_load_dwordx2 v[168:169], v[36:37], off
	v_pk_mul_f32 v[108:109], v[72:73], s[22:23]
	global_load_dwordx2 v[172:173], v[44:45], off
	v_pk_fma_f32 v[72:73], v[72:73], s[24:25], v[108:109] op_sel:[0,0,1] op_sel_hi:[1,0,0]
	s_waitcnt lgkmcnt(5)
	v_pk_add_f32 v[108:109], v[74:75], v[110:111]
	v_pk_add_f32 v[74:75], v[74:75], v[110:111] neg_lo:[0,1] neg_hi:[0,1]
	global_load_dwordx2 v[174:175], v[52:53], off
	v_pk_mul_f32 v[110:111], v[74:75], s[8:9]
	global_load_dwordx2 v[176:177], v[60:61], off
	v_pk_fma_f32 v[74:75], v[74:75], s[10:11], v[110:111] op_sel:[0,0,1] op_sel_hi:[1,0,0]
	v_pk_add_f32 v[110:111], v[76:77], v[112:113]
	v_pk_add_f32 v[76:77], v[76:77], v[112:113] neg_lo:[0,1] neg_hi:[0,1]
	s_nop 0
	v_pk_mul_f32 v[112:113], v[76:77], s[26:27]
	s_nop 0
	v_pk_fma_f32 v[76:77], v[76:77], s[0:1], v[112:113] op_sel:[0,0,1] op_sel_hi:[1,0,0]
	s_waitcnt lgkmcnt(4)
	v_pk_add_f32 v[112:113], v[78:79], v[114:115]
	v_pk_add_f32 v[78:79], v[78:79], v[114:115] neg_lo:[0,1] neg_hi:[0,1]
	s_nop 0
	v_pk_mul_f32 v[114:115], v[78:79], s[12:13]
	s_nop 0
	v_pk_fma_f32 v[78:79], v[78:79], s[14:15], v[114:115] op_sel:[0,0,1] op_sel_hi:[1,0,0]
	v_pk_add_f32 v[114:115], v[80:81], v[116:117]
	v_pk_add_f32 v[80:81], v[80:81], v[116:117] neg_lo:[0,1] neg_hi:[0,1]
	s_nop 0
	v_pk_mul_f32 v[116:117], v[80:81], s[34:35]
	s_nop 0
	v_pk_fma_f32 v[80:81], v[80:81], s[48:49], v[116:117] op_sel:[0,0,1] op_sel_hi:[1,0,0]
	s_waitcnt lgkmcnt(3)
	v_pk_add_f32 v[116:117], v[82:83], v[118:119]
	v_pk_add_f32 v[118:119], v[82:83], v[118:119] op_sel:[1,1] op_sel_hi:[0,0] neg_lo:[0,1] neg_hi:[1,0]
	s_nop 0
	v_pk_add_f32 v[82:83], v[84:85], v[120:121]
	v_pk_add_f32 v[84:85], v[84:85], v[120:121] neg_lo:[0,1] neg_hi:[0,1]
	s_nop 0
	v_pk_mul_f32 v[120:121], v[84:85], s[34:35]
	s_nop 0
	v_pk_fma_f32 v[84:85], v[84:85], s[18:19], v[120:121] op_sel:[0,0,1] op_sel_hi:[1,0,0]
	s_waitcnt lgkmcnt(2)
	v_pk_add_f32 v[120:121], v[86:87], v[122:123]
	v_pk_add_f32 v[86:87], v[86:87], v[122:123] neg_lo:[0,1] neg_hi:[0,1]
	s_nop 0
	v_pk_mul_f32 v[122:123], v[86:87], s[12:13]
	s_nop 0
	v_pk_fma_f32 v[86:87], v[86:87], s[4:5], v[122:123] op_sel:[0,0,1] op_sel_hi:[1,0,0]
	v_pk_add_f32 v[122:123], v[88:89], v[124:125]
	v_pk_add_f32 v[88:89], v[88:89], v[124:125] neg_lo:[0,1] neg_hi:[0,1]
	s_nop 0
	v_pk_mul_f32 v[124:125], v[88:89], s[26:27]
	s_nop 0
	v_pk_fma_f32 v[88:89], v[88:89], s[22:23], v[124:125] op_sel:[0,0,1] op_sel_hi:[1,0,0]
	s_waitcnt lgkmcnt(1)
	v_pk_add_f32 v[124:125], v[90:91], v[126:127]
	v_pk_add_f32 v[90:91], v[90:91], v[126:127] neg_lo:[0,1] neg_hi:[0,1]
	s_nop 0
	v_pk_mul_f32 v[126:127], v[90:91], s[8:9]
	s_nop 0
	v_pk_fma_f32 v[90:91], v[90:91], s[8:9], v[126:127] op_sel:[0,0,1] op_sel_hi:[1,0,0]
	v_pk_add_f32 v[126:127], v[92:93], v[128:129]
	v_pk_add_f32 v[92:93], v[92:93], v[128:129] neg_lo:[0,1] neg_hi:[0,1]
	s_nop 0
	v_pk_mul_f32 v[128:129], v[92:93], s[22:23]
	s_nop 0
	v_pk_fma_f32 v[92:93], v[92:93], s[26:27], v[128:129] op_sel:[0,0,1] op_sel_hi:[1,0,0]
	s_waitcnt lgkmcnt(0)
	v_pk_add_f32 v[128:129], v[94:95], v[130:131]
	v_pk_add_f32 v[94:95], v[94:95], v[130:131] neg_lo:[0,1] neg_hi:[0,1]
	s_nop 0
	v_pk_mul_f32 v[130:131], v[94:95], s[4:5]
	s_nop 0
	v_pk_fma_f32 v[94:95], v[94:95], s[12:13], v[130:131] op_sel:[0,0,1] op_sel_hi:[1,0,0]
	v_pk_add_f32 v[130:131], v[96:97], v[132:133]
	v_pk_add_f32 v[96:97], v[96:97], v[132:133] neg_lo:[0,1] neg_hi:[0,1]
	s_nop 0
	v_pk_mul_f32 v[132:133], v[96:97], s[18:19]
	s_nop 0
	v_pk_fma_f32 v[96:97], v[96:97], s[34:35], v[132:133] op_sel:[0,0,1] op_sel_hi:[1,0,0]
	v_pk_add_f32 v[132:133], v[102:103], v[116:117]
	v_pk_add_f32 v[102:103], v[102:103], v[116:117] neg_lo:[0,1] neg_hi:[0,1]
	v_pk_add_f32 v[116:117], v[98:99], v[82:83]
	v_pk_add_f32 v[82:83], v[98:99], v[82:83] neg_lo:[0,1] neg_hi:[0,1]
	s_nop 0
	v_pk_mul_f32 v[98:99], v[82:83], s[4:5]
	s_nop 0
	v_pk_fma_f32 v[82:83], v[82:83], s[6:7], v[98:99] op_sel:[0,0,1] op_sel_hi:[1,0,0]
	v_pk_add_f32 v[98:99], v[100:101], v[120:121]
	v_pk_add_f32 v[100:101], v[100:101], v[120:121] neg_lo:[0,1] neg_hi:[0,1]
	s_nop 0
	v_pk_mul_f32 v[120:121], v[100:101], s[8:9]
	s_nop 0
	v_pk_fma_f32 v[100:101], v[100:101], s[10:11], v[120:121] op_sel:[0,0,1] op_sel_hi:[1,0,0]
	v_pk_add_f32 v[120:121], v[106:107], v[122:123]
	v_pk_add_f32 v[106:107], v[106:107], v[122:123] neg_lo:[0,1] neg_hi:[0,1]
	s_nop 0
	v_pk_mul_f32 v[122:123], v[106:107], s[12:13]
	s_nop 0
	v_pk_fma_f32 v[106:107], v[106:107], s[14:15], v[122:123] op_sel:[0,0,1] op_sel_hi:[1,0,0]
	v_pk_add_f32 v[122:123], v[108:109], v[124:125]
	v_pk_add_f32 v[124:125], v[108:109], v[124:125] op_sel:[1,1] op_sel_hi:[0,0] neg_lo:[0,1] neg_hi:[1,0]
	s_nop 0
	v_pk_add_f32 v[108:109], v[110:111], v[126:127]
	v_pk_add_f32 v[110:111], v[110:111], v[126:127] neg_lo:[0,1] neg_hi:[0,1]
	s_nop 0
	v_pk_mul_f32 v[126:127], v[110:111], s[12:13]
	s_nop 0
	v_pk_fma_f32 v[110:111], v[110:111], s[4:5], v[126:127] op_sel:[0,0,1] op_sel_hi:[1,0,0]
	v_pk_add_f32 v[126:127], v[112:113], v[128:129]
	v_pk_add_f32 v[112:113], v[112:113], v[128:129] neg_lo:[0,1] neg_hi:[0,1]
	s_nop 0
	v_pk_mul_f32 v[128:129], v[112:113], s[8:9]
	s_nop 0
	v_pk_fma_f32 v[112:113], v[112:113], s[8:9], v[128:129] op_sel:[0,0,1] op_sel_hi:[1,0,0]
	v_pk_add_f32 v[128:129], v[114:115], v[130:131]
	v_pk_add_f32 v[114:115], v[114:115], v[130:131] neg_lo:[0,1] neg_hi:[0,1]
	s_nop 0
	v_pk_mul_f32 v[130:131], v[114:115], s[4:5]
	s_nop 0
	v_pk_fma_f32 v[114:115], v[114:115], s[12:13], v[130:131] op_sel:[0,0,1] op_sel_hi:[1,0,0]
	v_pk_add_f32 v[130:131], v[66:67], v[118:119]
	v_pk_add_f32 v[66:67], v[66:67], v[118:119] neg_lo:[0,1] neg_hi:[0,1]
	v_pk_add_f32 v[118:119], v[68:69], v[84:85]
	v_pk_add_f32 v[68:69], v[68:69], v[84:85] neg_lo:[0,1] neg_hi:[0,1]
	s_nop 0
	v_pk_mul_f32 v[84:85], v[68:69], s[4:5]
	s_nop 0
	v_pk_fma_f32 v[68:69], v[68:69], s[6:7], v[84:85] op_sel:[0,0,1] op_sel_hi:[1,0,0]
	v_pk_add_f32 v[84:85], v[70:71], v[86:87]
	v_pk_add_f32 v[70:71], v[70:71], v[86:87] neg_lo:[0,1] neg_hi:[0,1]
	s_nop 0
	v_pk_mul_f32 v[86:87], v[70:71], s[8:9]
	s_nop 0
	v_pk_fma_f32 v[70:71], v[70:71], s[10:11], v[86:87] op_sel:[0,0,1] op_sel_hi:[1,0,0]
	v_pk_add_f32 v[86:87], v[72:73], v[88:89]
	v_pk_add_f32 v[72:73], v[72:73], v[88:89] neg_lo:[0,1] neg_hi:[0,1]
	s_nop 0
	v_pk_mul_f32 v[88:89], v[72:73], s[12:13]
	s_nop 0
	v_pk_fma_f32 v[72:73], v[72:73], s[14:15], v[88:89] op_sel:[0,0,1] op_sel_hi:[1,0,0]
	v_pk_add_f32 v[88:89], v[74:75], v[90:91]
	v_pk_add_f32 v[90:91], v[74:75], v[90:91] op_sel:[1,1] op_sel_hi:[0,0] neg_lo:[0,1] neg_hi:[1,0]
	s_mov_b32 s15, s4
	v_pk_add_f32 v[74:75], v[76:77], v[92:93]
	v_pk_add_f32 v[76:77], v[76:77], v[92:93] neg_lo:[0,1] neg_hi:[0,1]
	s_nop 0
	v_pk_mul_f32 v[92:93], v[76:77], s[12:13]
	s_nop 0
	v_pk_fma_f32 v[76:77], v[76:77], s[4:5], v[92:93] op_sel:[0,0,1] op_sel_hi:[1,0,0]
	v_pk_add_f32 v[92:93], v[78:79], v[94:95]
	v_pk_add_f32 v[78:79], v[78:79], v[94:95] neg_lo:[0,1] neg_hi:[0,1]
	s_nop 0
	v_pk_mul_f32 v[94:95], v[78:79], s[8:9]
	s_nop 0
	v_pk_fma_f32 v[78:79], v[78:79], s[8:9], v[94:95] op_sel:[0,0,1] op_sel_hi:[1,0,0]
	v_pk_add_f32 v[94:95], v[80:81], v[96:97]
	v_pk_add_f32 v[80:81], v[80:81], v[96:97] neg_lo:[0,1] neg_hi:[0,1]
	s_nop 0
	v_pk_mul_f32 v[96:97], v[80:81], s[4:5]
	s_nop 0
	v_pk_fma_f32 v[80:81], v[80:81], s[12:13], v[96:97] op_sel:[0,0,1] op_sel_hi:[1,0,0]
	v_pk_add_f32 v[96:97], v[132:133], v[122:123]
	v_pk_add_f32 v[122:123], v[132:133], v[122:123] neg_lo:[0,1] neg_hi:[0,1]
	v_pk_add_f32 v[132:133], v[116:117], v[108:109]
	v_pk_add_f32 v[108:109], v[116:117], v[108:109] neg_lo:[0,1] neg_hi:[0,1]
	s_nop 0
	v_pk_mul_f32 v[116:117], v[108:109], s[8:9]
	s_nop 0
	v_pk_fma_f32 v[108:109], v[108:109], s[10:11], v[116:117] op_sel:[0,0,1] op_sel_hi:[1,0,0]
	v_pk_add_f32 v[116:117], v[98:99], v[126:127]
	v_pk_add_f32 v[126:127], v[98:99], v[126:127] op_sel:[1,1] op_sel_hi:[0,0] neg_lo:[0,1] neg_hi:[1,0]
	s_nop 0
	v_pk_add_f32 v[98:99], v[120:121], v[128:129]
	v_pk_add_f32 v[120:121], v[120:121], v[128:129] neg_lo:[0,1] neg_hi:[0,1]
	s_nop 0
	v_pk_mul_f32 v[128:129], v[120:121], s[8:9]
	s_nop 0
	v_pk_fma_f32 v[120:121], v[120:121], s[8:9], v[128:129] op_sel:[0,0,1] op_sel_hi:[1,0,0]
	v_pk_add_f32 v[128:129], v[102:103], v[124:125]
	v_pk_add_f32 v[102:103], v[102:103], v[124:125] neg_lo:[0,1] neg_hi:[0,1]
	v_pk_add_f32 v[124:125], v[82:83], v[110:111]
	v_pk_add_f32 v[82:83], v[82:83], v[110:111] neg_lo:[0,1] neg_hi:[0,1]
	s_nop 0
	v_pk_mul_f32 v[110:111], v[82:83], s[8:9]
	s_nop 0
	v_pk_fma_f32 v[82:83], v[82:83], s[10:11], v[110:111] op_sel:[0,0,1] op_sel_hi:[1,0,0]
	v_pk_add_f32 v[110:111], v[100:101], v[112:113]
	v_pk_add_f32 v[112:113], v[100:101], v[112:113] op_sel:[1,1] op_sel_hi:[0,0] neg_lo:[0,1] neg_hi:[1,0]
	s_nop 0
	v_pk_add_f32 v[100:101], v[106:107], v[114:115]
	v_pk_add_f32 v[106:107], v[106:107], v[114:115] neg_lo:[0,1] neg_hi:[0,1]
	s_nop 0
	v_pk_mul_f32 v[114:115], v[106:107], s[8:9]
	s_nop 0
	v_pk_fma_f32 v[106:107], v[106:107], s[8:9], v[114:115] op_sel:[0,0,1] op_sel_hi:[1,0,0]
	v_pk_add_f32 v[114:115], v[130:131], v[88:89]
	v_pk_add_f32 v[88:89], v[130:131], v[88:89] neg_lo:[0,1] neg_hi:[0,1]
	v_pk_add_f32 v[130:131], v[118:119], v[74:75]
	v_pk_add_f32 v[74:75], v[118:119], v[74:75] neg_lo:[0,1] neg_hi:[0,1]
	s_nop 0
	v_pk_mul_f32 v[118:119], v[74:75], s[8:9]
	s_nop 0
	v_pk_fma_f32 v[74:75], v[74:75], s[10:11], v[118:119] op_sel:[0,0,1] op_sel_hi:[1,0,0]
	v_pk_add_f32 v[118:119], v[84:85], v[92:93]
	v_pk_add_f32 v[92:93], v[84:85], v[92:93] op_sel:[1,1] op_sel_hi:[0,0] neg_lo:[0,1] neg_hi:[1,0]
	s_nop 0
	v_pk_add_f32 v[84:85], v[86:87], v[94:95]
	v_pk_add_f32 v[86:87], v[86:87], v[94:95] neg_lo:[0,1] neg_hi:[0,1]
	v_pk_add_f32 v[140:141], v[88:89], v[92:93]
	v_pk_mul_f32 v[94:95], v[86:87], s[8:9]
	v_pk_add_f32 v[88:89], v[88:89], v[92:93] neg_lo:[0,1] neg_hi:[0,1]
	v_pk_fma_f32 v[86:87], v[86:87], s[8:9], v[94:95] op_sel:[0,0,1] op_sel_hi:[1,0,0]
	v_pk_add_f32 v[94:95], v[66:67], v[90:91]
	v_pk_add_f32 v[66:67], v[66:67], v[90:91] neg_lo:[0,1] neg_hi:[0,1]
	v_pk_add_f32 v[90:91], v[68:69], v[76:77]
	v_pk_add_f32 v[68:69], v[68:69], v[76:77] neg_lo:[0,1] neg_hi:[0,1]
	v_pk_add_f32 v[92:93], v[74:75], v[86:87]
	v_pk_mul_f32 v[76:77], v[68:69], s[8:9]
	v_pk_add_f32 v[142:143], v[74:75], v[86:87] op_sel:[1,1] op_sel_hi:[0,0] neg_lo:[0,1] neg_hi:[1,0]
	v_pk_fma_f32 v[68:69], v[68:69], s[10:11], v[76:77] op_sel:[0,0,1] op_sel_hi:[1,0,0]
	v_pk_add_f32 v[76:77], v[70:71], v[78:79]
	v_pk_add_f32 v[78:79], v[70:71], v[78:79] op_sel:[1,1] op_sel_hi:[0,0] neg_lo:[0,1] neg_hi:[1,0]
	global_load_dwordx2 v[86:87], v[10:11], off
	v_pk_add_f32 v[70:71], v[72:73], v[80:81]
	v_pk_add_f32 v[72:73], v[72:73], v[80:81] neg_lo:[0,1] neg_hi:[0,1]
	v_pk_mul_f32 v[80:81], v[72:73], s[8:9]
	v_pk_fma_f32 v[72:73], v[72:73], s[8:9], v[80:81] op_sel:[0,0,1] op_sel_hi:[1,0,0]
	v_pk_add_f32 v[80:81], v[96:97], v[116:117]
	v_pk_add_f32 v[96:97], v[96:97], v[116:117] neg_lo:[0,1] neg_hi:[0,1]
	v_pk_add_f32 v[116:117], v[132:133], v[98:99]
	v_pk_add_f32 v[132:133], v[132:133], v[98:99] op_sel:[1,1] op_sel_hi:[0,0] neg_lo:[0,1] neg_hi:[1,0]
	v_pk_add_f32 v[74:75], v[94:95], v[76:77]
	v_pk_add_f32 v[98:99], v[122:123], v[126:127]
	v_pk_add_f32 v[122:123], v[122:123], v[126:127] neg_lo:[0,1] neg_hi:[0,1]
	v_pk_add_f32 v[126:127], v[108:109], v[120:121]
	v_pk_add_f32 v[120:121], v[108:109], v[120:121] op_sel:[1,1] op_sel_hi:[0,0] neg_lo:[0,1] neg_hi:[1,0]
	v_pk_add_f32 v[76:77], v[94:95], v[76:77] neg_lo:[0,1] neg_hi:[0,1]
	v_pk_add_f32 v[108:109], v[128:129], v[110:111]
	v_pk_add_f32 v[110:111], v[128:129], v[110:111] neg_lo:[0,1] neg_hi:[0,1]
	v_pk_add_f32 v[128:129], v[124:125], v[100:101]
	v_pk_add_f32 v[124:125], v[124:125], v[100:101] op_sel:[1,1] op_sel_hi:[0,0] neg_lo:[0,1] neg_hi:[1,0]
	global_load_dwordx2 v[94:95], v[12:13], off
	v_pk_add_f32 v[100:101], v[102:103], v[112:113]
	v_pk_add_f32 v[102:103], v[102:103], v[112:113] neg_lo:[0,1] neg_hi:[0,1]
	v_pk_add_f32 v[112:113], v[82:83], v[106:107]
	v_pk_add_f32 v[106:107], v[82:83], v[106:107] op_sel:[1,1] op_sel_hi:[0,0] neg_lo:[0,1] neg_hi:[1,0]
	v_pk_add_f32 v[146:147], v[66:67], v[78:79]
	v_pk_add_f32 v[82:83], v[114:115], v[118:119]
	v_pk_add_f32 v[114:115], v[114:115], v[118:119] neg_lo:[0,1] neg_hi:[0,1]
	v_pk_add_f32 v[118:119], v[130:131], v[84:85]
	v_pk_add_f32 v[130:131], v[130:131], v[84:85] op_sel:[1,1] op_sel_hi:[0,0] neg_lo:[0,1] neg_hi:[1,0]
	v_pk_add_f32 v[78:79], v[66:67], v[78:79] neg_lo:[0,1] neg_hi:[0,1]
	global_load_dwordx2 v[84:85], v[8:9], off
	v_pk_add_f32 v[152:153], v[68:69], v[72:73] op_sel:[1,1] op_sel_hi:[0,0] neg_lo:[0,1] neg_hi:[1,0]
	v_pk_add_f32 v[150:151], v[68:69], v[72:73]
	v_pk_add_f32 v[156:157], v[80:81], v[116:117]
	v_pk_add_f32 v[80:81], v[80:81], v[116:117] neg_lo:[0,1] neg_hi:[0,1]
	v_pk_add_f32 v[116:117], v[96:97], v[132:133]
	v_pk_add_f32 v[68:69], v[96:97], v[132:133] neg_lo:[0,1] neg_hi:[0,1]
	v_pk_add_f32 v[96:97], v[98:99], v[126:127]
	v_pk_add_f32 v[98:99], v[98:99], v[126:127] neg_lo:[0,1] neg_hi:[0,1]
	v_pk_add_f32 v[126:127], v[122:123], v[120:121]
	v_pk_add_f32 v[66:67], v[122:123], v[120:121] neg_lo:[0,1] neg_hi:[0,1]
	global_load_dwordx2 v[120:121], v[20:21], off
	v_pk_add_f32 v[122:123], v[108:109], v[128:129]
	v_pk_add_f32 v[108:109], v[108:109], v[128:129] neg_lo:[0,1] neg_hi:[0,1]
	v_pk_add_f32 v[128:129], v[110:111], v[124:125]
	v_pk_add_f32 v[72:73], v[110:111], v[124:125] neg_lo:[0,1] neg_hi:[0,1]
	global_load_dwordx2 v[110:111], v[22:23], off
	v_pk_add_f32 v[144:145], v[90:91], v[70:71]
	v_pk_add_f32 v[90:91], v[90:91], v[70:71] op_sel:[1,1] op_sel_hi:[0,0] neg_lo:[0,1] neg_hi:[1,0]
	v_pk_add_f32 v[124:125], v[100:101], v[112:113]
	v_pk_add_f32 v[100:101], v[100:101], v[112:113] neg_lo:[0,1] neg_hi:[0,1]
	v_pk_add_f32 v[112:113], v[102:103], v[106:107]
	v_pk_add_f32 v[70:71], v[102:103], v[106:107] neg_lo:[0,1] neg_hi:[0,1]
	global_load_dwordx2 v[102:103], v[24:25], off
	v_pk_add_f32 v[106:107], v[82:83], v[118:119]
	v_pk_add_f32 v[82:83], v[82:83], v[118:119] neg_lo:[0,1] neg_hi:[0,1]
	v_pk_add_f32 v[118:119], v[114:115], v[130:131]
	v_pk_add_f32 v[114:115], v[114:115], v[130:131] neg_lo:[0,1] neg_hi:[0,1]
	global_load_dwordx2 v[130:131], v[26:27], off
	v_pk_add_f32 v[162:163], v[76:77], v[90:91]
	v_pk_add_f32 v[76:77], v[76:77], v[90:91] neg_lo:[0,1] neg_hi:[0,1]
	v_pk_add_f32 v[90:91], v[146:147], v[150:151]
	v_pk_add_f32 v[146:147], v[146:147], v[150:151] neg_lo:[0,1] neg_hi:[0,1]
	v_pk_add_f32 v[150:151], v[78:79], v[152:153]
	v_pk_add_f32 v[78:79], v[78:79], v[152:153] neg_lo:[0,1] neg_hi:[0,1]
	global_load_dwordx2 v[152:153], v[34:35], off
	s_waitcnt vmcnt(19)
	v_pk_mul_f32 v[166:167], v[156:157], v[134:135] op_sel:[1,1] op_sel_hi:[0,1] neg_lo:[0,1]
	v_pk_add_f32 v[132:133], v[140:141], v[92:93]
	v_pk_fma_f32 v[134:135], v[156:157], v[134:135], v[166:167] op_sel_hi:[1,0,1]
	s_waitcnt vmcnt(18)
	global_load_dwordx2 v[166:167], v[38:39], off
	v_pk_mul_f32 v[156:157], v[106:107], v[136:137] op_sel:[1,1] op_sel_hi:[0,1] neg_lo:[0,1]
	v_pk_add_f32 v[92:93], v[140:141], v[92:93] neg_lo:[0,1] neg_hi:[0,1]
	v_pk_fma_f32 v[106:107], v[106:107], v[136:137], v[156:157] op_sel_hi:[1,0,1]
	s_waitcnt vmcnt(18)
	global_load_dwordx2 v[156:157], v[40:41], off
	v_pk_mul_f32 v[136:137], v[122:123], v[138:139] op_sel:[1,1] op_sel_hi:[0,1] neg_lo:[0,1]
	v_pk_add_f32 v[140:141], v[88:89], v[142:143]
	v_pk_fma_f32 v[122:123], v[122:123], v[138:139], v[136:137] op_sel_hi:[1,0,1]
	global_load_dwordx2 v[136:137], v[42:43], off
	v_pk_add_f32 v[88:89], v[88:89], v[142:143] neg_lo:[0,1] neg_hi:[0,1]
	v_pk_add_f32 v[142:143], v[74:75], v[144:145]
	v_pk_add_f32 v[74:75], v[74:75], v[144:145] neg_lo:[0,1] neg_hi:[0,1]
	global_load_dwordx2 v[144:145], v[30:31], off
	s_mov_b32 s11, s8
	s_waitcnt vmcnt(9)
	v_pk_mul_f32 v[138:139], v[142:143], v[84:85] op_sel:[1,1] op_sel_hi:[0,1] neg_lo:[0,1]
	s_nop 0
	v_pk_fma_f32 v[84:85], v[142:143], v[84:85], v[138:139] op_sel_hi:[1,0,1]
	global_load_dwordx2 v[142:143], v[46:47], off
	v_pk_mul_f32 v[138:139], v[96:97], v[86:87] op_sel:[1,1] op_sel_hi:[0,1] neg_lo:[0,1]
	s_nop 0
	v_pk_fma_f32 v[86:87], v[96:97], v[86:87], v[138:139] op_sel_hi:[1,0,1]
	global_load_dwordx2 v[138:139], v[48:49], off
	v_pk_mul_f32 v[96:97], v[132:133], v[94:95] op_sel:[1,1] op_sel_hi:[0,1] neg_lo:[0,1]
	s_nop 0
	v_pk_fma_f32 v[94:95], v[132:133], v[94:95], v[96:97] op_sel_hi:[1,0,1]
	global_load_dwordx2 v[96:97], v[50:51], off
	v_pk_mul_f32 v[132:133], v[124:125], v[148:149] op_sel:[1,1] op_sel_hi:[0,1] neg_lo:[0,1]
	s_nop 0
	v_pk_fma_f32 v[124:125], v[124:125], v[148:149], v[132:133] op_sel_hi:[1,0,1]
	global_load_dwordx2 v[148:149], v[54:55], off
	v_pk_mul_f32 v[132:133], v[90:91], v[154:155] op_sel:[1,1] op_sel_hi:[0,1] neg_lo:[0,1]
	s_nop 0
	v_pk_fma_f32 v[90:91], v[90:91], v[154:155], v[132:133] op_sel_hi:[1,0,1]
	global_load_dwordx2 v[154:155], v[56:57], off
	v_pk_mul_f32 v[132:133], v[116:117], v[158:159] op_sel:[1,1] op_sel_hi:[0,1] neg_lo:[0,1]
	v_pk_fma_f32 v[116:117], v[116:117], v[158:159], v[132:133] op_sel_hi:[1,0,1]
	global_load_dwordx2 v[132:133], v[58:59], off
	s_waitcnt vmcnt(14)
	v_pk_mul_f32 v[158:159], v[118:119], v[120:121] op_sel:[1,1] op_sel_hi:[0,1] neg_lo:[0,1]
	v_pk_fma_f32 v[118:119], v[118:119], v[120:121], v[158:159] op_sel_hi:[1,0,1]
	s_waitcnt vmcnt(13)
	global_load_dwordx2 v[158:159], v[62:63], off
	v_pk_mul_f32 v[120:121], v[128:129], v[110:111] op_sel:[1,1] op_sel_hi:[0,1] neg_lo:[0,1]
	v_pk_fma_f32 v[110:111], v[128:129], v[110:111], v[120:121] op_sel_hi:[1,0,1]
	global_load_dwordx2 v[128:129], v[64:65], off
	s_waitcnt vmcnt(14)
	v_pk_mul_f32 v[120:121], v[162:163], v[102:103] op_sel:[1,1] op_sel_hi:[0,1] neg_lo:[0,1]
	v_mov_b32 v0, 0
	s_nop 0
	v_pk_fma_f32 v[102:103], v[162:163], v[102:103], v[120:121] op_sel_hi:[1,0,1]
	s_waitcnt vmcnt(13)
	v_pk_mul_f32 v[120:121], v[126:127], v[130:131] op_sel:[1,1] op_sel_hi:[0,1] neg_lo:[0,1]
	v_pk_fma_f32 v[120:121], v[126:127], v[130:131], v[120:121] op_sel_hi:[1,0,1]
	v_pk_mul_f32 v[126:127], v[140:141], v[160:161] op_sel:[1,1] op_sel_hi:[0,1] neg_lo:[0,1]
	v_pk_fma_f32 v[126:127], v[140:141], v[160:161], v[126:127] op_sel_hi:[1,0,1]
	s_waitcnt vmcnt(12)
	v_pk_mul_f32 v[140:141], v[80:81], v[152:153] op_sel:[1,1] op_sel_hi:[0,1] neg_lo:[0,1]
	v_pk_fma_f32 v[80:81], v[80:81], v[152:153], v[140:141] op_sel_hi:[1,0,1]
	v_pk_mul_f32 v[140:141], v[82:83], v[168:169] op_sel:[1,1] op_sel_hi:[0,1] neg_lo:[0,1]
	v_pk_fma_f32 v[82:83], v[82:83], v[168:169], v[140:141] op_sel_hi:[1,0,1]
	s_waitcnt vmcnt(11)
	v_pk_mul_f32 v[140:141], v[108:109], v[166:167] op_sel:[1,1] op_sel_hi:[0,1] neg_lo:[0,1]
	v_pk_fma_f32 v[108:109], v[108:109], v[166:167], v[140:141] op_sel_hi:[1,0,1]
	s_waitcnt vmcnt(10)
	v_pk_mul_f32 v[140:141], v[74:75], v[156:157] op_sel:[1,1] op_sel_hi:[0,1] neg_lo:[0,1]
	v_pk_fma_f32 v[74:75], v[74:75], v[156:157], v[140:141] op_sel_hi:[1,0,1]
	s_waitcnt vmcnt(9)
	v_pk_mul_f32 v[140:141], v[98:99], v[136:137] op_sel:[1,1] op_sel_hi:[0,1] neg_lo:[0,1]
	v_pk_fma_f32 v[98:99], v[98:99], v[136:137], v[140:141] op_sel_hi:[1,0,1]
	v_pk_mul_f32 v[136:137], v[92:93], v[172:173] op_sel:[1,1] op_sel_hi:[0,1] neg_lo:[0,1]
	v_pk_fma_f32 v[92:93], v[92:93], v[172:173], v[136:137] op_sel_hi:[1,0,1]
	s_waitcnt vmcnt(8)
	v_pk_mul_f32 v[130:131], v[112:113], v[144:145] op_sel:[1,1] op_sel_hi:[0,1] neg_lo:[0,1]
	v_pk_fma_f32 v[112:113], v[112:113], v[144:145], v[130:131] op_sel_hi:[1,0,1]
	s_waitcnt vmcnt(7)
	v_pk_mul_f32 v[136:137], v[100:101], v[142:143] op_sel:[1,1] op_sel_hi:[0,1] neg_lo:[0,1]
	v_pk_fma_f32 v[100:101], v[100:101], v[142:143], v[136:137] op_sel_hi:[1,0,1]
	s_waitcnt vmcnt(6)
	v_pk_mul_f32 v[136:137], v[146:147], v[138:139] op_sel:[1,1] op_sel_hi:[0,1] neg_lo:[0,1]
	v_pk_fma_f32 v[136:137], v[146:147], v[138:139], v[136:137] op_sel_hi:[1,0,1]
	s_waitcnt vmcnt(5)
	v_pk_mul_f32 v[138:139], v[68:69], v[96:97] op_sel:[1,1] op_sel_hi:[0,1] neg_lo:[0,1]
	v_pk_fma_f32 v[68:69], v[68:69], v[96:97], v[138:139] op_sel_hi:[1,0,1]
	v_pk_mul_f32 v[96:97], v[114:115], v[174:175] op_sel:[1,1] op_sel_hi:[0,1] neg_lo:[0,1]
	v_pk_fma_f32 v[96:97], v[114:115], v[174:175], v[96:97] op_sel_hi:[1,0,1]
	s_waitcnt vmcnt(4)
	v_pk_mul_f32 v[114:115], v[72:73], v[148:149] op_sel:[1,1] op_sel_hi:[0,1] neg_lo:[0,1]
	v_pk_fma_f32 v[72:73], v[72:73], v[148:149], v[114:115] op_sel_hi:[1,0,1]
	v_pk_mul_f32 v[130:131], v[150:151], v[164:165] op_sel:[1,1] op_sel_hi:[0,1] neg_lo:[0,1]
	s_waitcnt vmcnt(3)
	v_pk_mul_f32 v[114:115], v[76:77], v[154:155] op_sel:[1,1] op_sel_hi:[0,1] neg_lo:[0,1]
	v_pk_fma_f32 v[76:77], v[76:77], v[154:155], v[114:115] op_sel_hi:[1,0,1]
	s_waitcnt vmcnt(2)
	v_pk_mul_f32 v[114:115], v[66:67], v[132:133] op_sel:[1,1] op_sel_hi:[0,1] neg_lo:[0,1]
	v_pk_fma_f32 v[66:67], v[66:67], v[132:133], v[114:115] op_sel_hi:[1,0,1]
	v_pk_mul_f32 v[114:115], v[88:89], v[176:177] op_sel:[1,1] op_sel_hi:[0,1] neg_lo:[0,1]
	v_pk_fma_f32 v[88:89], v[88:89], v[176:177], v[114:115] op_sel_hi:[1,0,1]
	s_waitcnt vmcnt(1)
	v_pk_mul_f32 v[114:115], v[70:71], v[158:159] op_sel:[1,1] op_sel_hi:[0,1] neg_lo:[0,1]
	v_pk_fma_f32 v[70:71], v[70:71], v[158:159], v[114:115] op_sel_hi:[1,0,1]
	s_waitcnt vmcnt(0)
	v_pk_mul_f32 v[114:115], v[78:79], v[128:129] op_sel:[1,1] op_sel_hi:[0,1] neg_lo:[0,1]
	v_pk_fma_f32 v[78:79], v[78:79], v[128:129], v[114:115] op_sel_hi:[1,0,1]
	v_pk_add_f32 v[128:129], v[106:107], v[82:83]
	v_pk_add_f32 v[82:83], v[106:107], v[82:83] neg_lo:[0,1] neg_hi:[0,1]
	v_pk_fma_f32 v[130:131], v[150:151], v[164:165], v[130:131] op_sel_hi:[1,0,1]
	v_pk_mul_f32 v[106:107], v[82:83], s[50:51]
	v_pk_add_f32 v[114:115], v[134:135], v[80:81]
	v_pk_fma_f32 v[82:83], v[82:83], s[20:21], v[106:107] op_sel:[0,0,1] op_sel_hi:[1,0,0]
	v_pk_add_f32 v[106:107], v[122:123], v[108:109]
	v_pk_add_f32 v[108:109], v[122:123], v[108:109] neg_lo:[0,1] neg_hi:[0,1]
	s_mov_b32 s21, s34
	v_pk_mul_f32 v[122:123], v[108:109], s[14:15]
	v_pk_add_f32 v[80:81], v[134:135], v[80:81] neg_lo:[0,1] neg_hi:[0,1]
	v_pk_fma_f32 v[108:109], v[108:109], s[6:7], v[122:123] op_sel:[0,0,1] op_sel_hi:[1,0,0]
	v_pk_add_f32 v[122:123], v[84:85], v[74:75]
	v_pk_add_f32 v[74:75], v[84:85], v[74:75] neg_lo:[0,1] neg_hi:[0,1]
	s_mov_b32 s7, s12
	v_pk_mul_f32 v[84:85], v[74:75], s[52:53]
	v_add_u32_e32 v0, v0, v170
	v_pk_fma_f32 v[74:75], v[74:75], s[24:25], v[84:85] op_sel:[0,0,1] op_sel_hi:[1,0,0]
	v_pk_add_f32 v[84:85], v[86:87], v[98:99]
	v_pk_add_f32 v[86:87], v[86:87], v[98:99] neg_lo:[0,1] neg_hi:[0,1]
	s_mov_b32 s25, s26
	v_pk_mul_f32 v[98:99], v[86:87], s[10:11]
	v_lshlrev_b32_e32 v105, 5, v0
	v_pk_fma_f32 v[86:87], v[86:87], s[10:11], v[98:99] op_sel:[0,0,1] op_sel_hi:[1,0,0]
	v_pk_add_f32 v[98:99], v[94:95], v[92:93]
	v_pk_add_f32 v[92:93], v[94:95], v[92:93] neg_lo:[0,1] neg_hi:[0,1]
	s_nop 0
	v_pk_mul_f32 v[94:95], v[92:93], s[24:25]
	s_nop 0
	v_pk_fma_f32 v[92:93], v[92:93], s[0:1], v[94:95] op_sel:[0,0,1] op_sel_hi:[1,0,0]
	v_pk_add_f32 v[94:95], v[124:125], v[100:101]
	v_pk_add_f32 v[100:101], v[124:125], v[100:101] neg_lo:[0,1] neg_hi:[0,1]
	s_nop 0
	v_pk_mul_f32 v[124:125], v[100:101], s[6:7]
	s_nop 0
	v_pk_fma_f32 v[100:101], v[100:101], s[14:15], v[124:125] op_sel:[0,0,1] op_sel_hi:[1,0,0]
	v_pk_add_f32 v[124:125], v[90:91], v[136:137]
	v_pk_add_f32 v[90:91], v[90:91], v[136:137] neg_lo:[0,1] neg_hi:[0,1]
	s_nop 0
	v_pk_mul_f32 v[132:133], v[90:91], s[20:21]
	s_nop 0
	v_pk_fma_f32 v[90:91], v[90:91], s[48:49], v[132:133] op_sel:[0,0,1] op_sel_hi:[1,0,0]
	v_pk_add_f32 v[132:133], v[116:117], v[68:69]
	v_pk_add_f32 v[116:117], v[116:117], v[68:69] op_sel:[1,1] op_sel_hi:[0,0] neg_lo:[1,0] neg_hi:[0,1]
	s_nop 0
	v_pk_add_f32 v[68:69], v[118:119], v[96:97]
	v_pk_add_f32 v[96:97], v[118:119], v[96:97] neg_lo:[0,1] neg_hi:[0,1]
	s_nop 0
	v_pk_mul_f32 v[118:119], v[96:97], s[20:21]
	s_nop 0
	v_pk_fma_f32 v[96:97], v[96:97], s[18:19], v[118:119] op_sel:[0,0,1] op_sel_hi:[1,0,0]
	v_pk_add_f32 v[118:119], v[110:111], v[72:73]
	v_pk_add_f32 v[72:73], v[110:111], v[72:73] neg_lo:[0,1] neg_hi:[0,1]
	s_nop 0
	v_pk_mul_f32 v[110:111], v[72:73], s[6:7]
	s_nop 0
	v_pk_fma_f32 v[72:73], v[72:73], s[4:5], v[110:111] op_sel:[0,0,1] op_sel_hi:[1,0,0]
	v_pk_add_f32 v[110:111], v[102:103], v[76:77]
	v_pk_add_f32 v[76:77], v[102:103], v[76:77] neg_lo:[0,1] neg_hi:[0,1]
	s_nop 0
	v_pk_mul_f32 v[102:103], v[76:77], s[24:25]
	s_nop 0
	v_pk_fma_f32 v[76:77], v[76:77], s[22:23], v[102:103] op_sel:[0,0,1] op_sel_hi:[1,0,0]
	v_pk_add_f32 v[102:103], v[120:121], v[66:67]
	v_pk_add_f32 v[66:67], v[120:121], v[66:67] neg_lo:[0,1] neg_hi:[0,1]
	s_nop 0
	v_pk_mul_f32 v[120:121], v[66:67], s[10:11]
	s_nop 0
	v_pk_fma_f32 v[66:67], v[66:67], s[8:9], v[120:121] op_sel:[0,0,1] op_sel_hi:[1,0,0]
	v_pk_add_f32 v[120:121], v[126:127], v[88:89]
	v_pk_add_f32 v[88:89], v[126:127], v[88:89] neg_lo:[0,1] neg_hi:[0,1]
	s_nop 0
	v_pk_mul_f32 v[126:127], v[88:89], s[52:53]
	s_nop 0
	v_pk_fma_f32 v[88:89], v[88:89], s[26:27], v[126:127] op_sel:[0,0,1] op_sel_hi:[1,0,0]
	v_pk_add_f32 v[126:127], v[112:113], v[70:71]
	v_pk_add_f32 v[70:71], v[112:113], v[70:71] neg_lo:[0,1] neg_hi:[0,1]
	s_nop 0
	v_pk_mul_f32 v[112:113], v[70:71], s[14:15]
	s_nop 0
	v_pk_fma_f32 v[70:71], v[70:71], s[12:13], v[112:113] op_sel:[0,0,1] op_sel_hi:[1,0,0]
	v_pk_add_f32 v[112:113], v[130:131], v[78:79]
	v_pk_add_f32 v[78:79], v[130:131], v[78:79] neg_lo:[0,1] neg_hi:[0,1]
	s_nop 0
	v_pk_mul_f32 v[130:131], v[78:79], s[50:51]
	s_nop 0
	v_pk_fma_f32 v[78:79], v[78:79], s[34:35], v[130:131] op_sel:[0,0,1] op_sel_hi:[1,0,0]
	v_pk_add_f32 v[130:131], v[114:115], v[132:133]
	v_pk_add_f32 v[114:115], v[114:115], v[132:133] neg_lo:[0,1] neg_hi:[0,1]
	v_pk_add_f32 v[132:133], v[128:129], v[68:69]
	v_pk_add_f32 v[68:69], v[128:129], v[68:69] neg_lo:[0,1] neg_hi:[0,1]
	s_nop 0
	v_pk_mul_f32 v[128:129], v[68:69], s[14:15]
	s_nop 0
	v_pk_fma_f32 v[68:69], v[68:69], s[6:7], v[128:129] op_sel:[0,0,1] op_sel_hi:[1,0,0]
	v_pk_add_f32 v[128:129], v[106:107], v[118:119]
	v_pk_add_f32 v[106:107], v[106:107], v[118:119] neg_lo:[0,1] neg_hi:[0,1]
	s_nop 0
	v_pk_mul_f32 v[118:119], v[106:107], s[10:11]
	s_nop 0
	v_pk_fma_f32 v[106:107], v[106:107], s[10:11], v[118:119] op_sel:[0,0,1] op_sel_hi:[1,0,0]
	v_pk_add_f32 v[118:119], v[122:123], v[110:111]
	v_pk_add_f32 v[110:111], v[122:123], v[110:111] neg_lo:[0,1] neg_hi:[0,1]
	s_nop 0
	v_pk_mul_f32 v[122:123], v[110:111], s[6:7]
	s_nop 0
	v_pk_fma_f32 v[110:111], v[110:111], s[14:15], v[122:123] op_sel:[0,0,1] op_sel_hi:[1,0,0]
	v_pk_add_f32 v[122:123], v[84:85], v[102:103]
	v_pk_add_f32 v[102:103], v[84:85], v[102:103] op_sel:[1,1] op_sel_hi:[0,0] neg_lo:[1,0] neg_hi:[0,1]
	s_nop 0
	v_pk_add_f32 v[84:85], v[98:99], v[120:121]
	v_pk_add_f32 v[98:99], v[98:99], v[120:121] neg_lo:[0,1] neg_hi:[0,1]
	s_nop 0
	v_pk_mul_f32 v[120:121], v[98:99], s[6:7]
	s_nop 0
	v_pk_fma_f32 v[98:99], v[98:99], s[4:5], v[120:121] op_sel:[0,0,1] op_sel_hi:[1,0,0]
	v_pk_add_f32 v[120:121], v[94:95], v[126:127]
	v_pk_add_f32 v[94:95], v[94:95], v[126:127] neg_lo:[0,1] neg_hi:[0,1]
	s_nop 0
	v_pk_mul_f32 v[126:127], v[94:95], s[10:11]
	s_nop 0
	v_pk_fma_f32 v[94:95], v[94:95], s[8:9], v[126:127] op_sel:[0,0,1] op_sel_hi:[1,0,0]
	v_pk_add_f32 v[126:127], v[124:125], v[112:113]
	v_pk_add_f32 v[112:113], v[124:125], v[112:113] neg_lo:[0,1] neg_hi:[0,1]
	s_nop 0
	v_pk_mul_f32 v[124:125], v[112:113], s[14:15]
	s_nop 0
	v_pk_fma_f32 v[112:113], v[112:113], s[12:13], v[124:125] op_sel:[0,0,1] op_sel_hi:[1,0,0]
	v_pk_add_f32 v[124:125], v[80:81], v[116:117]
	v_pk_add_f32 v[80:81], v[80:81], v[116:117] neg_lo:[0,1] neg_hi:[0,1]
	v_pk_add_f32 v[116:117], v[82:83], v[96:97]
	v_pk_add_f32 v[82:83], v[82:83], v[96:97] neg_lo:[0,1] neg_hi:[0,1]
	s_nop 0
	v_pk_mul_f32 v[96:97], v[82:83], s[14:15]
	s_nop 0
	v_pk_fma_f32 v[82:83], v[82:83], s[6:7], v[96:97] op_sel:[0,0,1] op_sel_hi:[1,0,0]
	v_pk_add_f32 v[96:97], v[108:109], v[72:73]
	v_pk_add_f32 v[72:73], v[108:109], v[72:73] neg_lo:[0,1] neg_hi:[0,1]
	s_nop 0
	v_pk_mul_f32 v[108:109], v[72:73], s[10:11]
	s_nop 0
	v_pk_fma_f32 v[72:73], v[72:73], s[10:11], v[108:109] op_sel:[0,0,1] op_sel_hi:[1,0,0]
	v_pk_add_f32 v[108:109], v[74:75], v[76:77]
	v_pk_add_f32 v[74:75], v[74:75], v[76:77] neg_lo:[0,1] neg_hi:[0,1]
	s_nop 0
	v_pk_mul_f32 v[76:77], v[74:75], s[6:7]
	s_nop 0
	v_pk_fma_f32 v[74:75], v[74:75], s[14:15], v[76:77] op_sel:[0,0,1] op_sel_hi:[1,0,0]
	v_pk_add_f32 v[76:77], v[86:87], v[66:67]
	v_pk_add_f32 v[86:87], v[86:87], v[66:67] op_sel:[1,1] op_sel_hi:[0,0] neg_lo:[1,0] neg_hi:[0,1]
	s_nop 0
	v_pk_add_f32 v[66:67], v[92:93], v[88:89]
	v_pk_add_f32 v[88:89], v[92:93], v[88:89] neg_lo:[0,1] neg_hi:[0,1]
	s_nop 0
	v_pk_mul_f32 v[92:93], v[88:89], s[6:7]
	s_nop 0
	v_pk_fma_f32 v[88:89], v[88:89], s[4:5], v[92:93] op_sel:[0,0,1] op_sel_hi:[1,0,0]
	v_pk_add_f32 v[92:93], v[100:101], v[70:71]
	v_pk_add_f32 v[70:71], v[100:101], v[70:71] neg_lo:[0,1] neg_hi:[0,1]
	s_nop 0
	v_pk_mul_f32 v[100:101], v[70:71], s[10:11]
	s_nop 0
	v_pk_fma_f32 v[70:71], v[70:71], s[8:9], v[100:101] op_sel:[0,0,1] op_sel_hi:[1,0,0]
	v_pk_add_f32 v[100:101], v[90:91], v[78:79]
	v_pk_add_f32 v[78:79], v[90:91], v[78:79] neg_lo:[0,1] neg_hi:[0,1]
	s_nop 0
	v_pk_mul_f32 v[90:91], v[78:79], s[14:15]
	s_nop 0
	v_pk_fma_f32 v[78:79], v[78:79], s[12:13], v[90:91] op_sel:[0,0,1] op_sel_hi:[1,0,0]
	v_pk_add_f32 v[90:91], v[130:131], v[122:123]
	v_pk_add_f32 v[122:123], v[130:131], v[122:123] neg_lo:[0,1] neg_hi:[0,1]
	v_pk_add_f32 v[130:131], v[132:133], v[84:85]
	v_pk_add_f32 v[84:85], v[132:133], v[84:85] neg_lo:[0,1] neg_hi:[0,1]
	s_nop 0
	v_pk_mul_f32 v[132:133], v[84:85], s[10:11]
	s_nop 0
	v_pk_fma_f32 v[84:85], v[84:85], s[10:11], v[132:133] op_sel:[0,0,1] op_sel_hi:[1,0,0]
	v_pk_add_f32 v[132:133], v[128:129], v[120:121]
	v_pk_add_f32 v[128:129], v[128:129], v[120:121] op_sel:[1,1] op_sel_hi:[0,0] neg_lo:[1,0] neg_hi:[0,1]
	s_nop 0
	v_pk_add_f32 v[120:121], v[118:119], v[126:127]
	v_pk_add_f32 v[118:119], v[118:119], v[126:127] neg_lo:[0,1] neg_hi:[0,1]
	s_nop 0
	v_pk_mul_f32 v[126:127], v[118:119], s[10:11]
	s_nop 0
	v_pk_fma_f32 v[118:119], v[118:119], s[8:9], v[126:127] op_sel:[0,0,1] op_sel_hi:[1,0,0]
	v_pk_add_f32 v[126:127], v[114:115], v[102:103]
	v_pk_add_f32 v[102:103], v[114:115], v[102:103] neg_lo:[0,1] neg_hi:[0,1]
	v_pk_add_f32 v[114:115], v[68:69], v[98:99]
	v_pk_add_f32 v[68:69], v[68:69], v[98:99] neg_lo:[0,1] neg_hi:[0,1]
	s_nop 0
	v_pk_mul_f32 v[98:99], v[68:69], s[10:11]
	s_nop 0
	v_pk_fma_f32 v[68:69], v[68:69], s[10:11], v[98:99] op_sel:[0,0,1] op_sel_hi:[1,0,0]
	v_pk_add_f32 v[98:99], v[106:107], v[94:95]
	v_pk_add_f32 v[106:107], v[106:107], v[94:95] op_sel:[1,1] op_sel_hi:[0,0] neg_lo:[1,0] neg_hi:[0,1]
	s_nop 0
	v_pk_add_f32 v[94:95], v[110:111], v[112:113]
	v_pk_add_f32 v[110:111], v[110:111], v[112:113] neg_lo:[0,1] neg_hi:[0,1]
	s_nop 0
	v_pk_mul_f32 v[112:113], v[110:111], s[10:11]
	s_nop 0
	v_pk_fma_f32 v[110:111], v[110:111], s[8:9], v[112:113] op_sel:[0,0,1] op_sel_hi:[1,0,0]
	v_pk_add_f32 v[112:113], v[124:125], v[76:77]
	v_pk_add_f32 v[76:77], v[124:125], v[76:77] neg_lo:[0,1] neg_hi:[0,1]
	v_pk_add_f32 v[124:125], v[116:117], v[66:67]
	v_pk_add_f32 v[66:67], v[116:117], v[66:67] neg_lo:[0,1] neg_hi:[0,1]
	s_nop 0
	v_pk_mul_f32 v[116:117], v[66:67], s[10:11]
	s_nop 0
	v_pk_fma_f32 v[66:67], v[66:67], s[10:11], v[116:117] op_sel:[0,0,1] op_sel_hi:[1,0,0]
	v_pk_add_f32 v[116:117], v[96:97], v[92:93]
	v_pk_add_f32 v[96:97], v[96:97], v[92:93] op_sel:[1,1] op_sel_hi:[0,0] neg_lo:[1,0] neg_hi:[0,1]
	v_pk_add_f32 v[134:135], v[112:113], v[116:117]
	v_pk_add_f32 v[92:93], v[108:109], v[100:101]
	v_pk_add_f32 v[100:101], v[108:109], v[100:101] neg_lo:[0,1] neg_hi:[0,1]
	v_pk_add_f32 v[112:113], v[112:113], v[116:117] neg_lo:[0,1] neg_hi:[0,1]
	v_pk_mul_f32 v[108:109], v[100:101], s[10:11]
	v_pk_add_f32 v[116:117], v[124:125], v[92:93]
	v_pk_fma_f32 v[100:101], v[100:101], s[8:9], v[108:109] op_sel:[0,0,1] op_sel_hi:[1,0,0]
	v_pk_add_f32 v[108:109], v[80:81], v[86:87]
	v_pk_add_f32 v[80:81], v[80:81], v[86:87] neg_lo:[0,1] neg_hi:[0,1]
	v_pk_add_f32 v[86:87], v[82:83], v[88:89]
	v_pk_add_f32 v[82:83], v[82:83], v[88:89] neg_lo:[0,1] neg_hi:[0,1]
	s_nop 0
	v_pk_mul_f32 v[88:89], v[82:83], s[10:11]
	s_nop 0
	v_pk_fma_f32 v[82:83], v[82:83], s[10:11], v[88:89] op_sel:[0,0,1] op_sel_hi:[1,0,0]
	v_pk_add_f32 v[88:89], v[72:73], v[70:71]
	v_pk_add_f32 v[72:73], v[72:73], v[70:71] op_sel:[1,1] op_sel_hi:[0,0] neg_lo:[1,0] neg_hi:[0,1]
	v_pk_add_f32 v[136:137], v[108:109], v[88:89]
	v_pk_add_f32 v[70:71], v[74:75], v[78:79]
	v_pk_add_f32 v[74:75], v[74:75], v[78:79] neg_lo:[0,1] neg_hi:[0,1]
	v_pk_add_f32 v[88:89], v[108:109], v[88:89] neg_lo:[0,1] neg_hi:[0,1]
	v_pk_mul_f32 v[78:79], v[74:75], s[10:11]
	v_pk_add_f32 v[108:109], v[86:87], v[70:71]
	v_pk_fma_f32 v[74:75], v[74:75], s[8:9], v[78:79] op_sel:[0,0,1] op_sel_hi:[1,0,0]
	v_pk_add_f32 v[78:79], v[90:91], v[132:133]
	v_pk_add_f32 v[90:91], v[90:91], v[132:133] neg_lo:[0,1] neg_hi:[0,1]
	v_pk_add_f32 v[132:133], v[130:131], v[120:121]
	v_pk_add_f32 v[130:131], v[130:131], v[120:121] op_sel:[1,1] op_sel_hi:[0,0] neg_lo:[1,0] neg_hi:[0,1]
	v_pk_add_f32 v[138:139], v[80:81], v[72:73] neg_lo:[0,1] neg_hi:[0,1]
	v_pk_add_f32 v[120:121], v[122:123], v[128:129]
	v_pk_add_f32 v[122:123], v[122:123], v[128:129] neg_lo:[0,1] neg_hi:[0,1]
	v_pk_add_f32 v[128:129], v[84:85], v[118:119]
	v_pk_add_f32 v[118:119], v[84:85], v[118:119] op_sel:[1,1] op_sel_hi:[0,0] neg_lo:[1,0] neg_hi:[0,1]
	v_pk_add_f32 v[140:141], v[82:83], v[74:75]
	v_pk_add_f32 v[84:85], v[126:127], v[98:99]
	v_pk_add_f32 v[98:99], v[126:127], v[98:99] neg_lo:[0,1] neg_hi:[0,1]
	v_pk_add_f32 v[126:127], v[114:115], v[94:95]
	v_pk_add_f32 v[114:115], v[114:115], v[94:95] op_sel:[1,1] op_sel_hi:[0,0] neg_lo:[1,0] neg_hi:[0,1]
	v_pk_add_f32 v[142:143], v[78:79], v[132:133]
	v_pk_add_f32 v[94:95], v[102:103], v[106:107]
	v_pk_add_f32 v[102:103], v[102:103], v[106:107] neg_lo:[0,1] neg_hi:[0,1]
	v_pk_add_f32 v[106:107], v[68:69], v[110:111]
	v_pk_add_f32 v[110:111], v[68:69], v[110:111] op_sel:[1,1] op_sel_hi:[0,0] neg_lo:[1,0] neg_hi:[0,1]
	v_pk_add_f32 v[132:133], v[78:79], v[132:133] neg_lo:[0,1] neg_hi:[0,1]
	v_pk_add_f32 v[92:93], v[124:125], v[92:93] op_sel:[1,1] op_sel_hi:[0,0] neg_lo:[1,0] neg_hi:[0,1]
	v_pk_add_f32 v[124:125], v[76:77], v[96:97]
	v_pk_add_f32 v[76:77], v[76:77], v[96:97] neg_lo:[0,1] neg_hi:[0,1]
	v_pk_add_f32 v[96:97], v[66:67], v[100:101]
	v_pk_add_f32 v[100:101], v[66:67], v[100:101] op_sel:[1,1] op_sel_hi:[0,0] neg_lo:[1,0] neg_hi:[0,1]
	v_pk_add_f32 v[70:71], v[86:87], v[70:71] op_sel:[1,1] op_sel_hi:[0,0] neg_lo:[1,0] neg_hi:[0,1]
	v_pk_add_f32 v[74:75], v[82:83], v[74:75] op_sel:[1,1] op_sel_hi:[0,0] neg_lo:[1,0] neg_hi:[0,1]
	v_pk_add_f32 v[86:87], v[80:81], v[72:73]
	v_pk_add_f32 v[144:145], v[90:91], v[130:131]
	v_pk_add_f32 v[82:83], v[90:91], v[130:131] neg_lo:[0,1] neg_hi:[0,1]
	v_pk_add_f32 v[90:91], v[120:121], v[128:129]
	v_pk_add_f32 v[120:121], v[120:121], v[128:129] neg_lo:[0,1] neg_hi:[0,1]
	v_pk_add_f32 v[128:129], v[122:123], v[118:119]
	v_pk_add_f32 v[68:69], v[122:123], v[118:119] neg_lo:[0,1] neg_hi:[0,1]
	v_pk_add_f32 v[118:119], v[84:85], v[126:127]
	v_pk_add_f32 v[122:123], v[84:85], v[126:127] neg_lo:[0,1] neg_hi:[0,1]
	v_pk_add_f32 v[126:127], v[98:99], v[114:115]
	v_pk_add_f32 v[78:79], v[98:99], v[114:115] neg_lo:[0,1] neg_hi:[0,1]
	v_pk_add_f32 v[98:99], v[94:95], v[106:107]
	v_pk_add_f32 v[94:95], v[94:95], v[106:107] neg_lo:[0,1] neg_hi:[0,1]
	v_pk_add_f32 v[106:107], v[102:103], v[110:111]
	v_pk_add_f32 v[66:67], v[102:103], v[110:111] neg_lo:[0,1] neg_hi:[0,1]
	v_pk_add_f32 v[102:103], v[134:135], v[116:117]
	v_pk_add_f32 v[110:111], v[134:135], v[116:117] neg_lo:[0,1] neg_hi:[0,1]
	v_pk_add_f32 v[116:117], v[88:89], v[70:71]
	v_pk_add_f32 v[80:81], v[88:89], v[70:71] neg_lo:[0,1] neg_hi:[0,1]
	v_lshlrev_b32_e32 v70, 4, v0
	v_and_b32_e32 v70, 0x1f0, v70
	v_pk_add_f32 v[114:115], v[112:113], v[92:93]
	v_pk_add_f32 v[84:85], v[112:113], v[92:93] neg_lo:[0,1] neg_hi:[0,1]
	v_pk_add_f32 v[112:113], v[76:77], v[100:101]
	v_pk_add_f32 v[72:73], v[76:77], v[100:101] neg_lo:[0,1] neg_hi:[0,1]
	v_cvt_f32_u32_e32 v76, v70
	v_pk_add_f32 v[92:93], v[124:125], v[96:97]
	v_pk_add_f32 v[96:97], v[124:125], v[96:97] neg_lo:[0,1] neg_hi:[0,1]
	v_pk_add_f32 v[124:125], v[138:139], v[74:75]
	v_mul_f32_e32 v76, 0x38800000, v76
	v_pk_add_f32 v[70:71], v[138:139], v[74:75] neg_lo:[0,1] neg_hi:[0,1]
	v_sin_f32_e32 v75, v76
	v_ashrrev_i32_e32 v74, 2, v105
	v_lshlrev_b32_e32 v0, 8, v0
	v_add3_u32 v0, 0, v74, v0
	v_cos_f32_e32 v74, v76
	v_xor_b32_e32 v76, 0x80000000, v75
	v_mov_b32_e32 v77, v75
	v_pk_mul_f32 v[130:131], v[76:77], v[102:103] op_sel:[0,1] op_sel_hi:[1,0]
	v_pk_add_f32 v[100:101], v[136:137], v[108:109]
	v_pk_fma_f32 v[102:103], v[102:103], v[74:75], v[130:131] op_sel_hi:[1,0,1]
	ds_write2_b64 v0, v[142:143], v[102:103] offset1:1
	v_pk_mul_f32 v[102:103], v[76:77], v[74:75] op_sel:[0,1] op_sel_hi:[1,0]
	v_pk_add_f32 v[88:89], v[86:87], v[140:141]
	v_pk_fma_f32 v[102:103], v[74:75], v[74:75], v[102:103] op_sel_hi:[1,0,1]
	v_pk_add_f32 v[108:109], v[136:137], v[108:109] neg_lo:[0,1] neg_hi:[0,1]
	v_pk_mul_f32 v[130:131], v[118:119], v[102:103] op_sel:[1,1] op_sel_hi:[0,1] neg_lo:[0,1]
	v_pk_fma_f32 v[118:119], v[118:119], v[102:103], v[130:131] op_sel_hi:[1,0,1]
	v_pk_mul_f32 v[130:131], v[76:77], v[102:103] op_sel:[0,1] op_sel_hi:[1,0]
	v_pk_add_f32 v[86:87], v[86:87], v[140:141] neg_lo:[0,1] neg_hi:[0,1]
	v_pk_fma_f32 v[102:103], v[102:103], v[74:75], v[130:131] op_sel_hi:[1,0,1]
	s_nop 0
	v_pk_mul_f32 v[130:131], v[100:101], v[102:103] op_sel:[1,1] op_sel_hi:[0,1] neg_lo:[0,1]
	v_pk_fma_f32 v[100:101], v[100:101], v[102:103], v[130:131] op_sel_hi:[1,0,1]
	ds_write2_b64 v0, v[118:119], v[100:101] offset0:2 offset1:3
	v_pk_mul_f32 v[100:101], v[76:77], v[102:103] op_sel:[0,1] op_sel_hi:[1,0]
	s_nop 0
	v_pk_fma_f32 v[100:101], v[102:103], v[74:75], v[100:101] op_sel_hi:[1,0,1]
	s_nop 0
	v_pk_mul_f32 v[102:103], v[90:91], v[100:101] op_sel:[1,1] op_sel_hi:[0,1] neg_lo:[0,1]
	v_pk_fma_f32 v[90:91], v[90:91], v[100:101], v[102:103] op_sel_hi:[1,0,1]
	v_pk_mul_f32 v[102:103], v[76:77], v[100:101] op_sel:[0,1] op_sel_hi:[1,0]
	s_nop 0
	v_pk_fma_f32 v[100:101], v[100:101], v[74:75], v[102:103] op_sel_hi:[1,0,1]
	s_nop 0
	v_pk_mul_f32 v[102:103], v[92:93], v[100:101] op_sel:[1,1] op_sel_hi:[0,1] neg_lo:[0,1]
	v_pk_fma_f32 v[92:93], v[92:93], v[100:101], v[102:103] op_sel_hi:[1,0,1]
	ds_write2_b64 v0, v[90:91], v[92:93] offset0:4 offset1:5
	v_pk_mul_f32 v[90:91], v[76:77], v[100:101] op_sel:[0,1] op_sel_hi:[1,0]
	s_nop 0
	v_pk_fma_f32 v[90:91], v[100:101], v[74:75], v[90:91] op_sel_hi:[1,0,1]
	s_nop 0
	v_pk_mul_f32 v[92:93], v[98:99], v[90:91] op_sel:[1,1] op_sel_hi:[0,1] neg_lo:[0,1]
	v_pk_fma_f32 v[92:93], v[98:99], v[90:91], v[92:93] op_sel_hi:[1,0,1]
	v_pk_mul_f32 v[98:99], v[76:77], v[90:91] op_sel:[0,1] op_sel_hi:[1,0]
	s_nop 0
	v_pk_fma_f32 v[90:91], v[90:91], v[74:75], v[98:99] op_sel_hi:[1,0,1]
	s_nop 0
	v_pk_mul_f32 v[98:99], v[88:89], v[90:91] op_sel:[1,1] op_sel_hi:[0,1] neg_lo:[0,1]
	v_pk_fma_f32 v[88:89], v[88:89], v[90:91], v[98:99] op_sel_hi:[1,0,1]
	ds_write2_b64 v0, v[92:93], v[88:89] offset0:6 offset1:7
	v_pk_mul_f32 v[88:89], v[76:77], v[90:91] op_sel:[0,1] op_sel_hi:[1,0]
	s_nop 0
	v_pk_fma_f32 v[88:89], v[90:91], v[74:75], v[88:89] op_sel_hi:[1,0,1]
	s_nop 0
	v_pk_mul_f32 v[90:91], v[144:145], v[88:89] op_sel:[1,1] op_sel_hi:[0,1] neg_lo:[0,1]
	v_pk_mul_f32 v[92:93], v[76:77], v[88:89] op_sel:[0,1] op_sel_hi:[1,0]
	v_pk_fma_f32 v[90:91], v[144:145], v[88:89], v[90:91] op_sel_hi:[1,0,1]
	v_pk_fma_f32 v[88:89], v[88:89], v[74:75], v[92:93] op_sel_hi:[1,0,1]
	s_nop 0
	v_pk_mul_f32 v[92:93], v[114:115], v[88:89] op_sel:[1,1] op_sel_hi:[0,1] neg_lo:[0,1]
	v_pk_fma_f32 v[92:93], v[114:115], v[88:89], v[92:93] op_sel_hi:[1,0,1]
	ds_write2_b64 v0, v[90:91], v[92:93] offset0:8 offset1:9
	v_pk_mul_f32 v[90:91], v[76:77], v[88:89] op_sel:[0,1] op_sel_hi:[1,0]
	s_nop 0
	v_pk_fma_f32 v[88:89], v[88:89], v[74:75], v[90:91] op_sel_hi:[1,0,1]
	s_nop 0
	v_pk_mul_f32 v[90:91], v[126:127], v[88:89] op_sel:[1,1] op_sel_hi:[0,1] neg_lo:[0,1]
	v_pk_mul_f32 v[92:93], v[76:77], v[88:89] op_sel:[0,1] op_sel_hi:[1,0]
	v_pk_fma_f32 v[90:91], v[126:127], v[88:89], v[90:91] op_sel_hi:[1,0,1]
	v_pk_fma_f32 v[88:89], v[88:89], v[74:75], v[92:93] op_sel_hi:[1,0,1]
	s_nop 0
	v_pk_mul_f32 v[92:93], v[116:117], v[88:89] op_sel:[1,1] op_sel_hi:[0,1] neg_lo:[0,1]
	v_pk_fma_f32 v[92:93], v[116:117], v[88:89], v[92:93] op_sel_hi:[1,0,1]
	ds_write2_b64 v0, v[90:91], v[92:93] offset0:10 offset1:11
	v_pk_mul_f32 v[90:91], v[76:77], v[88:89] op_sel:[0,1] op_sel_hi:[1,0]
	s_nop 0
	v_pk_fma_f32 v[88:89], v[88:89], v[74:75], v[90:91] op_sel_hi:[1,0,1]
	s_nop 0
	v_pk_mul_f32 v[90:91], v[128:129], v[88:89] op_sel:[1,1] op_sel_hi:[0,1] neg_lo:[0,1]
	v_pk_mul_f32 v[92:93], v[76:77], v[88:89] op_sel:[0,1] op_sel_hi:[1,0]
	v_pk_fma_f32 v[90:91], v[128:129], v[88:89], v[90:91] op_sel_hi:[1,0,1]
	v_pk_fma_f32 v[88:89], v[88:89], v[74:75], v[92:93] op_sel_hi:[1,0,1]
	s_nop 0
	v_pk_mul_f32 v[92:93], v[112:113], v[88:89] op_sel:[1,1] op_sel_hi:[0,1] neg_lo:[0,1]
	v_pk_fma_f32 v[92:93], v[112:113], v[88:89], v[92:93] op_sel_hi:[1,0,1]
	ds_write2_b64 v0, v[90:91], v[92:93] offset0:12 offset1:13
	v_pk_mul_f32 v[90:91], v[76:77], v[88:89] op_sel:[0,1] op_sel_hi:[1,0]
	s_nop 0
	v_pk_fma_f32 v[88:89], v[88:89], v[74:75], v[90:91] op_sel_hi:[1,0,1]
	s_nop 0
	v_pk_mul_f32 v[90:91], v[106:107], v[88:89] op_sel:[1,1] op_sel_hi:[0,1] neg_lo:[0,1]
	v_pk_mul_f32 v[92:93], v[76:77], v[88:89] op_sel:[0,1] op_sel_hi:[1,0]
	v_pk_fma_f32 v[90:91], v[106:107], v[88:89], v[90:91] op_sel_hi:[1,0,1]
	v_pk_fma_f32 v[88:89], v[88:89], v[74:75], v[92:93] op_sel_hi:[1,0,1]
	s_nop 0
	v_pk_mul_f32 v[92:93], v[124:125], v[88:89] op_sel:[1,1] op_sel_hi:[0,1] neg_lo:[0,1]
	v_pk_fma_f32 v[92:93], v[124:125], v[88:89], v[92:93] op_sel_hi:[1,0,1]
	ds_write2_b64 v0, v[90:91], v[92:93] offset0:14 offset1:15
	v_pk_mul_f32 v[90:91], v[76:77], v[88:89] op_sel:[0,1] op_sel_hi:[1,0]
	s_nop 0
	v_pk_fma_f32 v[88:89], v[88:89], v[74:75], v[90:91] op_sel_hi:[1,0,1]
	s_nop 0
	v_pk_mul_f32 v[90:91], v[132:133], v[88:89] op_sel:[1,1] op_sel_hi:[0,1] neg_lo:[0,1]
	v_pk_mul_f32 v[92:93], v[76:77], v[88:89] op_sel:[0,1] op_sel_hi:[1,0]
	v_pk_fma_f32 v[90:91], v[132:133], v[88:89], v[90:91] op_sel_hi:[1,0,1]
	v_pk_fma_f32 v[88:89], v[88:89], v[74:75], v[92:93] op_sel_hi:[1,0,1]
	s_nop 0
	v_pk_mul_f32 v[92:93], v[110:111], v[88:89] op_sel:[1,1] op_sel_hi:[0,1] neg_lo:[0,1]
	v_pk_fma_f32 v[92:93], v[110:111], v[88:89], v[92:93] op_sel_hi:[1,0,1]
	ds_write2_b64 v0, v[90:91], v[92:93] offset0:16 offset1:17
	v_pk_mul_f32 v[90:91], v[76:77], v[88:89] op_sel:[0,1] op_sel_hi:[1,0]
	s_nop 0
	v_pk_fma_f32 v[88:89], v[88:89], v[74:75], v[90:91] op_sel_hi:[1,0,1]
	s_nop 0
	v_pk_mul_f32 v[90:91], v[122:123], v[88:89] op_sel:[1,1] op_sel_hi:[0,1] neg_lo:[0,1]
	v_pk_mul_f32 v[92:93], v[76:77], v[88:89] op_sel:[0,1] op_sel_hi:[1,0]
	v_pk_fma_f32 v[90:91], v[122:123], v[88:89], v[90:91] op_sel_hi:[1,0,1]
	v_pk_fma_f32 v[88:89], v[88:89], v[74:75], v[92:93] op_sel_hi:[1,0,1]
	s_nop 0
	v_pk_mul_f32 v[92:93], v[108:109], v[88:89] op_sel:[1,1] op_sel_hi:[0,1] neg_lo:[0,1]
	v_pk_fma_f32 v[92:93], v[108:109], v[88:89], v[92:93] op_sel_hi:[1,0,1]
	ds_write2_b64 v0, v[90:91], v[92:93] offset0:18 offset1:19
	v_pk_mul_f32 v[90:91], v[76:77], v[88:89] op_sel:[0,1] op_sel_hi:[1,0]
	s_nop 0
	v_pk_fma_f32 v[88:89], v[88:89], v[74:75], v[90:91] op_sel_hi:[1,0,1]
	s_nop 0
	v_pk_mul_f32 v[90:91], v[120:121], v[88:89] op_sel:[1,1] op_sel_hi:[0,1] neg_lo:[0,1]
	v_pk_mul_f32 v[92:93], v[76:77], v[88:89] op_sel:[0,1] op_sel_hi:[1,0]
	v_pk_fma_f32 v[90:91], v[120:121], v[88:89], v[90:91] op_sel_hi:[1,0,1]
	v_pk_fma_f32 v[88:89], v[88:89], v[74:75], v[92:93] op_sel_hi:[1,0,1]
	s_nop 0
	v_pk_mul_f32 v[92:93], v[96:97], v[88:89] op_sel:[1,1] op_sel_hi:[0,1] neg_lo:[0,1]
	v_pk_fma_f32 v[92:93], v[96:97], v[88:89], v[92:93] op_sel_hi:[1,0,1]
	ds_write2_b64 v0, v[90:91], v[92:93] offset0:20 offset1:21
	v_pk_mul_f32 v[90:91], v[76:77], v[88:89] op_sel:[0,1] op_sel_hi:[1,0]
	s_nop 0
	v_pk_fma_f32 v[88:89], v[88:89], v[74:75], v[90:91] op_sel_hi:[1,0,1]
	s_nop 0
	v_pk_mul_f32 v[90:91], v[94:95], v[88:89] op_sel:[1,1] op_sel_hi:[0,1] neg_lo:[0,1]
	v_pk_mul_f32 v[92:93], v[76:77], v[88:89] op_sel:[0,1] op_sel_hi:[1,0]
	v_pk_fma_f32 v[90:91], v[94:95], v[88:89], v[90:91] op_sel_hi:[1,0,1]
	v_pk_fma_f32 v[88:89], v[88:89], v[74:75], v[92:93] op_sel_hi:[1,0,1]
	s_nop 0
	v_pk_mul_f32 v[92:93], v[86:87], v[88:89] op_sel:[1,1] op_sel_hi:[0,1] neg_lo:[0,1]
	v_pk_fma_f32 v[86:87], v[86:87], v[88:89], v[92:93] op_sel_hi:[1,0,1]
	ds_write2_b64 v0, v[90:91], v[86:87] offset0:22 offset1:23
	v_pk_mul_f32 v[86:87], v[76:77], v[88:89] op_sel:[0,1] op_sel_hi:[1,0]
	s_nop 0
	v_pk_fma_f32 v[86:87], v[88:89], v[74:75], v[86:87] op_sel_hi:[1,0,1]
	s_nop 0
	v_pk_mul_f32 v[88:89], v[82:83], v[86:87] op_sel:[1,1] op_sel_hi:[0,1] neg_lo:[0,1]
	v_pk_fma_f32 v[82:83], v[82:83], v[86:87], v[88:89] op_sel_hi:[1,0,1]
	v_pk_mul_f32 v[88:89], v[76:77], v[86:87] op_sel:[0,1] op_sel_hi:[1,0]
	s_nop 0
	v_pk_fma_f32 v[86:87], v[86:87], v[74:75], v[88:89] op_sel_hi:[1,0,1]
	s_nop 0
	v_pk_mul_f32 v[88:89], v[84:85], v[86:87] op_sel:[1,1] op_sel_hi:[0,1] neg_lo:[0,1]
	v_pk_fma_f32 v[84:85], v[84:85], v[86:87], v[88:89] op_sel_hi:[1,0,1]
	ds_write2_b64 v0, v[82:83], v[84:85] offset0:24 offset1:25
	v_pk_mul_f32 v[82:83], v[76:77], v[86:87] op_sel:[0,1] op_sel_hi:[1,0]
	s_nop 0
	v_pk_fma_f32 v[82:83], v[86:87], v[74:75], v[82:83] op_sel_hi:[1,0,1]
	s_nop 0
	v_pk_mul_f32 v[84:85], v[78:79], v[82:83] op_sel:[1,1] op_sel_hi:[0,1] neg_lo:[0,1]
	v_pk_fma_f32 v[78:79], v[78:79], v[82:83], v[84:85] op_sel_hi:[1,0,1]
	v_pk_mul_f32 v[84:85], v[76:77], v[82:83] op_sel:[0,1] op_sel_hi:[1,0]
	s_nop 0
	v_pk_fma_f32 v[82:83], v[82:83], v[74:75], v[84:85] op_sel_hi:[1,0,1]
	s_nop 0
	v_pk_mul_f32 v[84:85], v[80:81], v[82:83] op_sel:[1,1] op_sel_hi:[0,1] neg_lo:[0,1]
	v_pk_fma_f32 v[80:81], v[80:81], v[82:83], v[84:85] op_sel_hi:[1,0,1]
	ds_write2_b64 v0, v[78:79], v[80:81] offset0:26 offset1:27
	v_pk_mul_f32 v[78:79], v[76:77], v[82:83] op_sel:[0,1] op_sel_hi:[1,0]
	s_nop 0
	v_pk_fma_f32 v[78:79], v[82:83], v[74:75], v[78:79] op_sel_hi:[1,0,1]
	s_nop 0
	v_pk_mul_f32 v[80:81], v[68:69], v[78:79] op_sel:[1,1] op_sel_hi:[0,1] neg_lo:[0,1]
	v_pk_fma_f32 v[68:69], v[68:69], v[78:79], v[80:81] op_sel_hi:[1,0,1]
	v_pk_mul_f32 v[80:81], v[76:77], v[78:79] op_sel:[0,1] op_sel_hi:[1,0]
	s_nop 0
	v_pk_fma_f32 v[78:79], v[78:79], v[74:75], v[80:81] op_sel_hi:[1,0,1]
	s_nop 0
	v_pk_mul_f32 v[80:81], v[72:73], v[78:79] op_sel:[1,1] op_sel_hi:[0,1] neg_lo:[0,1]
	v_pk_fma_f32 v[72:73], v[72:73], v[78:79], v[80:81] op_sel_hi:[1,0,1]
	ds_write2_b64 v0, v[68:69], v[72:73] offset0:28 offset1:29
	v_pk_mul_f32 v[68:69], v[76:77], v[78:79] op_sel:[0,1] op_sel_hi:[1,0]
	s_nop 0
	v_pk_fma_f32 v[68:69], v[78:79], v[74:75], v[68:69] op_sel_hi:[1,0,1]
	s_nop 0
	v_pk_mul_f32 v[72:73], v[66:67], v[68:69] op_sel:[1,1] op_sel_hi:[0,1] neg_lo:[0,1]
	v_pk_fma_f32 v[66:67], v[66:67], v[68:69], v[72:73] op_sel_hi:[1,0,1]
	v_pk_mul_f32 v[72:73], v[76:77], v[68:69] op_sel:[0,1] op_sel_hi:[1,0]
	s_nop 0
	v_pk_fma_f32 v[68:69], v[68:69], v[74:75], v[72:73] op_sel_hi:[1,0,1]
	s_nop 0
	v_pk_mul_f32 v[72:73], v[70:71], v[68:69] op_sel:[1,1] op_sel_hi:[0,1] neg_lo:[0,1]
	v_pk_fma_f32 v[68:69], v[70:71], v[68:69], v[72:73] op_sel_hi:[1,0,1]
	ds_write2_b64 v0, v[66:67], v[68:69] offset0:30 offset1:31
	s_waitcnt lgkmcnt(0)
	s_barrier
	v_mov_b32 v0, 0
	s_nop 0
	v_add_u32_e32 v71, v0, v170
	v_ashrrev_i32_e32 v105, 5, v71
	v_lshlrev_b32_e32 v0, 10, v105
	v_and_b32_e32 v140, 31, v71
	v_ashrrev_i32_e32 v0, 2, v0
	v_lshlrev_b32_e32 v67, 13, v105
	v_lshlrev_b32_e32 v68, 3, v140
	v_add_u32_e32 v0, 0, v0
	v_lshl_add_u32 v66, v105, 8, 0
	v_add3_u32 v0, v0, v67, v68
	v_add3_u32 v142, v66, v67, v68
	v_add_u32_e32 v143, 0x400, v0
	v_add_u32_e32 v144, 0x800, v0
	v_add_u32_e32 v145, 0xc00, v0
	ds_read_b64 v[130:131], v142
	ds_read2_b64 v[66:69], v0 offset0:33 offset1:66
	ds_read2_b64 v[72:75], v0 offset0:99 offset1:132
	ds_read2_b64 v[76:79], v0 offset0:165 offset1:198
	ds_read2_b64 v[80:83], v143 offset0:103 offset1:136
	ds_read2_b64 v[84:87], v144 offset0:41 offset1:74
	ds_read2_b64 v[88:91], v144 offset0:107 offset1:140
	ds_read2_b64 v[92:95], v144 offset0:173 offset1:206
	ds_read2_b64 v[96:99], v145 offset0:111 offset1:144
	v_add_u32_e32 v146, 0x1000, v0
	ds_read2_b64 v[100:103], v146 offset0:49 offset1:82
	ds_read2_b64 v[106:109], v146 offset0:115 offset1:148
	ds_read2_b64 v[110:113], v146 offset0:181 offset1:214
	v_add_u32_e32 v147, 0x1400, v0
	ds_read2_b64 v[114:117], v147 offset0:119 offset1:152
	s_waitcnt lgkmcnt(4)
	v_pk_add_f32 v[134:135], v[130:131], v[98:99]
	v_pk_add_f32 v[98:99], v[130:131], v[98:99] neg_lo:[0,1] neg_hi:[0,1]
	s_waitcnt lgkmcnt(3)
	v_pk_add_f32 v[130:131], v[66:67], v[100:101]
	v_pk_add_f32 v[66:67], v[66:67], v[100:101] neg_lo:[0,1] neg_hi:[0,1]
	v_add_u32_e32 v70, 0x1800, v0
	v_pk_mul_f32 v[100:101], v[66:67], s[50:51]
	ds_read2_b64 v[118:121], v70 offset0:57 offset1:90
	ds_read2_b64 v[122:125], v70 offset0:123 offset1:156
	ds_read2_b64 v[126:129], v70 offset0:189 offset1:222
	ds_read_b64 v[132:133], v0 offset:8184
	v_pk_fma_f32 v[66:67], v[66:67], s[20:21], v[100:101] op_sel:[0,0,1] op_sel_hi:[1,0,0]
	v_pk_add_f32 v[100:101], v[68:69], v[102:103]
	v_pk_add_f32 v[68:69], v[68:69], v[102:103] neg_lo:[0,1] neg_hi:[0,1]
	v_mul_lo_u32 v105, v140, v105
	v_pk_mul_f32 v[102:103], v[68:69], s[14:15]
	v_cvt_f32_i32_e32 v105, v105
	v_pk_fma_f32 v[68:69], v[68:69], s[6:7], v[102:103] op_sel:[0,0,1] op_sel_hi:[1,0,0]
	s_waitcnt lgkmcnt(6)
	v_pk_add_f32 v[102:103], v[72:73], v[106:107]
	v_pk_add_f32 v[72:73], v[72:73], v[106:107] neg_lo:[0,1] neg_hi:[0,1]
	v_and_b32_e32 v71, 0xffffffe0, v71
	v_pk_mul_f32 v[106:107], v[72:73], s[52:53]
	v_cvt_f32_i32_e32 v71, v71
	v_pk_fma_f32 v[72:73], v[72:73], s[24:25], v[106:107] op_sel:[0,0,1] op_sel_hi:[1,0,0]
	v_pk_add_f32 v[106:107], v[74:75], v[108:109]
	v_pk_add_f32 v[74:75], v[74:75], v[108:109] neg_lo:[0,1] neg_hi:[0,1]
	v_mul_f32_e32 v71, 0x38800000, v71
	v_pk_mul_f32 v[108:109], v[74:75], s[10:11]
	s_nop 0
	v_pk_fma_f32 v[74:75], v[74:75], s[10:11], v[108:109] op_sel:[0,0,1] op_sel_hi:[1,0,0]
	s_waitcnt lgkmcnt(5)
	v_pk_add_f32 v[108:109], v[76:77], v[110:111]
	v_pk_add_f32 v[76:77], v[76:77], v[110:111] neg_lo:[0,1] neg_hi:[0,1]
	s_nop 0
	v_pk_mul_f32 v[110:111], v[76:77], s[24:25]
	s_nop 0
	v_pk_fma_f32 v[76:77], v[76:77], s[0:1], v[110:111] op_sel:[0,0,1] op_sel_hi:[1,0,0]
	v_pk_add_f32 v[110:111], v[78:79], v[112:113]
	v_pk_add_f32 v[78:79], v[78:79], v[112:113] neg_lo:[0,1] neg_hi:[0,1]
	s_nop 0
	v_pk_mul_f32 v[112:113], v[78:79], s[6:7]
	s_nop 0
	v_pk_fma_f32 v[78:79], v[78:79], s[14:15], v[112:113] op_sel:[0,0,1] op_sel_hi:[1,0,0]
	s_waitcnt lgkmcnt(4)
	v_pk_add_f32 v[112:113], v[80:81], v[114:115]
	v_pk_add_f32 v[80:81], v[80:81], v[114:115] neg_lo:[0,1] neg_hi:[0,1]
	s_nop 0
	v_pk_mul_f32 v[114:115], v[80:81], s[20:21]
	s_nop 0
	v_pk_fma_f32 v[80:81], v[80:81], s[48:49], v[114:115] op_sel:[0,0,1] op_sel_hi:[1,0,0]
	v_pk_add_f32 v[114:115], v[82:83], v[116:117]
	v_pk_add_f32 v[116:117], v[82:83], v[116:117] op_sel:[1,1] op_sel_hi:[0,0] neg_lo:[1,0] neg_hi:[0,1]
	s_mov_b64 s[48:49], -1
	s_waitcnt lgkmcnt(3)
	v_pk_add_f32 v[82:83], v[84:85], v[118:119]
	v_pk_add_f32 v[84:85], v[84:85], v[118:119] neg_lo:[0,1] neg_hi:[0,1]
	s_nop 0
	v_pk_mul_f32 v[118:119], v[84:85], s[20:21]
	s_nop 0
	v_pk_fma_f32 v[84:85], v[84:85], s[18:19], v[118:119] op_sel:[0,0,1] op_sel_hi:[1,0,0]
	v_pk_add_f32 v[118:119], v[86:87], v[120:121]
	v_pk_add_f32 v[86:87], v[86:87], v[120:121] neg_lo:[0,1] neg_hi:[0,1]
	s_nop 0
	v_pk_mul_f32 v[120:121], v[86:87], s[6:7]
	s_nop 0
	v_pk_fma_f32 v[86:87], v[86:87], s[4:5], v[120:121] op_sel:[0,0,1] op_sel_hi:[1,0,0]
	s_waitcnt lgkmcnt(2)
	v_pk_add_f32 v[120:121], v[88:89], v[122:123]
	v_pk_add_f32 v[88:89], v[88:89], v[122:123] neg_lo:[0,1] neg_hi:[0,1]
	s_nop 0
	v_pk_mul_f32 v[122:123], v[88:89], s[24:25]
	s_nop 0
	v_pk_fma_f32 v[88:89], v[88:89], s[22:23], v[122:123] op_sel:[0,0,1] op_sel_hi:[1,0,0]
	v_pk_add_f32 v[122:123], v[90:91], v[124:125]
	v_pk_add_f32 v[90:91], v[90:91], v[124:125] neg_lo:[0,1] neg_hi:[0,1]
	s_nop 0
	v_pk_mul_f32 v[124:125], v[90:91], s[10:11]
	s_nop 0
	v_pk_fma_f32 v[90:91], v[90:91], s[8:9], v[124:125] op_sel:[0,0,1] op_sel_hi:[1,0,0]
	s_waitcnt lgkmcnt(1)
	v_pk_add_f32 v[124:125], v[92:93], v[126:127]
	v_pk_add_f32 v[92:93], v[92:93], v[126:127] neg_lo:[0,1] neg_hi:[0,1]
	s_nop 0
	v_pk_mul_f32 v[126:127], v[92:93], s[52:53]
	s_nop 0
	v_pk_fma_f32 v[92:93], v[92:93], s[26:27], v[126:127] op_sel:[0,0,1] op_sel_hi:[1,0,0]
	v_pk_add_f32 v[126:127], v[94:95], v[128:129]
	v_pk_add_f32 v[94:95], v[94:95], v[128:129] neg_lo:[0,1] neg_hi:[0,1]
	s_nop 0
	v_pk_mul_f32 v[128:129], v[94:95], s[14:15]
	s_nop 0
	v_pk_fma_f32 v[94:95], v[94:95], s[12:13], v[128:129] op_sel:[0,0,1] op_sel_hi:[1,0,0]
	s_waitcnt lgkmcnt(0)
	v_pk_add_f32 v[128:129], v[96:97], v[132:133]
	v_pk_add_f32 v[96:97], v[96:97], v[132:133] neg_lo:[0,1] neg_hi:[0,1]
	s_nop 0
	v_pk_mul_f32 v[132:133], v[96:97], s[50:51]
	s_nop 0
	v_pk_fma_f32 v[96:97], v[96:97], s[34:35], v[132:133] op_sel:[0,0,1] op_sel_hi:[1,0,0]
	v_pk_add_f32 v[132:133], v[134:135], v[114:115]
	v_pk_add_f32 v[114:115], v[134:135], v[114:115] neg_lo:[0,1] neg_hi:[0,1]
	v_pk_add_f32 v[134:135], v[130:131], v[82:83]
	v_pk_add_f32 v[82:83], v[130:131], v[82:83] neg_lo:[0,1] neg_hi:[0,1]
	s_nop 0
	v_pk_mul_f32 v[130:131], v[82:83], s[14:15]
	s_nop 0
	v_pk_fma_f32 v[82:83], v[82:83], s[6:7], v[130:131] op_sel:[0,0,1] op_sel_hi:[1,0,0]
	v_pk_add_f32 v[130:131], v[100:101], v[118:119]
	v_pk_add_f32 v[100:101], v[100:101], v[118:119] neg_lo:[0,1] neg_hi:[0,1]
	s_nop 0
	v_pk_mul_f32 v[118:119], v[100:101], s[10:11]
	s_nop 0
	v_pk_fma_f32 v[100:101], v[100:101], s[10:11], v[118:119] op_sel:[0,0,1] op_sel_hi:[1,0,0]
	v_pk_add_f32 v[118:119], v[102:103], v[120:121]
	v_pk_add_f32 v[102:103], v[102:103], v[120:121] neg_lo:[0,1] neg_hi:[0,1]
	s_nop 0
	v_pk_mul_f32 v[120:121], v[102:103], s[6:7]
	s_nop 0
	v_pk_fma_f32 v[102:103], v[102:103], s[14:15], v[120:121] op_sel:[0,0,1] op_sel_hi:[1,0,0]
	v_pk_add_f32 v[120:121], v[106:107], v[122:123]
	v_pk_add_f32 v[122:123], v[106:107], v[122:123] op_sel:[1,1] op_sel_hi:[0,0] neg_lo:[1,0] neg_hi:[0,1]
	s_nop 0
	v_pk_add_f32 v[106:107], v[108:109], v[124:125]
	v_pk_add_f32 v[108:109], v[108:109], v[124:125] neg_lo:[0,1] neg_hi:[0,1]
	s_nop 0
	v_pk_mul_f32 v[124:125], v[108:109], s[6:7]
	s_nop 0
	v_pk_fma_f32 v[108:109], v[108:109], s[4:5], v[124:125] op_sel:[0,0,1] op_sel_hi:[1,0,0]
	v_pk_add_f32 v[124:125], v[110:111], v[126:127]
	v_pk_add_f32 v[110:111], v[110:111], v[126:127] neg_lo:[0,1] neg_hi:[0,1]
	s_nop 0
	v_pk_mul_f32 v[126:127], v[110:111], s[10:11]
	s_nop 0
	v_pk_fma_f32 v[110:111], v[110:111], s[8:9], v[126:127] op_sel:[0,0,1] op_sel_hi:[1,0,0]
	v_pk_add_f32 v[126:127], v[112:113], v[128:129]
	v_pk_add_f32 v[112:113], v[112:113], v[128:129] neg_lo:[0,1] neg_hi:[0,1]
	s_nop 0
	v_pk_mul_f32 v[128:129], v[112:113], s[14:15]
	s_nop 0
	v_pk_fma_f32 v[112:113], v[112:113], s[12:13], v[128:129] op_sel:[0,0,1] op_sel_hi:[1,0,0]
	v_pk_add_f32 v[128:129], v[98:99], v[116:117]
	v_pk_add_f32 v[98:99], v[98:99], v[116:117] neg_lo:[0,1] neg_hi:[0,1]
	v_pk_add_f32 v[116:117], v[66:67], v[84:85]
	v_pk_add_f32 v[66:67], v[66:67], v[84:85] neg_lo:[0,1] neg_hi:[0,1]
	s_nop 0
	v_pk_mul_f32 v[84:85], v[66:67], s[14:15]
	s_nop 0
	v_pk_fma_f32 v[66:67], v[66:67], s[6:7], v[84:85] op_sel:[0,0,1] op_sel_hi:[1,0,0]
	v_pk_add_f32 v[84:85], v[68:69], v[86:87]
	v_pk_add_f32 v[68:69], v[68:69], v[86:87] neg_lo:[0,1] neg_hi:[0,1]
	s_nop 0
	v_pk_mul_f32 v[86:87], v[68:69], s[10:11]
	s_nop 0
	v_pk_fma_f32 v[68:69], v[68:69], s[10:11], v[86:87] op_sel:[0,0,1] op_sel_hi:[1,0,0]
	v_pk_add_f32 v[86:87], v[72:73], v[88:89]
	v_pk_add_f32 v[72:73], v[72:73], v[88:89] neg_lo:[0,1] neg_hi:[0,1]
	s_nop 0
	v_pk_mul_f32 v[88:89], v[72:73], s[6:7]
	s_nop 0
	v_pk_fma_f32 v[72:73], v[72:73], s[14:15], v[88:89] op_sel:[0,0,1] op_sel_hi:[1,0,0]
	v_pk_add_f32 v[88:89], v[74:75], v[90:91]
	v_pk_add_f32 v[90:91], v[74:75], v[90:91] op_sel:[1,1] op_sel_hi:[0,0] neg_lo:[1,0] neg_hi:[0,1]
	s_nop 0
	v_pk_add_f32 v[74:75], v[76:77], v[92:93]
	v_pk_add_f32 v[76:77], v[76:77], v[92:93] neg_lo:[0,1] neg_hi:[0,1]
	s_nop 0
	v_pk_mul_f32 v[92:93], v[76:77], s[6:7]
	s_nop 0
	v_pk_fma_f32 v[76:77], v[76:77], s[4:5], v[92:93] op_sel:[0,0,1] op_sel_hi:[1,0,0]
	v_pk_add_f32 v[92:93], v[78:79], v[94:95]
	v_pk_add_f32 v[78:79], v[78:79], v[94:95] neg_lo:[0,1] neg_hi:[0,1]
	s_mov_b32 s5, 0
	v_pk_mul_f32 v[94:95], v[78:79], s[10:11]
	s_nop 0
	v_pk_fma_f32 v[78:79], v[78:79], s[8:9], v[94:95] op_sel:[0,0,1] op_sel_hi:[1,0,0]
	v_pk_add_f32 v[94:95], v[80:81], v[96:97]
	v_pk_add_f32 v[80:81], v[80:81], v[96:97] neg_lo:[0,1] neg_hi:[0,1]
	s_nop 0
	v_pk_mul_f32 v[96:97], v[80:81], s[14:15]
	s_nop 0
	v_pk_fma_f32 v[80:81], v[80:81], s[12:13], v[96:97] op_sel:[0,0,1] op_sel_hi:[1,0,0]
	v_pk_add_f32 v[96:97], v[132:133], v[120:121]
	v_pk_add_f32 v[120:121], v[132:133], v[120:121] neg_lo:[0,1] neg_hi:[0,1]
	v_pk_add_f32 v[132:133], v[134:135], v[106:107]
	v_pk_add_f32 v[106:107], v[134:135], v[106:107] neg_lo:[0,1] neg_hi:[0,1]
	s_nop 0
	v_pk_mul_f32 v[134:135], v[106:107], s[10:11]
	s_nop 0
	v_pk_fma_f32 v[106:107], v[106:107], s[10:11], v[134:135] op_sel:[0,0,1] op_sel_hi:[1,0,0]
	v_pk_add_f32 v[134:135], v[130:131], v[124:125]
	v_pk_add_f32 v[130:131], v[130:131], v[124:125] op_sel:[1,1] op_sel_hi:[0,0] neg_lo:[1,0] neg_hi:[0,1]
	s_nop 0
	v_pk_add_f32 v[124:125], v[118:119], v[126:127]
	v_pk_add_f32 v[118:119], v[118:119], v[126:127] neg_lo:[0,1] neg_hi:[0,1]
	s_nop 0
	v_pk_mul_f32 v[126:127], v[118:119], s[10:11]
	s_nop 0
	v_pk_fma_f32 v[118:119], v[118:119], s[8:9], v[126:127] op_sel:[0,0,1] op_sel_hi:[1,0,0]
	v_pk_add_f32 v[126:127], v[114:115], v[122:123]
	v_pk_add_f32 v[114:115], v[114:115], v[122:123] neg_lo:[0,1] neg_hi:[0,1]
	v_pk_add_f32 v[122:123], v[82:83], v[108:109]
	v_pk_add_f32 v[82:83], v[82:83], v[108:109] neg_lo:[0,1] neg_hi:[0,1]
	s_nop 0
	v_pk_mul_f32 v[108:109], v[82:83], s[10:11]
	s_nop 0
	v_pk_fma_f32 v[82:83], v[82:83], s[10:11], v[108:109] op_sel:[0,0,1] op_sel_hi:[1,0,0]
	v_pk_add_f32 v[108:109], v[100:101], v[110:111]
	v_pk_add_f32 v[110:111], v[100:101], v[110:111] op_sel:[1,1] op_sel_hi:[0,0] neg_lo:[1,0] neg_hi:[0,1]
	s_nop 0
	v_pk_add_f32 v[100:101], v[102:103], v[112:113]
	v_pk_add_f32 v[102:103], v[102:103], v[112:113] neg_lo:[0,1] neg_hi:[0,1]
	s_nop 0
	v_pk_mul_f32 v[112:113], v[102:103], s[10:11]
	s_nop 0
	v_pk_fma_f32 v[102:103], v[102:103], s[8:9], v[112:113] op_sel:[0,0,1] op_sel_hi:[1,0,0]
	v_pk_add_f32 v[112:113], v[128:129], v[88:89]
	v_pk_add_f32 v[88:89], v[128:129], v[88:89] neg_lo:[0,1] neg_hi:[0,1]
	v_pk_add_f32 v[128:129], v[116:117], v[74:75]
	v_pk_add_f32 v[74:75], v[116:117], v[74:75] neg_lo:[0,1] neg_hi:[0,1]
	s_nop 0
	v_pk_mul_f32 v[116:117], v[74:75], s[10:11]
	s_nop 0
	v_pk_fma_f32 v[74:75], v[74:75], s[10:11], v[116:117] op_sel:[0,0,1] op_sel_hi:[1,0,0]
	v_pk_add_f32 v[116:117], v[84:85], v[92:93]
	v_pk_add_f32 v[92:93], v[84:85], v[92:93] op_sel:[1,1] op_sel_hi:[0,0] neg_lo:[1,0] neg_hi:[0,1]
	s_nop 0
	v_pk_add_f32 v[84:85], v[86:87], v[94:95]
	v_pk_add_f32 v[86:87], v[86:87], v[94:95] neg_lo:[0,1] neg_hi:[0,1]
	s_nop 0
	v_pk_mul_f32 v[94:95], v[86:87], s[10:11]
	s_nop 0
	v_pk_fma_f32 v[86:87], v[86:87], s[8:9], v[94:95] op_sel:[0,0,1] op_sel_hi:[1,0,0]
	v_pk_add_f32 v[94:95], v[98:99], v[90:91]
	v_pk_add_f32 v[90:91], v[98:99], v[90:91] neg_lo:[0,1] neg_hi:[0,1]
	v_pk_add_f32 v[98:99], v[66:67], v[76:77]
	v_pk_add_f32 v[66:67], v[66:67], v[76:77] neg_lo:[0,1] neg_hi:[0,1]
	s_nop 0
	v_pk_mul_f32 v[76:77], v[66:67], s[10:11]
	s_nop 0
	v_pk_fma_f32 v[66:67], v[66:67], s[10:11], v[76:77] op_sel:[0,0,1] op_sel_hi:[1,0,0]
	v_pk_add_f32 v[76:77], v[68:69], v[78:79]
	v_pk_add_f32 v[78:79], v[68:69], v[78:79] op_sel:[1,1] op_sel_hi:[0,0] neg_lo:[1,0] neg_hi:[0,1]
	s_nop 0
	v_pk_add_f32 v[68:69], v[72:73], v[80:81]
	v_pk_add_f32 v[72:73], v[72:73], v[80:81] neg_lo:[0,1] neg_hi:[0,1]
	v_pk_add_f32 v[136:137], v[90:91], v[78:79]
	v_pk_mul_f32 v[80:81], v[72:73], s[10:11]
	v_pk_add_f32 v[78:79], v[90:91], v[78:79] neg_lo:[0,1] neg_hi:[0,1]
	v_pk_fma_f32 v[72:73], v[72:73], s[8:9], v[80:81] op_sel:[0,0,1] op_sel_hi:[1,0,0]
	v_pk_add_f32 v[80:81], v[96:97], v[134:135]
	v_pk_add_f32 v[96:97], v[96:97], v[134:135] neg_lo:[0,1] neg_hi:[0,1]
	v_pk_add_f32 v[134:135], v[132:133], v[124:125]
	v_pk_add_f32 v[132:133], v[132:133], v[124:125] op_sel:[1,1] op_sel_hi:[0,0] neg_lo:[1,0] neg_hi:[0,1]
	v_pk_add_f32 v[90:91], v[66:67], v[72:73]
	v_pk_add_f32 v[124:125], v[120:121], v[130:131]
	v_pk_add_f32 v[120:121], v[120:121], v[130:131] neg_lo:[0,1] neg_hi:[0,1]
	v_pk_add_f32 v[130:131], v[106:107], v[118:119]
	v_pk_add_f32 v[118:119], v[106:107], v[118:119] op_sel:[1,1] op_sel_hi:[0,0] neg_lo:[1,0] neg_hi:[0,1]
	v_pk_add_f32 v[72:73], v[66:67], v[72:73] op_sel:[1,1] op_sel_hi:[0,0] neg_lo:[1,0] neg_hi:[0,1]
	v_pk_add_f32 v[106:107], v[126:127], v[108:109]
	v_pk_add_f32 v[108:109], v[126:127], v[108:109] neg_lo:[0,1] neg_hi:[0,1]
	v_pk_add_f32 v[126:127], v[122:123], v[100:101]
	v_pk_add_f32 v[122:123], v[122:123], v[100:101] op_sel:[1,1] op_sel_hi:[0,0] neg_lo:[1,0] neg_hi:[0,1]
	v_pk_add_f32 v[100:101], v[114:115], v[110:111]
	v_pk_add_f32 v[110:111], v[114:115], v[110:111] neg_lo:[0,1] neg_hi:[0,1]
	v_pk_add_f32 v[114:115], v[82:83], v[102:103]
	v_pk_add_f32 v[102:103], v[82:83], v[102:103] op_sel:[1,1] op_sel_hi:[0,0] neg_lo:[1,0] neg_hi:[0,1]
	v_pk_add_f32 v[82:83], v[112:113], v[116:117]
	v_pk_add_f32 v[112:113], v[112:113], v[116:117] neg_lo:[0,1] neg_hi:[0,1]
	v_pk_add_f32 v[116:117], v[128:129], v[84:85]
	v_pk_add_f32 v[128:129], v[128:129], v[84:85] op_sel:[1,1] op_sel_hi:[0,0] neg_lo:[1,0] neg_hi:[0,1]
	v_pk_add_f32 v[138:139], v[80:81], v[134:135]
	v_pk_add_f32 v[84:85], v[88:89], v[92:93]
	v_pk_add_f32 v[88:89], v[88:89], v[92:93] neg_lo:[0,1] neg_hi:[0,1]
	v_pk_add_f32 v[92:93], v[74:75], v[86:87]
	v_pk_add_f32 v[86:87], v[74:75], v[86:87] op_sel:[1,1] op_sel_hi:[0,0] neg_lo:[1,0] neg_hi:[0,1]
	v_pk_add_f32 v[80:81], v[80:81], v[134:135] neg_lo:[0,1] neg_hi:[0,1]
	v_pk_add_f32 v[74:75], v[94:95], v[76:77]
	v_pk_add_f32 v[76:77], v[94:95], v[76:77] neg_lo:[0,1] neg_hi:[0,1]
	v_pk_add_f32 v[94:95], v[98:99], v[68:69]
	v_pk_add_f32 v[98:99], v[98:99], v[68:69] op_sel:[1,1] op_sel_hi:[0,0] neg_lo:[1,0] neg_hi:[0,1]
	v_pk_add_f32 v[134:135], v[96:97], v[132:133]
	v_pk_add_f32 v[96:97], v[96:97], v[132:133] neg_lo:[0,1] neg_hi:[0,1]
	v_pk_add_f32 v[132:133], v[124:125], v[130:131]
	v_pk_add_f32 v[124:125], v[124:125], v[130:131] neg_lo:[0,1] neg_hi:[0,1]
	v_pk_add_f32 v[130:131], v[120:121], v[118:119]
	v_pk_add_f32 v[68:69], v[120:121], v[118:119] neg_lo:[0,1] neg_hi:[0,1]
	v_pk_add_f32 v[118:119], v[106:107], v[126:127]
	v_pk_add_f32 v[106:107], v[106:107], v[126:127] neg_lo:[0,1] neg_hi:[0,1]
	v_pk_add_f32 v[126:127], v[78:79], v[72:73]
	v_pk_add_f32 v[72:73], v[78:79], v[72:73] neg_lo:[0,1] neg_hi:[0,1]
	v_mul_f32_e32 v78, 0x38800000, v105
	v_sin_f32_e32 v79, v78
	v_cos_f32_e32 v78, v78
	v_pk_add_f32 v[120:121], v[108:109], v[122:123]
	v_pk_add_f32 v[108:109], v[108:109], v[122:123] neg_lo:[0,1] neg_hi:[0,1]
	v_pk_add_f32 v[122:123], v[100:101], v[114:115]
	v_pk_add_f32 v[100:101], v[100:101], v[114:115] neg_lo:[0,1] neg_hi:[0,1]
	v_pk_add_f32 v[114:115], v[110:111], v[102:103]
	v_pk_add_f32 v[66:67], v[110:111], v[102:103] neg_lo:[0,1] neg_hi:[0,1]
	v_pk_add_f32 v[102:103], v[82:83], v[116:117]
	v_pk_add_f32 v[82:83], v[82:83], v[116:117] neg_lo:[0,1] neg_hi:[0,1]
	v_pk_add_f32 v[116:117], v[84:85], v[92:93]
	v_pk_add_f32 v[84:85], v[84:85], v[92:93] neg_lo:[0,1] neg_hi:[0,1]
	v_pk_add_f32 v[92:93], v[88:89], v[86:87]
	v_pk_add_f32 v[86:87], v[88:89], v[86:87] neg_lo:[0,1] neg_hi:[0,1]
	v_pk_add_f32 v[88:89], v[74:75], v[94:95]
	v_pk_add_f32 v[74:75], v[74:75], v[94:95] neg_lo:[0,1] neg_hi:[0,1]
	v_pk_add_f32 v[94:95], v[76:77], v[98:99]
	v_pk_add_f32 v[76:77], v[76:77], v[98:99] neg_lo:[0,1] neg_hi:[0,1]
	v_pk_add_f32 v[98:99], v[136:137], v[90:91]
	v_pk_add_f32 v[90:91], v[136:137], v[90:91] neg_lo:[0,1] neg_hi:[0,1]
	v_sin_f32_e32 v136, v71
	v_pk_add_f32 v[110:111], v[112:113], v[128:129]
	v_pk_add_f32 v[112:113], v[112:113], v[128:129] neg_lo:[0,1] neg_hi:[0,1]
	v_cos_f32_e32 v128, v71
	v_pk_mul_f32 v[140:141], v[138:139], v[78:79] op_sel:[1,1] op_sel_hi:[0,1] neg_lo:[0,1]
	s_nop 0
	v_pk_fma_f32 v[138:139], v[138:139], v[78:79], v[140:141] op_sel_hi:[1,0,1]
	ds_write_b64 v142, v[138:139]
	v_pk_mul_f32 v[138:139], v[136:137], v[78:79] op_sel:[0,1] op_sel_hi:[0,0] neg_lo:[1,0]
	v_pk_fma_f32 v[78:79], v[78:79], v[128:129], v[138:139] op_sel_hi:[1,0,1]
	s_nop 0
	v_pk_mul_f32 v[138:139], v[102:103], v[78:79] op_sel:[1,1] op_sel_hi:[0,1] neg_lo:[0,1]
	s_nop 0
	v_pk_fma_f32 v[102:103], v[102:103], v[78:79], v[138:139] op_sel_hi:[1,0,1]
	v_pk_mul_f32 v[138:139], v[136:137], v[78:79] op_sel:[0,1] op_sel_hi:[0,0] neg_lo:[1,0]
	v_pk_fma_f32 v[78:79], v[78:79], v[128:129], v[138:139] op_sel_hi:[1,0,1]
	s_nop 0
	v_pk_mul_f32 v[138:139], v[118:119], v[78:79] op_sel:[1,1] op_sel_hi:[0,1] neg_lo:[0,1]
	s_nop 0
	v_pk_fma_f32 v[118:119], v[118:119], v[78:79], v[138:139] op_sel_hi:[1,0,1]
	ds_write2_b64 v0, v[102:103], v[118:119] offset0:33 offset1:66
	v_pk_mul_f32 v[102:103], v[136:137], v[78:79] op_sel:[0,1] op_sel_hi:[0,0] neg_lo:[1,0]
	v_pk_fma_f32 v[78:79], v[78:79], v[128:129], v[102:103] op_sel_hi:[1,0,1]
	s_nop 0
	v_pk_mul_f32 v[102:103], v[88:89], v[78:79] op_sel:[1,1] op_sel_hi:[0,1] neg_lo:[0,1]
	s_nop 0
	v_pk_fma_f32 v[88:89], v[88:89], v[78:79], v[102:103] op_sel_hi:[1,0,1]
	v_pk_mul_f32 v[102:103], v[136:137], v[78:79] op_sel:[0,1] op_sel_hi:[0,0] neg_lo:[1,0]
	v_pk_fma_f32 v[78:79], v[78:79], v[128:129], v[102:103] op_sel_hi:[1,0,1]
	s_nop 0
	v_pk_mul_f32 v[102:103], v[132:133], v[78:79] op_sel:[1,1] op_sel_hi:[0,1] neg_lo:[0,1]
	s_nop 0
	v_pk_fma_f32 v[102:103], v[132:133], v[78:79], v[102:103] op_sel_hi:[1,0,1]
	ds_write2_b64 v0, v[88:89], v[102:103] offset0:99 offset1:132
	v_pk_mul_f32 v[88:89], v[136:137], v[78:79] op_sel:[0,1] op_sel_hi:[0,0] neg_lo:[1,0]
	v_pk_fma_f32 v[78:79], v[78:79], v[128:129], v[88:89] op_sel_hi:[1,0,1]
	s_nop 0
	v_pk_mul_f32 v[88:89], v[116:117], v[78:79] op_sel:[1,1] op_sel_hi:[0,1] neg_lo:[0,1]
	v_pk_mul_f32 v[102:103], v[136:137], v[78:79] op_sel:[0,1] op_sel_hi:[0,0] neg_lo:[1,0]
	v_pk_fma_f32 v[88:89], v[116:117], v[78:79], v[88:89] op_sel_hi:[1,0,1]
	v_pk_fma_f32 v[78:79], v[78:79], v[128:129], v[102:103] op_sel_hi:[1,0,1]
	s_nop 0
	v_pk_mul_f32 v[102:103], v[122:123], v[78:79] op_sel:[1,1] op_sel_hi:[0,1] neg_lo:[0,1]
	s_nop 0
	v_pk_fma_f32 v[102:103], v[122:123], v[78:79], v[102:103] op_sel_hi:[1,0,1]
	ds_write2_b64 v0, v[88:89], v[102:103] offset0:165 offset1:198
	v_pk_mul_f32 v[88:89], v[136:137], v[78:79] op_sel:[0,1] op_sel_hi:[0,0] neg_lo:[1,0]
	v_pk_fma_f32 v[78:79], v[78:79], v[128:129], v[88:89] op_sel_hi:[1,0,1]
	s_nop 0
	v_pk_mul_f32 v[88:89], v[98:99], v[78:79] op_sel:[1,1] op_sel_hi:[0,1] neg_lo:[0,1]
	s_nop 0
	v_pk_fma_f32 v[88:89], v[98:99], v[78:79], v[88:89] op_sel_hi:[1,0,1]
	v_pk_mul_f32 v[98:99], v[136:137], v[78:79] op_sel:[0,1] op_sel_hi:[0,0] neg_lo:[1,0]
	v_pk_fma_f32 v[78:79], v[78:79], v[128:129], v[98:99] op_sel_hi:[1,0,1]
	s_nop 0
	v_pk_mul_f32 v[98:99], v[134:135], v[78:79] op_sel:[1,1] op_sel_hi:[0,1] neg_lo:[0,1]
	s_nop 0
	v_pk_fma_f32 v[98:99], v[134:135], v[78:79], v[98:99] op_sel_hi:[1,0,1]
	ds_write2_b64 v143, v[88:89], v[98:99] offset0:103 offset1:136
	v_pk_mul_f32 v[88:89], v[136:137], v[78:79] op_sel:[0,1] op_sel_hi:[0,0] neg_lo:[1,0]
	v_pk_fma_f32 v[78:79], v[78:79], v[128:129], v[88:89] op_sel_hi:[1,0,1]
	s_nop 0
	v_pk_mul_f32 v[88:89], v[110:111], v[78:79] op_sel:[1,1] op_sel_hi:[0,1] neg_lo:[0,1]
	v_pk_mul_f32 v[98:99], v[136:137], v[78:79] op_sel:[0,1] op_sel_hi:[0,0] neg_lo:[1,0]
	v_pk_fma_f32 v[88:89], v[110:111], v[78:79], v[88:89] op_sel_hi:[1,0,1]
	v_pk_fma_f32 v[78:79], v[78:79], v[128:129], v[98:99] op_sel_hi:[1,0,1]
	s_nop 0
	v_pk_mul_f32 v[98:99], v[120:121], v[78:79] op_sel:[1,1] op_sel_hi:[0,1] neg_lo:[0,1]
	s_nop 0
	v_pk_fma_f32 v[98:99], v[120:121], v[78:79], v[98:99] op_sel_hi:[1,0,1]
	ds_write2_b64 v144, v[88:89], v[98:99] offset0:41 offset1:74
	v_pk_mul_f32 v[88:89], v[136:137], v[78:79] op_sel:[0,1] op_sel_hi:[0,0] neg_lo:[1,0]
	v_pk_fma_f32 v[78:79], v[78:79], v[128:129], v[88:89] op_sel_hi:[1,0,1]
	s_nop 0
	v_pk_mul_f32 v[88:89], v[94:95], v[78:79] op_sel:[1,1] op_sel_hi:[0,1] neg_lo:[0,1]
	s_nop 0
	v_pk_fma_f32 v[88:89], v[94:95], v[78:79], v[88:89] op_sel_hi:[1,0,1]
	v_pk_mul_f32 v[94:95], v[136:137], v[78:79] op_sel:[0,1] op_sel_hi:[0,0] neg_lo:[1,0]
	v_pk_fma_f32 v[78:79], v[78:79], v[128:129], v[94:95] op_sel_hi:[1,0,1]
	s_nop 0
	v_pk_mul_f32 v[94:95], v[130:131], v[78:79] op_sel:[1,1] op_sel_hi:[0,1] neg_lo:[0,1]
	v_pk_fma_f32 v[94:95], v[130:131], v[78:79], v[94:95] op_sel_hi:[1,0,1]
	ds_write2_b64 v144, v[88:89], v[94:95] offset0:107 offset1:140
	v_pk_mul_f32 v[88:89], v[136:137], v[78:79] op_sel:[0,1] op_sel_hi:[0,0] neg_lo:[1,0]
	v_pk_fma_f32 v[78:79], v[78:79], v[128:129], v[88:89] op_sel_hi:[1,0,1]
	s_nop 0
	v_pk_mul_f32 v[88:89], v[92:93], v[78:79] op_sel:[1,1] op_sel_hi:[0,1] neg_lo:[0,1]
	v_pk_fma_f32 v[88:89], v[92:93], v[78:79], v[88:89] op_sel_hi:[1,0,1]
	v_pk_mul_f32 v[92:93], v[136:137], v[78:79] op_sel:[0,1] op_sel_hi:[0,0] neg_lo:[1,0]
	v_pk_fma_f32 v[78:79], v[78:79], v[128:129], v[92:93] op_sel_hi:[1,0,1]
	s_nop 0
	v_pk_mul_f32 v[92:93], v[114:115], v[78:79] op_sel:[1,1] op_sel_hi:[0,1] neg_lo:[0,1]
	v_pk_fma_f32 v[92:93], v[114:115], v[78:79], v[92:93] op_sel_hi:[1,0,1]
	ds_write2_b64 v144, v[88:89], v[92:93] offset0:173 offset1:206
	v_pk_mul_f32 v[88:89], v[136:137], v[78:79] op_sel:[0,1] op_sel_hi:[0,0] neg_lo:[1,0]
	v_pk_fma_f32 v[78:79], v[78:79], v[128:129], v[88:89] op_sel_hi:[1,0,1]
	s_nop 0
	v_pk_mul_f32 v[88:89], v[126:127], v[78:79] op_sel:[1,1] op_sel_hi:[0,1] neg_lo:[0,1]
	v_pk_mul_f32 v[92:93], v[136:137], v[78:79] op_sel:[0,1] op_sel_hi:[0,0] neg_lo:[1,0]
	v_pk_fma_f32 v[88:89], v[126:127], v[78:79], v[88:89] op_sel_hi:[1,0,1]
	v_pk_fma_f32 v[78:79], v[78:79], v[128:129], v[92:93] op_sel_hi:[1,0,1]
	s_nop 0
	v_pk_mul_f32 v[92:93], v[80:81], v[78:79] op_sel:[1,1] op_sel_hi:[0,1] neg_lo:[0,1]
	v_pk_fma_f32 v[80:81], v[80:81], v[78:79], v[92:93] op_sel_hi:[1,0,1]
	ds_write2_b64 v145, v[88:89], v[80:81] offset0:111 offset1:144
	v_pk_mul_f32 v[80:81], v[136:137], v[78:79] op_sel:[0,1] op_sel_hi:[0,0] neg_lo:[1,0]
	v_pk_fma_f32 v[78:79], v[78:79], v[128:129], v[80:81] op_sel_hi:[1,0,1]
	s_nop 0
	v_pk_mul_f32 v[80:81], v[82:83], v[78:79] op_sel:[1,1] op_sel_hi:[0,1] neg_lo:[0,1]
	v_pk_fma_f32 v[80:81], v[82:83], v[78:79], v[80:81] op_sel_hi:[1,0,1]
	v_pk_mul_f32 v[82:83], v[136:137], v[78:79] op_sel:[0,1] op_sel_hi:[0,0] neg_lo:[1,0]
	v_pk_fma_f32 v[78:79], v[78:79], v[128:129], v[82:83] op_sel_hi:[1,0,1]
	s_nop 0
	v_pk_mul_f32 v[82:83], v[106:107], v[78:79] op_sel:[1,1] op_sel_hi:[0,1] neg_lo:[0,1]
	v_pk_fma_f32 v[82:83], v[106:107], v[78:79], v[82:83] op_sel_hi:[1,0,1]
	ds_write2_b64 v146, v[80:81], v[82:83] offset0:49 offset1:82
	v_pk_mul_f32 v[80:81], v[136:137], v[78:79] op_sel:[0,1] op_sel_hi:[0,0] neg_lo:[1,0]
	v_pk_fma_f32 v[78:79], v[78:79], v[128:129], v[80:81] op_sel_hi:[1,0,1]
	s_nop 0
	v_pk_mul_f32 v[80:81], v[74:75], v[78:79] op_sel:[1,1] op_sel_hi:[0,1] neg_lo:[0,1]
	v_pk_fma_f32 v[74:75], v[74:75], v[78:79], v[80:81] op_sel_hi:[1,0,1]
	v_pk_mul_f32 v[80:81], v[136:137], v[78:79] op_sel:[0,1] op_sel_hi:[0,0] neg_lo:[1,0]
	v_pk_fma_f32 v[78:79], v[78:79], v[128:129], v[80:81] op_sel_hi:[1,0,1]
	s_nop 0
	v_pk_mul_f32 v[80:81], v[124:125], v[78:79] op_sel:[1,1] op_sel_hi:[0,1] neg_lo:[0,1]
	v_pk_fma_f32 v[80:81], v[124:125], v[78:79], v[80:81] op_sel_hi:[1,0,1]
	ds_write2_b64 v146, v[74:75], v[80:81] offset0:115 offset1:148
	v_pk_mul_f32 v[74:75], v[136:137], v[78:79] op_sel:[0,1] op_sel_hi:[0,0] neg_lo:[1,0]
	v_pk_fma_f32 v[74:75], v[78:79], v[128:129], v[74:75] op_sel_hi:[1,0,1]
	s_nop 0
	v_pk_mul_f32 v[78:79], v[84:85], v[74:75] op_sel:[1,1] op_sel_hi:[0,1] neg_lo:[0,1]
	v_pk_mul_f32 v[80:81], v[136:137], v[74:75] op_sel:[0,1] op_sel_hi:[0,0] neg_lo:[1,0]
	v_pk_fma_f32 v[78:79], v[84:85], v[74:75], v[78:79] op_sel_hi:[1,0,1]
	v_pk_fma_f32 v[74:75], v[74:75], v[128:129], v[80:81] op_sel_hi:[1,0,1]
	s_nop 0
	v_pk_mul_f32 v[80:81], v[100:101], v[74:75] op_sel:[1,1] op_sel_hi:[0,1] neg_lo:[0,1]
	v_pk_fma_f32 v[80:81], v[100:101], v[74:75], v[80:81] op_sel_hi:[1,0,1]
	ds_write2_b64 v146, v[78:79], v[80:81] offset0:181 offset1:214
	v_pk_mul_f32 v[78:79], v[136:137], v[74:75] op_sel:[0,1] op_sel_hi:[0,0] neg_lo:[1,0]
	v_pk_fma_f32 v[74:75], v[74:75], v[128:129], v[78:79] op_sel_hi:[1,0,1]
	s_nop 0
	v_pk_mul_f32 v[78:79], v[90:91], v[74:75] op_sel:[1,1] op_sel_hi:[0,1] neg_lo:[0,1]
	v_pk_mul_f32 v[80:81], v[136:137], v[74:75] op_sel:[0,1] op_sel_hi:[0,0] neg_lo:[1,0]
	v_pk_fma_f32 v[78:79], v[90:91], v[74:75], v[78:79] op_sel_hi:[1,0,1]
	v_pk_fma_f32 v[74:75], v[74:75], v[128:129], v[80:81] op_sel_hi:[1,0,1]
	s_nop 0
	v_pk_mul_f32 v[80:81], v[96:97], v[74:75] op_sel:[1,1] op_sel_hi:[0,1] neg_lo:[0,1]
	v_pk_fma_f32 v[80:81], v[96:97], v[74:75], v[80:81] op_sel_hi:[1,0,1]
	ds_write2_b64 v147, v[78:79], v[80:81] offset0:119 offset1:152
	v_pk_mul_f32 v[78:79], v[136:137], v[74:75] op_sel:[0,1] op_sel_hi:[0,0] neg_lo:[1,0]
	v_pk_fma_f32 v[74:75], v[74:75], v[128:129], v[78:79] op_sel_hi:[1,0,1]
	s_nop 0
	v_pk_mul_f32 v[78:79], v[112:113], v[74:75] op_sel:[1,1] op_sel_hi:[0,1] neg_lo:[0,1]
	v_pk_mul_f32 v[80:81], v[136:137], v[74:75] op_sel:[0,1] op_sel_hi:[0,0] neg_lo:[1,0]
	v_pk_fma_f32 v[78:79], v[112:113], v[74:75], v[78:79] op_sel_hi:[1,0,1]
	v_pk_fma_f32 v[74:75], v[74:75], v[128:129], v[80:81] op_sel_hi:[1,0,1]
	s_nop 0
	v_pk_mul_f32 v[80:81], v[108:109], v[74:75] op_sel:[1,1] op_sel_hi:[0,1] neg_lo:[0,1]
	v_pk_fma_f32 v[80:81], v[108:109], v[74:75], v[80:81] op_sel_hi:[1,0,1]
	ds_write2_b64 v70, v[78:79], v[80:81] offset0:57 offset1:90
	v_pk_mul_f32 v[78:79], v[136:137], v[74:75] op_sel:[0,1] op_sel_hi:[0,0] neg_lo:[1,0]
	v_pk_fma_f32 v[74:75], v[74:75], v[128:129], v[78:79] op_sel_hi:[1,0,1]
	s_nop 0
	v_pk_mul_f32 v[78:79], v[76:77], v[74:75] op_sel:[1,1] op_sel_hi:[0,1] neg_lo:[0,1]
	v_pk_fma_f32 v[76:77], v[76:77], v[74:75], v[78:79] op_sel_hi:[1,0,1]
	v_pk_mul_f32 v[78:79], v[136:137], v[74:75] op_sel:[0,1] op_sel_hi:[0,0] neg_lo:[1,0]
	v_pk_fma_f32 v[74:75], v[74:75], v[128:129], v[78:79] op_sel_hi:[1,0,1]
	s_nop 0
	v_pk_mul_f32 v[78:79], v[68:69], v[74:75] op_sel:[1,1] op_sel_hi:[0,1] neg_lo:[0,1]
	v_pk_fma_f32 v[68:69], v[68:69], v[74:75], v[78:79] op_sel_hi:[1,0,1]
	ds_write2_b64 v70, v[76:77], v[68:69] offset0:123 offset1:156
	v_pk_mul_f32 v[68:69], v[136:137], v[74:75] op_sel:[0,1] op_sel_hi:[0,0] neg_lo:[1,0]
	v_pk_fma_f32 v[68:69], v[74:75], v[128:129], v[68:69] op_sel_hi:[1,0,1]
	s_nop 0
	v_pk_mul_f32 v[74:75], v[86:87], v[68:69] op_sel:[1,1] op_sel_hi:[0,1] neg_lo:[0,1]
	v_pk_mul_f32 v[76:77], v[136:137], v[68:69] op_sel:[0,1] op_sel_hi:[0,0] neg_lo:[1,0]
	v_pk_fma_f32 v[74:75], v[86:87], v[68:69], v[74:75] op_sel_hi:[1,0,1]
	v_pk_fma_f32 v[68:69], v[68:69], v[128:129], v[76:77] op_sel_hi:[1,0,1]
	s_nop 0
	v_pk_mul_f32 v[76:77], v[66:67], v[68:69] op_sel:[1,1] op_sel_hi:[0,1] neg_lo:[0,1]
	v_pk_fma_f32 v[66:67], v[66:67], v[68:69], v[76:77] op_sel_hi:[1,0,1]
	ds_write2_b64 v70, v[74:75], v[66:67] offset0:189 offset1:222
	v_pk_mul_f32 v[66:67], v[136:137], v[68:69] op_sel:[0,1] op_sel_hi:[0,0] neg_lo:[1,0]
	v_pk_fma_f32 v[66:67], v[68:69], v[128:129], v[66:67] op_sel_hi:[1,0,1]
	s_nop 0
	v_pk_mul_f32 v[68:69], v[72:73], v[66:67] op_sel:[1,1] op_sel_hi:[0,1] neg_lo:[0,1]
	v_pk_fma_f32 v[66:67], v[72:73], v[66:67], v[68:69] op_sel_hi:[1,0,1]
	ds_write_b64 v0, v[66:67] offset:8184
	s_waitcnt lgkmcnt(0)
	s_barrier
